# big GEMM: skip the dummy next-unit prefetch DMAs (last K iteration of a workgroup's last unit) in seven 256x256 loops incl. down-proj, with the tighter counted waits that iteration needs; plus small_g
# speedup vs baseline: 1.0145x; 1.0051x over previous
; #define PG8_STAGE(bufoff, gbase, voff) do { _Pragma("unroll") for (int _i = 0; _i < 2; ++_i) \
;         __builtin_amdgcn_global_load_lds((const unsigned*)((const char*)(gbase) + (voff)[_i]), (PG8_LAS unsigned*)(lds + (bufoff) + ldsw + _i * 8192), 16, 0, 0); } while (0)
; #define PG8_LDA(dst, b, h) do { _Pragma("unroll") for (int m = 0; m < 4; ++m) _Pragma("unroll") for (int k = 0; k < 2; ++k) dst[m][k] = *(const PG8_LAS bf16x8*)(lds + PG8_SA(b, h) + aoff + m * 2048 + k * 1024); } while (0)
; #define PG8_LDB(dst, b, h) do { _Pragma("unroll") for (int n = 0; n < 2; ++n) _Pragma("unroll") for (int k = 0; k < 2; ++k) dst[n][k] = *(const PG8_LAS bf16x8*)(lds + PG8_SB(b, h) + boff + n * 2048 + k * 1024); } while (0)
; #define PG8_WAIT_V(n) asm volatile("s_waitcnt vmcnt(" #n ")" ::: "memory")
; #define PG8_WAIT_L(n) asm volatile("s_waitcnt lgkmcnt(" #n ")" ::: "memory")
; #define PG8_BAR __builtin_amdgcn_s_barrier()
; #define PG8_SCHED __builtin_amdgcn_sched_barrier(0)
; template <class Epi, class Sched, bool ALIGN_EPI = false, bool SP2 = false>
; __device__ __forceinline__ void gemm_phase(PG8_LAS unsigned char* lds, const Gemm g, const Sched& S, const Epi& E, const int tid) {
;     ...
;         const char* nA = has_next ? (const char*)g.A + (size_t)nxt.pm * tstep : cA; const char* nB = has_next ? (const char*)g.Bt + (size_t)nxt.pn * tstep : cB;
;         for (int t = 0; t < nt; t += 2) {
;             const bool last = (t == nt - 2);
;             const char* a1 = cA + (size_t)(t + 1) * kstep;
;             const char* a2 = last ? nA : cA + (size_t)(t + 2) * kstep; const char* b2 = last ? nB : cB + (size_t)(t + 2) * kstep;
;             const char* a3 = a2 + kstep; const char* b3 = b2 + kstep;
;             if (last && has_next) S.a_ready(nxt);
;             if constexpr (SP2) {
;             PG8_LDB(B0, 0, 0); PG8_LDB(B1, 0, 1); PG8_SCHED; PG8_LDA(At, 0, 0); PG8_STAGE(PG8_SA(1, 1), a1 + hstep, voffA);
;             PG8_WAIT_V(8); PG8_WAIT_L(0); PG8_BAR; PG8_MMA(0, 0, At, B0); PG8_MMA(0, 1, At, B1); PG8_BAR; PG8_SCHED;
;             PG8_LDA(At, 0, 1); PG8_STAGE(PG8_SB(0, 0), b2, voffB); PG8_STAGE(PG8_SB(0, 1), b2 + hstepB, voffB); PG8_STAGE(PG8_SA(0, 0), a2, voffA);
;             PG8_WAIT_V(8); PG8_WAIT_L(0); PG8_BAR; PG8_MMA(1, 0, At, B0); PG8_MMA(1, 1, At, B1); PG8_BAR; PG8_SCHED;
.LBB0_185:
	s_add_u32 s40, s38, 0xfffc0080
	s_addc_u32 s41, s39, -1
	s_add_i32 s82, 0, 0x10000
	s_cmp_eq_u32 s67, 12
	s_cselect_b32 s43, s3, s41
	s_cselect_b32 s42, s5, s40
	v_add_u32_e32 v154, s82, v163
	s_cselect_b32 s41, s21, s66
	s_cselect_b32 s40, s23, s37
	s_cmp_eq_u32 s67, 12
	s_cselect_b32 s32, 1, 0
	s_andn2_b32 s32, s32, s28
	s_add_i32 s84, 0, 0x14000
	ds_read_b128 v[146:149], v154
	ds_read_b128 v[150:153], v154 offset:1024
	ds_read_b128 v[170:173], v154 offset:2048
	ds_read_b128 v[174:177], v154 offset:3072
	v_add_u32_e32 v154, s84, v163
	ds_read_b128 v[178:181], v154
	ds_read_b128 v[182:185], v154 offset:1024
	ds_read_b128 v[186:189], v154 offset:2048
	ds_read_b128 v[190:193], v154 offset:3072
	v_lshl_add_u64 v[154:155], s[38:39], 0, v[142:143]
	s_add_i32 m0, s63, 0xc000
	ds_read_b128 v[194:197], v166
	ds_read_b128 v[198:201], v166 offset:1024
	ds_read_b128 v[212:215], v166 offset:2048
	ds_read_b128 v[216:219], v166 offset:3072
	ds_read_b128 v[220:223], v166 offset:4096
	ds_read_b128 v[224:227], v166 offset:5120
	ds_read_b128 v[228:231], v166 offset:6144
	ds_read_b128 v[232:235], v166 offset:7168
	global_load_lds_dwordx4 v[154:155], off
	v_lshl_add_u64 v[154:155], s[38:39], 0, v[144:145]
	s_add_i32 m0, s63, 0xe000
	s_nop 0
	global_load_lds_dwordx4 v[154:155], off
	s_waitcnt vmcnt(8)
	s_waitcnt lgkmcnt(0)
	s_barrier
	s_setprio 1
	s_waitcnt lgkmcnt(0)
	v_mfma_f32_16x16x32_bf16 v[128:131], v[146:149], v[194:197], v[128:131]
	v_mfma_f32_16x16x32_bf16 v[124:127], v[170:173], v[194:197], v[124:127]
	v_mfma_f32_16x16x32_bf16 v[112:115], v[146:149], v[212:215], v[112:115]
	v_mfma_f32_16x16x32_bf16 v[108:111], v[170:173], v[212:215], v[108:111]
	v_mfma_f32_16x16x32_bf16 v[96:99], v[146:149], v[220:223], v[96:99]
	v_mfma_f32_16x16x32_bf16 v[92:95], v[170:173], v[220:223], v[92:95]
	v_mfma_f32_16x16x32_bf16 v[80:83], v[146:149], v[228:231], v[80:83]
	v_mfma_f32_16x16x32_bf16 v[76:79], v[170:173], v[228:231], v[76:79]
	v_mfma_f32_16x16x32_bf16 v[128:131], v[150:153], v[198:201], v[128:131]
	v_mfma_f32_16x16x32_bf16 v[124:127], v[174:177], v[198:201], v[124:127]
	v_mfma_f32_16x16x32_bf16 v[112:115], v[150:153], v[216:219], v[112:115]
	v_mfma_f32_16x16x32_bf16 v[108:111], v[174:177], v[216:219], v[108:111]
	v_mfma_f32_16x16x32_bf16 v[96:99], v[150:153], v[224:227], v[96:99]
	v_mfma_f32_16x16x32_bf16 v[92:95], v[174:177], v[224:227], v[92:95]
	v_mfma_f32_16x16x32_bf16 v[80:83], v[150:153], v[232:235], v[80:83]
	v_mfma_f32_16x16x32_bf16 v[76:79], v[174:177], v[232:235], v[76:79]
	s_setprio 0
	s_setprio 1
	v_mfma_f32_16x16x32_bf16 v[120:123], v[178:181], v[194:197], v[120:123]
	v_mfma_f32_16x16x32_bf16 v[116:119], v[186:189], v[194:197], v[116:119]
	v_mfma_f32_16x16x32_bf16 v[104:107], v[178:181], v[212:215], v[104:107]
	v_mfma_f32_16x16x32_bf16 v[100:103], v[186:189], v[212:215], v[100:103]
	v_mfma_f32_16x16x32_bf16 v[88:91], v[178:181], v[220:223], v[88:91]
	v_mfma_f32_16x16x32_bf16 v[84:87], v[186:189], v[220:223], v[84:87]
	v_mfma_f32_16x16x32_bf16 v[72:75], v[178:181], v[228:231], v[72:75]
	v_mfma_f32_16x16x32_bf16 v[68:71], v[186:189], v[228:231], v[68:71]
	v_mfma_f32_16x16x32_bf16 v[120:123], v[182:185], v[198:201], v[120:123]
	v_mfma_f32_16x16x32_bf16 v[116:119], v[190:193], v[198:201], v[116:119]
	v_mfma_f32_16x16x32_bf16 v[104:107], v[182:185], v[216:219], v[104:107]
	v_mfma_f32_16x16x32_bf16 v[100:103], v[190:193], v[216:219], v[100:103]
	v_mfma_f32_16x16x32_bf16 v[88:91], v[182:185], v[224:227], v[88:91]
	v_mfma_f32_16x16x32_bf16 v[84:87], v[190:193], v[224:227], v[84:87]
	v_mfma_f32_16x16x32_bf16 v[72:75], v[182:185], v[232:235], v[72:75]
	v_mfma_f32_16x16x32_bf16 v[68:71], v[190:193], v[232:235], v[68:71]
	s_setprio 0
	s_barrier
	s_add_i32 s82, s82, s62
	v_lshl_add_u64 v[154:155], s[40:41], 0, v[136:137]
	s_mov_b32 m0, s82
	ds_read_b128 v[194:197], v166 offset:16384
	ds_read_b128 v[198:201], v166 offset:17408
	ds_read_b128 v[212:215], v166 offset:18432
	ds_read_b128 v[216:219], v166 offset:19456
	ds_read_b128 v[220:223], v166 offset:20480
	ds_read_b128 v[224:227], v166 offset:21504
	ds_read_b128 v[228:231], v166 offset:22528
	ds_read_b128 v[232:235], v166 offset:23552
	s_cmp_lg_u32 s32, 0
	s_cbranch_scc1 .Lbt0_0
	global_load_lds_dwordx4 v[154:155], off
.Lbt0_0:
	s_add_i32 m0, s82, 0x2000
	s_add_u32 s82, s40, 0x10000
	v_lshl_add_u64 v[236:237], s[40:41], 0, v[140:141]
	s_addc_u32 s83, s41, 0
	s_add_i32 s84, s84, s62
	s_cmp_lg_u32 s32, 0
	s_cbranch_scc1 .Lbt0_1
	global_load_lds_dwordx4 v[236:237], off
.Lbt0_1:
	v_lshl_add_u64 v[238:239], s[82:83], 0, v[136:137]
	s_mov_b32 m0, s84
	v_lshl_add_u64 v[240:241], s[42:43], 0, v[138:139]
	s_cmp_lg_u32 s32, 0
	s_cbranch_scc1 .Lbt0_2
	global_load_lds_dwordx4 v[238:239], off
.Lbt0_2:
	v_lshl_add_u64 v[238:239], s[82:83], 0, v[140:141]
	s_add_i32 m0, s84, 0x2000
	s_nop 0
	s_cmp_lg_u32 s32, 0
	s_cbranch_scc1 .Lbt0_3
	global_load_lds_dwordx4 v[238:239], off
.Lbt0_3:
	v_lshl_add_u64 v[238:239], s[42:43], 0, v[134:135]
	s_mov_b32 m0, s63
	s_nop 0
	s_cmp_lg_u32 s32, 0
	s_cbranch_scc1 .Lbt0_4
	global_load_lds_dwordx4 v[238:239], off
.Lbt0_4:
	s_mov_b32 m0, s64
	s_nop 0
	s_cmp_lg_u32 s32, 0
	s_cbranch_scc1 .Lbt0_5
	global_load_lds_dwordx4 v[240:241], off
.Lbt0_5:
	s_waitcnt vmcnt(8)
	s_cmp_eq_u32 s32, 0
	s_cbranch_scc1 .Lbw0_2
	s_waitcnt vmcnt(2)
; #define PG8_STAGE(bufoff, gbase, voff) do { _Pragma("unroll") for (int _i = 0; _i < 2; ++_i) \
;         __builtin_amdgcn_global_load_lds((const unsigned*)((const char*)(gbase) + (voff)[_i]), (PG8_LAS unsigned*)(lds + (bufoff) + ldsw + _i * 8192), 16, 0, 0); } while (0)
; #define PG8_LDA(dst, b, h) do { _Pragma("unroll") for (int m = 0; m < 4; ++m) _Pragma("unroll") for (int k = 0; k < 2; ++k) dst[m][k] = *(const PG8_LAS bf16x8*)(lds + PG8_SA(b, h) + aoff + m * 2048 + k * 1024); } while (0)
; #define PG8_LDB(dst, b, h) do { _Pragma("unroll") for (int n = 0; n < 2; ++n) _Pragma("unroll") for (int k = 0; k < 2; ++k) dst[n][k] = *(const PG8_LAS bf16x8*)(lds + PG8_SB(b, h) + boff + n * 2048 + k * 1024); } while (0)
; #define PG8_MMA(ai, bj, At, Bt) do { __builtin_amdgcn_s_setprio(1); _Pragma("unroll") for (int m = 0; m < 4; ++m) _Pragma("unroll") for (int n = 0; n < 2; ++n) _Pragma("unroll") for (int k = 0; k < 2; ++k) \
;         acc[ai][bj][m][n] = __builtin_amdgcn_mfma_f32_16x16x32_bf16(Bt[n][k], At[m][k], acc[ai][bj][m][n], 0, 0, 0); __builtin_amdgcn_s_setprio(0); } while (0)
; #define PG8_WAIT_V(n) asm volatile("s_waitcnt vmcnt(" #n ")" ::: "memory")
; #define PG8_WAIT_L(n) asm volatile("s_waitcnt lgkmcnt(" #n ")" ::: "memory")
; #define PG8_BAR __builtin_amdgcn_s_barrier()
; #define PG8_SCHED __builtin_amdgcn_sched_barrier(0)
; template <class Epi, class Sched, bool ALIGN_EPI = false, bool SP2 = false>
; __device__ __forceinline__ void gemm_phase(PG8_LAS unsigned char* lds, const Gemm g, const Sched& S, const Epi& E, const int tid) {
;     ...
;             PG8_WAIT_V(8); PG8_WAIT_L(0); PG8_BAR; PG8_MMA(1, 0, At, B0); PG8_MMA(1, 1, At, B1); PG8_BAR; PG8_SCHED;
;             PG8_LDB(B0, 1, 0); PG8_LDB(B1, 1, 1); PG8_SCHED; PG8_LDA(At, 1, 0); PG8_STAGE(PG8_SA(0, 1), a2 + hstep, voffA);
;             PG8_WAIT_V(8); PG8_WAIT_L(0); PG8_BAR; PG8_MMA(0, 0, At, B0); PG8_MMA(0, 1, At, B1); PG8_BAR; PG8_SCHED;
.Lbw0_2:
	s_waitcnt lgkmcnt(0)
	s_barrier
	s_setprio 1
	s_waitcnt lgkmcnt(0)
	v_mfma_f32_16x16x32_bf16 v[64:67], v[146:149], v[194:197], v[64:67]
	v_mfma_f32_16x16x32_bf16 v[60:63], v[170:173], v[194:197], v[60:63]
	v_mfma_f32_16x16x32_bf16 v[48:51], v[146:149], v[212:215], v[48:51]
	v_mfma_f32_16x16x32_bf16 v[44:47], v[170:173], v[212:215], v[44:47]
	v_mfma_f32_16x16x32_bf16 v[32:35], v[146:149], v[220:223], v[32:35]
	v_mfma_f32_16x16x32_bf16 v[28:31], v[170:173], v[220:223], v[28:31]
	v_mfma_f32_16x16x32_bf16 v[16:19], v[146:149], v[228:231], v[16:19]
	v_mfma_f32_16x16x32_bf16 v[12:15], v[170:173], v[228:231], v[12:15]
	v_mfma_f32_16x16x32_bf16 v[64:67], v[150:153], v[198:201], v[64:67]
	v_mfma_f32_16x16x32_bf16 v[60:63], v[174:177], v[198:201], v[60:63]
	v_mfma_f32_16x16x32_bf16 v[48:51], v[150:153], v[216:219], v[48:51]
	v_mfma_f32_16x16x32_bf16 v[44:47], v[174:177], v[216:219], v[44:47]
	v_mfma_f32_16x16x32_bf16 v[32:35], v[150:153], v[224:227], v[32:35]
	v_mfma_f32_16x16x32_bf16 v[28:31], v[174:177], v[224:227], v[28:31]
	v_mfma_f32_16x16x32_bf16 v[16:19], v[150:153], v[232:235], v[16:19]
	v_mfma_f32_16x16x32_bf16 v[12:15], v[174:177], v[232:235], v[12:15]
	s_setprio 0
	s_setprio 1
	v_mfma_f32_16x16x32_bf16 v[56:59], v[178:181], v[194:197], v[56:59]
	v_mfma_f32_16x16x32_bf16 v[52:55], v[186:189], v[194:197], v[52:55]
	v_mfma_f32_16x16x32_bf16 v[40:43], v[178:181], v[212:215], v[40:43]
	v_mfma_f32_16x16x32_bf16 v[36:39], v[186:189], v[212:215], v[36:39]
	v_mfma_f32_16x16x32_bf16 v[24:27], v[178:181], v[220:223], v[24:27]
	v_mfma_f32_16x16x32_bf16 v[20:23], v[186:189], v[220:223], v[20:23]
	v_mfma_f32_16x16x32_bf16 v[8:11], v[178:181], v[228:231], v[8:11]
	v_mfma_f32_16x16x32_bf16 v[4:7], v[186:189], v[228:231], v[4:7]
	v_mfma_f32_16x16x32_bf16 v[56:59], v[182:185], v[198:201], v[56:59]
	v_mfma_f32_16x16x32_bf16 v[52:55], v[190:193], v[198:201], v[52:55]
	v_mfma_f32_16x16x32_bf16 v[40:43], v[182:185], v[216:219], v[40:43]
	v_mfma_f32_16x16x32_bf16 v[36:39], v[190:193], v[216:219], v[36:39]
	v_mfma_f32_16x16x32_bf16 v[24:27], v[182:185], v[224:227], v[24:27]
	v_mfma_f32_16x16x32_bf16 v[20:23], v[190:193], v[224:227], v[20:23]
	v_mfma_f32_16x16x32_bf16 v[8:11], v[182:185], v[232:235], v[8:11]
	v_mfma_f32_16x16x32_bf16 v[4:7], v[190:193], v[232:235], v[4:7]
	s_setprio 0
	s_barrier
	s_add_i32 s82, 0, 0x18000
	v_add_u32_e32 v167, s82, v163
	s_add_i32 s83, 0, 0x1c000
	ds_read_b128 v[146:149], v167
	ds_read_b128 v[150:153], v167 offset:1024
	ds_read_b128 v[170:173], v167 offset:2048
	ds_read_b128 v[174:177], v167 offset:3072
	v_add_u32_e32 v167, s83, v163
	ds_read_b128 v[178:181], v167
	ds_read_b128 v[182:185], v167 offset:1024
	ds_read_b128 v[186:189], v167 offset:2048
	ds_read_b128 v[190:193], v167 offset:3072
	s_add_u32 s42, s42, 0x40000
	s_addc_u32 s43, s43, 0
	s_mov_b32 m0, s65
	v_lshl_add_u64 v[242:243], s[42:43], 0, v[134:135]
	ds_read_b128 v[194:197], v166 offset:32768
	ds_read_b128 v[198:201], v166 offset:33792
	ds_read_b128 v[212:215], v166 offset:34816
	ds_read_b128 v[216:219], v166 offset:35840
	ds_read_b128 v[220:223], v166 offset:36864
	ds_read_b128 v[224:227], v166 offset:37888
	ds_read_b128 v[228:231], v166 offset:38912
	ds_read_b128 v[232:235], v166 offset:39936
	s_cmp_lg_u32 s32, 0
	s_cbranch_scc1 .Lbt0_6
	global_load_lds_dwordx4 v[242:243], off
.Lbt0_6:
	v_lshl_add_u64 v[242:243], s[42:43], 0, v[138:139]
	s_mov_b32 m0, s76
	s_nop 0
	s_cmp_lg_u32 s32, 0
	s_cbranch_scc1 .Lbt0_7
	global_load_lds_dwordx4 v[242:243], off
.Lbt0_7:
	s_waitcnt vmcnt(8)
	s_cmp_eq_u32 s32, 0
	s_cbranch_scc1 .Lbw0_0
	s_waitcnt vmcnt(0)
; #define PG8_STAGE(bufoff, gbase, voff) do { _Pragma("unroll") for (int _i = 0; _i < 2; ++_i) \
;         __builtin_amdgcn_global_load_lds((const unsigned*)((const char*)(gbase) + (voff)[_i]), (PG8_LAS unsigned*)(lds + (bufoff) + ldsw + _i * 8192), 16, 0, 0); } while (0)
; #define PG8_LDA(dst, b, h) do { _Pragma("unroll") for (int m = 0; m < 4; ++m) _Pragma("unroll") for (int k = 0; k < 2; ++k) dst[m][k] = *(const PG8_LAS bf16x8*)(lds + PG8_SA(b, h) + aoff + m * 2048 + k * 1024); } while (0)
; #define PG8_LDB(dst, b, h) do { _Pragma("unroll") for (int n = 0; n < 2; ++n) _Pragma("unroll") for (int k = 0; k < 2; ++k) dst[n][k] = *(const PG8_LAS bf16x8*)(lds + PG8_SB(b, h) + boff + n * 2048 + k * 1024); } while (0)
; #define PG8_MMA(ai, bj, At, Bt) do { __builtin_amdgcn_s_setprio(1); _Pragma("unroll") for (int m = 0; m < 4; ++m) _Pragma("unroll") for (int n = 0; n < 2; ++n) _Pragma("unroll") for (int k = 0; k < 2; ++k) \
;         acc[ai][bj][m][n] = __builtin_amdgcn_mfma_f32_16x16x32_bf16(Bt[n][k], At[m][k], acc[ai][bj][m][n], 0, 0, 0); __builtin_amdgcn_s_setprio(0); } while (0)
; #define PG8_WAIT_V(n) asm volatile("s_waitcnt vmcnt(" #n ")" ::: "memory")
; #define PG8_WAIT_L(n) asm volatile("s_waitcnt lgkmcnt(" #n ")" ::: "memory")
; #define PG8_BAR __builtin_amdgcn_s_barrier()
; #define PG8_SCHED __builtin_amdgcn_sched_barrier(0)
; template <class Epi, class Sched, bool ALIGN_EPI = false, bool SP2 = false>
; __device__ __forceinline__ void gemm_phase(PG8_LAS unsigned char* lds, const Gemm g, const Sched& S, const Epi& E, const int tid) {
;     ...
;             PG8_WAIT_V(8); PG8_WAIT_L(0); PG8_BAR; PG8_MMA(1, 0, At, B0); PG8_MMA(1, 1, At, B1); PG8_BAR; PG8_SCHED;
;             PG8_LDB(B0, 1, 0); PG8_LDB(B1, 1, 1); PG8_SCHED; PG8_LDA(At, 1, 0); PG8_STAGE(PG8_SA(0, 1), a2 + hstep, voffA);
;             PG8_WAIT_V(8); PG8_WAIT_L(0); PG8_BAR; PG8_MMA(0, 0, At, B0); PG8_MMA(0, 1, At, B1); PG8_BAR; PG8_SCHED;
;             PG8_LDA(At, 1, 1); PG8_STAGE(PG8_SB(1, 0), b3, voffB); PG8_STAGE(PG8_SB(1, 1), b3 + hstepB, voffB); PG8_STAGE(PG8_SA(1, 0), a3, voffA);
;             PG8_WAIT_V(8); PG8_WAIT_L(0); PG8_BAR; PG8_MMA(1, 0, At, B0); PG8_MMA(1, 1, At, B1); PG8_BAR; PG8_SCHED;
.Lbw0_0:
	s_waitcnt lgkmcnt(0)
	s_barrier
	s_setprio 1
	s_waitcnt lgkmcnt(0)
	v_mfma_f32_16x16x32_bf16 v[128:131], v[146:149], v[194:197], v[128:131]
	v_mfma_f32_16x16x32_bf16 v[124:127], v[170:173], v[194:197], v[124:127]
	v_mfma_f32_16x16x32_bf16 v[112:115], v[146:149], v[212:215], v[112:115]
	v_mfma_f32_16x16x32_bf16 v[108:111], v[170:173], v[212:215], v[108:111]
	v_mfma_f32_16x16x32_bf16 v[96:99], v[146:149], v[220:223], v[96:99]
	v_mfma_f32_16x16x32_bf16 v[92:95], v[170:173], v[220:223], v[92:95]
	v_mfma_f32_16x16x32_bf16 v[80:83], v[146:149], v[228:231], v[80:83]
	v_mfma_f32_16x16x32_bf16 v[76:79], v[170:173], v[228:231], v[76:79]
	v_mfma_f32_16x16x32_bf16 v[128:131], v[150:153], v[198:201], v[128:131]
	v_mfma_f32_16x16x32_bf16 v[124:127], v[174:177], v[198:201], v[124:127]
	v_mfma_f32_16x16x32_bf16 v[112:115], v[150:153], v[216:219], v[112:115]
	v_mfma_f32_16x16x32_bf16 v[108:111], v[174:177], v[216:219], v[108:111]
	v_mfma_f32_16x16x32_bf16 v[96:99], v[150:153], v[224:227], v[96:99]
	v_mfma_f32_16x16x32_bf16 v[92:95], v[174:177], v[224:227], v[92:95]
	v_mfma_f32_16x16x32_bf16 v[80:83], v[150:153], v[232:235], v[80:83]
	v_mfma_f32_16x16x32_bf16 v[76:79], v[174:177], v[232:235], v[76:79]
	s_setprio 0
	s_setprio 1
	v_mfma_f32_16x16x32_bf16 v[120:123], v[178:181], v[194:197], v[120:123]
	v_mfma_f32_16x16x32_bf16 v[116:119], v[186:189], v[194:197], v[116:119]
	v_mfma_f32_16x16x32_bf16 v[104:107], v[178:181], v[212:215], v[104:107]
	v_mfma_f32_16x16x32_bf16 v[100:103], v[186:189], v[212:215], v[100:103]
	v_mfma_f32_16x16x32_bf16 v[88:91], v[178:181], v[220:223], v[88:91]
	v_mfma_f32_16x16x32_bf16 v[84:87], v[186:189], v[220:223], v[84:87]
	v_mfma_f32_16x16x32_bf16 v[72:75], v[178:181], v[228:231], v[72:75]
	v_mfma_f32_16x16x32_bf16 v[68:71], v[186:189], v[228:231], v[68:71]
	v_mfma_f32_16x16x32_bf16 v[120:123], v[182:185], v[198:201], v[120:123]
	v_mfma_f32_16x16x32_bf16 v[116:119], v[190:193], v[198:201], v[116:119]
	v_mfma_f32_16x16x32_bf16 v[104:107], v[182:185], v[216:219], v[104:107]
	v_mfma_f32_16x16x32_bf16 v[100:103], v[190:193], v[216:219], v[100:103]
	v_mfma_f32_16x16x32_bf16 v[88:91], v[182:185], v[224:227], v[88:91]
	v_mfma_f32_16x16x32_bf16 v[84:87], v[190:193], v[224:227], v[84:87]
	v_mfma_f32_16x16x32_bf16 v[72:75], v[182:185], v[232:235], v[72:75]
	v_mfma_f32_16x16x32_bf16 v[68:71], v[190:193], v[232:235], v[68:71]
	s_setprio 0
	s_barrier
	s_add_i32 s42, s82, s62
	v_lshl_add_u64 v[154:155], v[154:155], 0, s[52:53]
	s_mov_b32 m0, s42
	ds_read_b128 v[194:197], v166 offset:49152
	ds_read_b128 v[198:201], v166 offset:50176
	ds_read_b128 v[212:215], v166 offset:51200
	ds_read_b128 v[216:219], v166 offset:52224
	ds_read_b128 v[220:223], v166 offset:53248
	ds_read_b128 v[224:227], v166 offset:54272
	ds_read_b128 v[228:231], v166 offset:55296
	ds_read_b128 v[232:235], v166 offset:56320
	s_cmp_lg_u32 s32, 0
	s_cbranch_scc1 .Lbt0_8
	global_load_lds_dwordx4 v[154:155], off
.Lbt0_8:
	s_add_i32 m0, s42, 0x2000
	s_add_u32 s40, s40, 0x10080
	v_lshl_add_u64 v[154:155], v[236:237], 0, s[52:53]
	s_addc_u32 s41, s41, 0
	s_add_i32 s42, s83, s62
	s_cmp_lg_u32 s32, 0
	s_cbranch_scc1 .Lbt0_9
	global_load_lds_dwordx4 v[154:155], off
.Lbt0_9:
	v_lshl_add_u64 v[154:155], s[40:41], 0, v[136:137]
	s_mov_b32 m0, s42
	s_nop 0
	s_cmp_lg_u32 s32, 0
	s_cbranch_scc1 .Lbt0_10
	global_load_lds_dwordx4 v[154:155], off
.Lbt0_10:
	v_lshl_add_u64 v[154:155], s[40:41], 0, v[140:141]
	s_add_i32 m0, s42, 0x2000
	s_nop 0
	s_cmp_lg_u32 s32, 0
	s_cbranch_scc1 .Lbt0_11
	global_load_lds_dwordx4 v[154:155], off
.Lbt0_11:
	v_lshl_add_u64 v[154:155], v[238:239], 0, s[52:53]
	s_mov_b32 m0, s78
	s_nop 0
	s_cmp_lg_u32 s32, 0
	s_cbranch_scc1 .Lbt0_12
	global_load_lds_dwordx4 v[154:155], off
.Lbt0_12:
	v_lshl_add_u64 v[154:155], v[240:241], 0, s[52:53]
	s_mov_b32 m0, s79
	s_nop 0
	s_cmp_lg_u32 s32, 0
	s_cbranch_scc1 .Lbt0_13
	global_load_lds_dwordx4 v[154:155], off
.Lbt0_13:
	s_waitcnt vmcnt(8)
	s_waitcnt lgkmcnt(0)
	s_barrier
	s_setprio 1
	s_waitcnt lgkmcnt(0)
	v_mfma_f32_16x16x32_bf16 v[64:67], v[146:149], v[194:197], v[64:67]
	v_mfma_f32_16x16x32_bf16 v[60:63], v[170:173], v[194:197], v[60:63]
	v_mfma_f32_16x16x32_bf16 v[48:51], v[146:149], v[212:215], v[48:51]
	v_mfma_f32_16x16x32_bf16 v[44:47], v[170:173], v[212:215], v[44:47]
	v_mfma_f32_16x16x32_bf16 v[32:35], v[146:149], v[220:223], v[32:35]
	v_mfma_f32_16x16x32_bf16 v[28:31], v[170:173], v[220:223], v[28:31]
	v_mfma_f32_16x16x32_bf16 v[16:19], v[146:149], v[228:231], v[16:19]
	v_mfma_f32_16x16x32_bf16 v[12:15], v[170:173], v[228:231], v[12:15]
	v_mfma_f32_16x16x32_bf16 v[64:67], v[150:153], v[198:201], v[64:67]
	v_mfma_f32_16x16x32_bf16 v[60:63], v[174:177], v[198:201], v[60:63]
	v_mfma_f32_16x16x32_bf16 v[48:51], v[150:153], v[216:219], v[48:51]
	v_mfma_f32_16x16x32_bf16 v[44:47], v[174:177], v[216:219], v[44:47]
	v_mfma_f32_16x16x32_bf16 v[32:35], v[150:153], v[224:227], v[32:35]
	v_mfma_f32_16x16x32_bf16 v[28:31], v[174:177], v[224:227], v[28:31]
	v_mfma_f32_16x16x32_bf16 v[16:19], v[150:153], v[232:235], v[16:19]
	v_mfma_f32_16x16x32_bf16 v[12:15], v[174:177], v[232:235], v[12:15]
	s_setprio 0
	s_setprio 1
	v_mfma_f32_16x16x32_bf16 v[56:59], v[178:181], v[194:197], v[56:59]
	v_mfma_f32_16x16x32_bf16 v[52:55], v[186:189], v[194:197], v[52:55]
	v_mfma_f32_16x16x32_bf16 v[40:43], v[178:181], v[212:215], v[40:43]
	v_mfma_f32_16x16x32_bf16 v[36:39], v[186:189], v[212:215], v[36:39]
	v_mfma_f32_16x16x32_bf16 v[24:27], v[178:181], v[220:223], v[24:27]
	v_mfma_f32_16x16x32_bf16 v[20:23], v[186:189], v[220:223], v[20:23]
	v_mfma_f32_16x16x32_bf16 v[8:11], v[178:181], v[228:231], v[8:11]
	v_mfma_f32_16x16x32_bf16 v[4:7], v[186:189], v[228:231], v[4:7]
	v_mfma_f32_16x16x32_bf16 v[56:59], v[182:185], v[198:201], v[56:59]
	v_mfma_f32_16x16x32_bf16 v[52:55], v[190:193], v[198:201], v[52:55]
	v_mfma_f32_16x16x32_bf16 v[40:43], v[182:185], v[216:219], v[40:43]
	v_mfma_f32_16x16x32_bf16 v[36:39], v[190:193], v[216:219], v[36:39]
	v_mfma_f32_16x16x32_bf16 v[24:27], v[182:185], v[224:227], v[24:27]
	v_mfma_f32_16x16x32_bf16 v[20:23], v[190:193], v[224:227], v[20:23]
	v_mfma_f32_16x16x32_bf16 v[8:11], v[182:185], v[232:235], v[8:11]
	v_mfma_f32_16x16x32_bf16 v[4:7], v[190:193], v[232:235], v[4:7]
	s_setprio 0
	s_barrier
	s_add_i32 s67, s67, 2
	s_add_u32 s38, s38, 0x100
	s_addc_u32 s39, s39, 0
	s_add_u32 s37, s37, 0x100
	s_addc_u32 s66, s66, 0
	s_cmp_gt_u32 s67, 13
	s_cbranch_scc0 .LBB0_185
	s_and_b64 vcc, exec, s[18:19]
	s_cbranch_vccz .LBB0_188
	s_barrier

; #define PG8_STAGE(bufoff, gbase, voff) do { _Pragma("unroll") for (int _i = 0; _i < 2; ++_i) \
;         __builtin_amdgcn_global_load_lds((const unsigned*)((const char*)(gbase) + (voff)[_i]), (PG8_LAS unsigned*)(lds + (bufoff) + ldsw + _i * 8192), 16, 0, 0); } while (0)
; #define PG8_LDA(dst, b, h) do { _Pragma("unroll") for (int m = 0; m < 4; ++m) _Pragma("unroll") for (int k = 0; k < 2; ++k) dst[m][k] = *(const PG8_LAS bf16x8*)(lds + PG8_SA(b, h) + aoff + m * 2048 + k * 1024); } while (0)
; #define PG8_LDB(dst, b, h) do { _Pragma("unroll") for (int n = 0; n < 2; ++n) _Pragma("unroll") for (int k = 0; k < 2; ++k) dst[n][k] = *(const PG8_LAS bf16x8*)(lds + PG8_SB(b, h) + boff + n * 2048 + k * 1024); } while (0)
; #define PG8_WAIT_V(n) asm volatile("s_waitcnt vmcnt(" #n ")" ::: "memory")
; #define PG8_WAIT_L(n) asm volatile("s_waitcnt lgkmcnt(" #n ")" ::: "memory")
; #define PG8_BAR __builtin_amdgcn_s_barrier()
; #define PG8_SCHED __builtin_amdgcn_sched_barrier(0)
; template <class Epi, class Sched, bool ALIGN_EPI = false, bool SP2 = false>
; __device__ __forceinline__ void gemm_phase(PG8_LAS unsigned char* lds, const Gemm g, const Sched& S, const Epi& E, const int tid) {
;     ...
;         const char* nA = has_next ? (const char*)g.A + (size_t)nxt.pm * tstep : cA; const char* nB = has_next ? (const char*)g.Bt + (size_t)nxt.pn * tstep : cB;
;         for (int t = 0; t < nt; t += 2) {
;             const bool last = (t == nt - 2);
;             const char* a1 = cA + (size_t)(t + 1) * kstep;
;             const char* a2 = last ? nA : cA + (size_t)(t + 2) * kstep; const char* b2 = last ? nB : cB + (size_t)(t + 2) * kstep;
;             const char* a3 = a2 + kstep; const char* b3 = b2 + kstep;
;             if (last && has_next) S.a_ready(nxt);
;             if constexpr (SP2) {
;             PG8_LDB(B0, 0, 0); PG8_LDB(B1, 0, 1); PG8_SCHED; PG8_LDA(At, 0, 0); PG8_STAGE(PG8_SA(1, 1), a1 + hstep, voffA);
;             PG8_WAIT_V(8); PG8_WAIT_L(0); PG8_BAR; PG8_MMA(0, 0, At, B0); PG8_MMA(0, 1, At, B1); PG8_BAR; PG8_SCHED;
;             PG8_LDA(At, 0, 1); PG8_STAGE(PG8_SB(0, 0), b2, voffB); PG8_STAGE(PG8_SB(0, 1), b2 + hstepB, voffB); PG8_STAGE(PG8_SA(0, 0), a2, voffA);
;             PG8_WAIT_V(8); PG8_WAIT_L(0); PG8_BAR; PG8_MMA(1, 0, At, B0); PG8_MMA(1, 1, At, B1); PG8_BAR; PG8_SCHED;
.LBB0_616:
	s_add_u32 s12, s10, 0xfffc0080
	s_addc_u32 s13, s11, -1
	s_add_i32 s79, 0, 0x10000
	s_cmp_eq_u32 s67, 12
	s_cselect_b32 s41, s3, s13
	s_cselect_b32 s40, s7, s12
	s_cselect_b32 s13, s9, s66
	s_cselect_b32 s12, s42, s43
	s_cmp_eq_u32 s67, 12
	s_cselect_b32 s32, 1, 0
	s_andn2_b32 s32, s32, s82
	s_add_i32 s88, 0, 0x14000
	v_add_u32_e32 v160, s79, v174
	v_add_u32_e32 v186, s88, v174
	ds_read_b128 v[148:151], v160
	ds_read_b128 v[152:155], v160 offset:1024
	ds_read_b128 v[156:159], v160 offset:2048
	ds_read_b128 v[160:163], v160 offset:3072
	ds_read_b128 v[164:167], v186
	ds_read_b128 v[178:181], v186 offset:1024
	ds_read_b128 v[182:185], v186 offset:2048
	ds_read_b128 v[186:189], v186 offset:3072
	v_lshl_add_u64 v[232:233], s[10:11], 0, v[144:145]
	s_add_i32 m0, s64, 0xc000
	ds_read_b128 v[190:193], v177
	ds_read_b128 v[194:197], v177 offset:1024
	ds_read_b128 v[198:201], v177 offset:2048
	ds_read_b128 v[212:215], v177 offset:3072
	ds_read_b128 v[216:219], v177 offset:4096
	ds_read_b128 v[220:223], v177 offset:5120
	ds_read_b128 v[224:227], v177 offset:6144
	ds_read_b128 v[228:231], v177 offset:7168
	global_load_lds_dwordx4 v[232:233], off
	v_lshl_add_u64 v[232:233], s[10:11], 0, v[146:147]
	s_add_i32 m0, s64, 0xe000
	s_nop 0
	global_load_lds_dwordx4 v[232:233], off
	s_waitcnt vmcnt(8)
	s_waitcnt lgkmcnt(0)
	s_barrier
	s_setprio 1
	s_waitcnt lgkmcnt(0)
	v_mfma_f32_16x16x32_bf16 v[128:131], v[148:151], v[190:193], v[128:131]
	v_mfma_f32_16x16x32_bf16 v[124:127], v[156:159], v[190:193], v[124:127]
	v_mfma_f32_16x16x32_bf16 v[112:115], v[148:151], v[198:201], v[112:115]
	v_mfma_f32_16x16x32_bf16 v[108:111], v[156:159], v[198:201], v[108:111]
	v_mfma_f32_16x16x32_bf16 v[96:99], v[148:151], v[216:219], v[96:99]
	v_mfma_f32_16x16x32_bf16 v[92:95], v[156:159], v[216:219], v[92:95]
	v_mfma_f32_16x16x32_bf16 v[80:83], v[148:151], v[224:227], v[80:83]
	v_mfma_f32_16x16x32_bf16 v[76:79], v[156:159], v[224:227], v[76:79]
	v_mfma_f32_16x16x32_bf16 v[128:131], v[152:155], v[194:197], v[128:131]
	v_mfma_f32_16x16x32_bf16 v[124:127], v[160:163], v[194:197], v[124:127]
	v_mfma_f32_16x16x32_bf16 v[112:115], v[152:155], v[212:215], v[112:115]
	v_mfma_f32_16x16x32_bf16 v[108:111], v[160:163], v[212:215], v[108:111]
	v_mfma_f32_16x16x32_bf16 v[96:99], v[152:155], v[220:223], v[96:99]
	v_mfma_f32_16x16x32_bf16 v[92:95], v[160:163], v[220:223], v[92:95]
	v_mfma_f32_16x16x32_bf16 v[80:83], v[152:155], v[228:231], v[80:83]
	v_mfma_f32_16x16x32_bf16 v[76:79], v[160:163], v[228:231], v[76:79]
	s_setprio 0
	s_setprio 1
	v_mfma_f32_16x16x32_bf16 v[120:123], v[164:167], v[190:193], v[120:123]
	v_mfma_f32_16x16x32_bf16 v[116:119], v[182:185], v[190:193], v[116:119]
	v_mfma_f32_16x16x32_bf16 v[104:107], v[164:167], v[198:201], v[104:107]
	v_mfma_f32_16x16x32_bf16 v[100:103], v[182:185], v[198:201], v[100:103]
	v_mfma_f32_16x16x32_bf16 v[88:91], v[164:167], v[216:219], v[88:91]
	v_mfma_f32_16x16x32_bf16 v[84:87], v[182:185], v[216:219], v[84:87]
	v_mfma_f32_16x16x32_bf16 v[72:75], v[164:167], v[224:227], v[72:75]
	v_mfma_f32_16x16x32_bf16 v[68:71], v[182:185], v[224:227], v[68:71]
	v_mfma_f32_16x16x32_bf16 v[120:123], v[178:181], v[194:197], v[120:123]
	v_mfma_f32_16x16x32_bf16 v[116:119], v[186:189], v[194:197], v[116:119]
	v_mfma_f32_16x16x32_bf16 v[104:107], v[178:181], v[212:215], v[104:107]
	v_mfma_f32_16x16x32_bf16 v[100:103], v[186:189], v[212:215], v[100:103]
	v_mfma_f32_16x16x32_bf16 v[88:91], v[178:181], v[220:223], v[88:91]
	v_mfma_f32_16x16x32_bf16 v[84:87], v[186:189], v[220:223], v[84:87]
	v_mfma_f32_16x16x32_bf16 v[72:75], v[178:181], v[228:231], v[72:75]
	v_mfma_f32_16x16x32_bf16 v[68:71], v[186:189], v[228:231], v[68:71]
	s_setprio 0
	s_barrier
	s_add_i32 s79, s79, s63
	v_lshl_add_u64 v[232:233], s[12:13], 0, v[136:137]
	s_mov_b32 m0, s79
	ds_read_b128 v[190:193], v177 offset:16384
	ds_read_b128 v[194:197], v177 offset:17408
	ds_read_b128 v[198:201], v177 offset:18432
	ds_read_b128 v[212:215], v177 offset:19456
	ds_read_b128 v[216:219], v177 offset:20480
	ds_read_b128 v[220:223], v177 offset:21504
	ds_read_b128 v[224:227], v177 offset:22528
	ds_read_b128 v[228:231], v177 offset:23552
	s_cmp_lg_u32 s32, 0
	s_cbranch_scc1 .Lbt1_0
	global_load_lds_dwordx4 v[232:233], off
.Lbt1_0:
	s_add_i32 m0, s79, 0x2000
	s_add_u32 vcc_lo, s12, 0x10000
	v_lshl_add_u64 v[234:235], s[12:13], 0, v[140:141]
	s_addc_u32 vcc_hi, s13, 0
	s_add_i32 s79, s88, s63
	s_cmp_lg_u32 s32, 0
	s_cbranch_scc1 .Lbt1_1
	global_load_lds_dwordx4 v[234:235], off
.Lbt1_1:
	v_lshl_add_u64 v[236:237], vcc, 0, v[136:137]
	s_mov_b32 m0, s79
	v_lshl_add_u64 v[238:239], s[40:41], 0, v[138:139]
	s_cmp_lg_u32 s32, 0
	s_cbranch_scc1 .Lbt1_2
	global_load_lds_dwordx4 v[236:237], off
.Lbt1_2:
	v_lshl_add_u64 v[236:237], vcc, 0, v[140:141]
	s_add_i32 m0, s79, 0x2000
	s_nop 0
	s_cmp_lg_u32 s32, 0
	s_cbranch_scc1 .Lbt1_3
	global_load_lds_dwordx4 v[236:237], off
.Lbt1_3:
	v_lshl_add_u64 v[236:237], s[40:41], 0, v[134:135]
	s_mov_b32 m0, s64
	s_nop 0
	s_cmp_lg_u32 s32, 0
	s_cbranch_scc1 .Lbt1_4
	global_load_lds_dwordx4 v[236:237], off
.Lbt1_4:
	s_mov_b32 m0, s65
	s_nop 0
	s_cmp_lg_u32 s32, 0
	s_cbranch_scc1 .Lbt1_5
	global_load_lds_dwordx4 v[238:239], off

; #define PG8_STAGE(bufoff, gbase, voff) do { _Pragma("unroll") for (int _i = 0; _i < 2; ++_i) \
;         __builtin_amdgcn_global_load_lds((const unsigned*)((const char*)(gbase) + (voff)[_i]), (PG8_LAS unsigned*)(lds + (bufoff) + ldsw + _i * 8192), 16, 0, 0); } while (0)
; #define PG8_LDA(dst, b, h) do { _Pragma("unroll") for (int m = 0; m < 4; ++m) _Pragma("unroll") for (int k = 0; k < 2; ++k) dst[m][k] = *(const PG8_LAS bf16x8*)(lds + PG8_SA(b, h) + aoff + m * 2048 + k * 1024); } while (0)
; #define PG8_LDB(dst, b, h) do { _Pragma("unroll") for (int n = 0; n < 2; ++n) _Pragma("unroll") for (int k = 0; k < 2; ++k) dst[n][k] = *(const PG8_LAS bf16x8*)(lds + PG8_SB(b, h) + boff + n * 2048 + k * 1024); } while (0)
; #define PG8_MMA(ai, bj, At, Bt) do { __builtin_amdgcn_s_setprio(1); _Pragma("unroll") for (int m = 0; m < 4; ++m) _Pragma("unroll") for (int n = 0; n < 2; ++n) _Pragma("unroll") for (int k = 0; k < 2; ++k) \
;         acc[ai][bj][m][n] = __builtin_amdgcn_mfma_f32_16x16x32_bf16(Bt[n][k], At[m][k], acc[ai][bj][m][n], 0, 0, 0); __builtin_amdgcn_s_setprio(0); } while (0)
; #define PG8_WAIT_V(n) asm volatile("s_waitcnt vmcnt(" #n ")" ::: "memory")
; #define PG8_WAIT_L(n) asm volatile("s_waitcnt lgkmcnt(" #n ")" ::: "memory")
; #define PG8_BAR __builtin_amdgcn_s_barrier()
; #define PG8_SCHED __builtin_amdgcn_sched_barrier(0)
; template <class Epi, class Sched, bool ALIGN_EPI = false, bool SP2 = false>
; __device__ __forceinline__ void gemm_phase(PG8_LAS unsigned char* lds, const Gemm g, const Sched& S, const Epi& E, const int tid) {
;     ...
;             PG8_WAIT_V(8); PG8_WAIT_L(0); PG8_BAR; PG8_MMA(1, 0, At, B0); PG8_MMA(1, 1, At, B1); PG8_BAR; PG8_SCHED;
;             PG8_LDB(B0, 1, 0); PG8_LDB(B1, 1, 1); PG8_SCHED; PG8_LDA(At, 1, 0); PG8_STAGE(PG8_SA(0, 1), a2 + hstep, voffA);
;             PG8_WAIT_V(8); PG8_WAIT_L(0); PG8_BAR; PG8_MMA(0, 0, At, B0); PG8_MMA(0, 1, At, B1); PG8_BAR; PG8_SCHED;
.Lbw1_2:
	s_waitcnt lgkmcnt(0)
	s_barrier
	s_setprio 1
	s_waitcnt lgkmcnt(0)
	v_mfma_f32_16x16x32_bf16 v[64:67], v[148:151], v[190:193], v[64:67]
	v_mfma_f32_16x16x32_bf16 v[60:63], v[156:159], v[190:193], v[60:63]
	v_mfma_f32_16x16x32_bf16 v[48:51], v[148:151], v[198:201], v[48:51]
	v_mfma_f32_16x16x32_bf16 v[44:47], v[156:159], v[198:201], v[44:47]
	v_mfma_f32_16x16x32_bf16 v[32:35], v[148:151], v[216:219], v[32:35]
	v_mfma_f32_16x16x32_bf16 v[28:31], v[156:159], v[216:219], v[28:31]
	v_mfma_f32_16x16x32_bf16 v[16:19], v[148:151], v[224:227], v[16:19]
	v_mfma_f32_16x16x32_bf16 v[12:15], v[156:159], v[224:227], v[12:15]
	v_mfma_f32_16x16x32_bf16 v[64:67], v[152:155], v[194:197], v[64:67]
	v_mfma_f32_16x16x32_bf16 v[60:63], v[160:163], v[194:197], v[60:63]
	v_mfma_f32_16x16x32_bf16 v[48:51], v[152:155], v[212:215], v[48:51]
	v_mfma_f32_16x16x32_bf16 v[44:47], v[160:163], v[212:215], v[44:47]
	v_mfma_f32_16x16x32_bf16 v[32:35], v[152:155], v[220:223], v[32:35]
	v_mfma_f32_16x16x32_bf16 v[28:31], v[160:163], v[220:223], v[28:31]
	v_mfma_f32_16x16x32_bf16 v[16:19], v[152:155], v[228:231], v[16:19]
	v_mfma_f32_16x16x32_bf16 v[12:15], v[160:163], v[228:231], v[12:15]
	s_setprio 0
	s_setprio 1
	v_mfma_f32_16x16x32_bf16 v[56:59], v[164:167], v[190:193], v[56:59]
	v_mfma_f32_16x16x32_bf16 v[52:55], v[182:185], v[190:193], v[52:55]
	v_mfma_f32_16x16x32_bf16 v[40:43], v[164:167], v[198:201], v[40:43]
	v_mfma_f32_16x16x32_bf16 v[36:39], v[182:185], v[198:201], v[36:39]
	v_mfma_f32_16x16x32_bf16 v[24:27], v[164:167], v[216:219], v[24:27]
	v_mfma_f32_16x16x32_bf16 v[20:23], v[182:185], v[216:219], v[20:23]
	v_mfma_f32_16x16x32_bf16 v[8:11], v[164:167], v[224:227], v[8:11]
	v_mfma_f32_16x16x32_bf16 v[4:7], v[182:185], v[224:227], v[4:7]
	v_mfma_f32_16x16x32_bf16 v[56:59], v[178:181], v[194:197], v[56:59]
	v_mfma_f32_16x16x32_bf16 v[52:55], v[186:189], v[194:197], v[52:55]
	v_mfma_f32_16x16x32_bf16 v[40:43], v[178:181], v[212:215], v[40:43]
	v_mfma_f32_16x16x32_bf16 v[36:39], v[186:189], v[212:215], v[36:39]
	v_mfma_f32_16x16x32_bf16 v[24:27], v[178:181], v[220:223], v[24:27]
	v_mfma_f32_16x16x32_bf16 v[20:23], v[186:189], v[220:223], v[20:23]
	v_mfma_f32_16x16x32_bf16 v[8:11], v[178:181], v[228:231], v[8:11]
	v_mfma_f32_16x16x32_bf16 v[4:7], v[186:189], v[228:231], v[4:7]
	s_setprio 0
	s_barrier
	s_add_i32 s79, 0, 0x18000
	s_add_i32 s88, 0, 0x1c000
	v_add_u32_e32 v160, s79, v174
	v_add_u32_e32 v186, s88, v174
	ds_read_b128 v[148:151], v160
	ds_read_b128 v[152:155], v160 offset:1024
	ds_read_b128 v[156:159], v160 offset:2048
	ds_read_b128 v[160:163], v160 offset:3072
	ds_read_b128 v[164:167], v186
	ds_read_b128 v[178:181], v186 offset:1024
	ds_read_b128 v[182:185], v186 offset:2048
	ds_read_b128 v[186:189], v186 offset:3072
	s_add_u32 s40, s40, 0x40000
	s_addc_u32 s41, s41, 0
	s_mov_b32 m0, s86
	v_lshl_add_u64 v[240:241], s[40:41], 0, v[134:135]
	ds_read_b128 v[190:193], v177 offset:32768
	ds_read_b128 v[194:197], v177 offset:33792
	ds_read_b128 v[198:201], v177 offset:34816
	ds_read_b128 v[212:215], v177 offset:35840
	ds_read_b128 v[216:219], v177 offset:36864
	ds_read_b128 v[220:223], v177 offset:37888
	ds_read_b128 v[224:227], v177 offset:38912
	ds_read_b128 v[228:231], v177 offset:39936
	s_cmp_lg_u32 s32, 0
	s_cbranch_scc1 .Lbt1_6
	global_load_lds_dwordx4 v[240:241], off
.Lbt1_6:
	v_lshl_add_u64 v[240:241], s[40:41], 0, v[138:139]
	s_mov_b32 m0, s87
	s_nop 0
	s_cmp_lg_u32 s32, 0
	s_cbranch_scc1 .Lbt1_7
	global_load_lds_dwordx4 v[240:241], off

; #define PG8_STAGE(bufoff, gbase, voff) do { _Pragma("unroll") for (int _i = 0; _i < 2; ++_i) \
;         __builtin_amdgcn_global_load_lds((const unsigned*)((const char*)(gbase) + (voff)[_i]), (PG8_LAS unsigned*)(lds + (bufoff) + ldsw + _i * 8192), 16, 0, 0); } while (0)
; #define PG8_LDA(dst, b, h) do { _Pragma("unroll") for (int m = 0; m < 4; ++m) _Pragma("unroll") for (int k = 0; k < 2; ++k) dst[m][k] = *(const PG8_LAS bf16x8*)(lds + PG8_SA(b, h) + aoff + m * 2048 + k * 1024); } while (0)
; #define PG8_LDB(dst, b, h) do { _Pragma("unroll") for (int n = 0; n < 2; ++n) _Pragma("unroll") for (int k = 0; k < 2; ++k) dst[n][k] = *(const PG8_LAS bf16x8*)(lds + PG8_SB(b, h) + boff + n * 2048 + k * 1024); } while (0)
; #define PG8_MMA(ai, bj, At, Bt) do { __builtin_amdgcn_s_setprio(1); _Pragma("unroll") for (int m = 0; m < 4; ++m) _Pragma("unroll") for (int n = 0; n < 2; ++n) _Pragma("unroll") for (int k = 0; k < 2; ++k) \
;         acc[ai][bj][m][n] = __builtin_amdgcn_mfma_f32_16x16x32_bf16(Bt[n][k], At[m][k], acc[ai][bj][m][n], 0, 0, 0); __builtin_amdgcn_s_setprio(0); } while (0)
; #define PG8_WAIT_V(n) asm volatile("s_waitcnt vmcnt(" #n ")" ::: "memory")
; #define PG8_WAIT_L(n) asm volatile("s_waitcnt lgkmcnt(" #n ")" ::: "memory")
; #define PG8_BAR __builtin_amdgcn_s_barrier()
; #define PG8_SCHED __builtin_amdgcn_sched_barrier(0)
; template <class Epi, class Sched, bool ALIGN_EPI = false, bool SP2 = false>
; __device__ __forceinline__ void gemm_phase(PG8_LAS unsigned char* lds, const Gemm g, const Sched& S, const Epi& E, const int tid) {
;     ...
;             PG8_WAIT_V(8); PG8_WAIT_L(0); PG8_BAR; PG8_MMA(1, 0, At, B0); PG8_MMA(1, 1, At, B1); PG8_BAR; PG8_SCHED;
;             PG8_LDB(B0, 1, 0); PG8_LDB(B1, 1, 1); PG8_SCHED; PG8_LDA(At, 1, 0); PG8_STAGE(PG8_SA(0, 1), a2 + hstep, voffA);
;             PG8_WAIT_V(8); PG8_WAIT_L(0); PG8_BAR; PG8_MMA(0, 0, At, B0); PG8_MMA(0, 1, At, B1); PG8_BAR; PG8_SCHED;
;             PG8_LDA(At, 1, 1); PG8_STAGE(PG8_SB(1, 0), b3, voffB); PG8_STAGE(PG8_SB(1, 1), b3 + hstepB, voffB); PG8_STAGE(PG8_SA(1, 0), a3, voffA);
;             PG8_WAIT_V(8); PG8_WAIT_L(0); PG8_BAR; PG8_MMA(1, 0, At, B0); PG8_MMA(1, 1, At, B1); PG8_BAR; PG8_SCHED;
.Lbw1_0:
	s_waitcnt lgkmcnt(0)
	s_barrier
	s_setprio 1
	s_waitcnt lgkmcnt(0)
	v_mfma_f32_16x16x32_bf16 v[128:131], v[148:151], v[190:193], v[128:131]
	v_mfma_f32_16x16x32_bf16 v[124:127], v[156:159], v[190:193], v[124:127]
	v_mfma_f32_16x16x32_bf16 v[112:115], v[148:151], v[198:201], v[112:115]
	v_mfma_f32_16x16x32_bf16 v[108:111], v[156:159], v[198:201], v[108:111]
	v_mfma_f32_16x16x32_bf16 v[96:99], v[148:151], v[216:219], v[96:99]
	v_mfma_f32_16x16x32_bf16 v[92:95], v[156:159], v[216:219], v[92:95]
	v_mfma_f32_16x16x32_bf16 v[80:83], v[148:151], v[224:227], v[80:83]
	v_mfma_f32_16x16x32_bf16 v[76:79], v[156:159], v[224:227], v[76:79]
	v_mfma_f32_16x16x32_bf16 v[128:131], v[152:155], v[194:197], v[128:131]
	v_mfma_f32_16x16x32_bf16 v[124:127], v[160:163], v[194:197], v[124:127]
	v_mfma_f32_16x16x32_bf16 v[112:115], v[152:155], v[212:215], v[112:115]
	v_mfma_f32_16x16x32_bf16 v[108:111], v[160:163], v[212:215], v[108:111]
	v_mfma_f32_16x16x32_bf16 v[96:99], v[152:155], v[220:223], v[96:99]
	v_mfma_f32_16x16x32_bf16 v[92:95], v[160:163], v[220:223], v[92:95]
	v_mfma_f32_16x16x32_bf16 v[80:83], v[152:155], v[228:231], v[80:83]
	v_mfma_f32_16x16x32_bf16 v[76:79], v[160:163], v[228:231], v[76:79]
	s_setprio 0
	s_setprio 1
	v_mfma_f32_16x16x32_bf16 v[120:123], v[164:167], v[190:193], v[120:123]
	v_mfma_f32_16x16x32_bf16 v[116:119], v[182:185], v[190:193], v[116:119]
	v_mfma_f32_16x16x32_bf16 v[104:107], v[164:167], v[198:201], v[104:107]
	v_mfma_f32_16x16x32_bf16 v[100:103], v[182:185], v[198:201], v[100:103]
	v_mfma_f32_16x16x32_bf16 v[88:91], v[164:167], v[216:219], v[88:91]
	v_mfma_f32_16x16x32_bf16 v[84:87], v[182:185], v[216:219], v[84:87]
	v_mfma_f32_16x16x32_bf16 v[72:75], v[164:167], v[224:227], v[72:75]
	v_mfma_f32_16x16x32_bf16 v[68:71], v[182:185], v[224:227], v[68:71]
	v_mfma_f32_16x16x32_bf16 v[120:123], v[178:181], v[194:197], v[120:123]
	v_mfma_f32_16x16x32_bf16 v[116:119], v[186:189], v[194:197], v[116:119]
	v_mfma_f32_16x16x32_bf16 v[104:107], v[178:181], v[212:215], v[104:107]
	v_mfma_f32_16x16x32_bf16 v[100:103], v[186:189], v[212:215], v[100:103]
	v_mfma_f32_16x16x32_bf16 v[88:91], v[178:181], v[220:223], v[88:91]
	v_mfma_f32_16x16x32_bf16 v[84:87], v[186:189], v[220:223], v[84:87]
	v_mfma_f32_16x16x32_bf16 v[72:75], v[178:181], v[228:231], v[72:75]
	v_mfma_f32_16x16x32_bf16 v[68:71], v[186:189], v[228:231], v[68:71]
	s_setprio 0
	s_barrier
	s_add_i32 s40, s79, s63
	v_lshl_add_u64 v[232:233], v[232:233], 0, s[52:53]
	s_mov_b32 m0, s40
	ds_read_b128 v[190:193], v177 offset:49152
	ds_read_b128 v[194:197], v177 offset:50176
	ds_read_b128 v[198:201], v177 offset:51200
	ds_read_b128 v[212:215], v177 offset:52224
	ds_read_b128 v[216:219], v177 offset:53248
	ds_read_b128 v[220:223], v177 offset:54272
	ds_read_b128 v[224:227], v177 offset:55296
	ds_read_b128 v[228:231], v177 offset:56320
	s_cmp_lg_u32 s32, 0
	s_cbranch_scc1 .Lbt1_8
	global_load_lds_dwordx4 v[232:233], off
.Lbt1_8:
	s_add_i32 m0, s40, 0x2000
	s_add_u32 s12, s12, 0x10080
	v_lshl_add_u64 v[232:233], v[234:235], 0, s[52:53]
	s_addc_u32 s13, s13, 0
	s_add_i32 s40, s88, s63
	s_cmp_lg_u32 s32, 0
	s_cbranch_scc1 .Lbt1_9
	global_load_lds_dwordx4 v[232:233], off
.Lbt1_9:
	v_lshl_add_u64 v[232:233], s[12:13], 0, v[136:137]
	s_mov_b32 m0, s40
	s_nop 0
	s_cmp_lg_u32 s32, 0
	s_cbranch_scc1 .Lbt1_10
	global_load_lds_dwordx4 v[232:233], off
.Lbt1_10:
	v_lshl_add_u64 v[232:233], s[12:13], 0, v[140:141]
	s_add_i32 m0, s40, 0x2000
	s_nop 0
	s_cmp_lg_u32 s32, 0
	s_cbranch_scc1 .Lbt1_11
	global_load_lds_dwordx4 v[232:233], off
.Lbt1_11:
	v_lshl_add_u64 v[232:233], v[236:237], 0, s[52:53]
	s_mov_b32 m0, s93
	s_nop 0
	s_cmp_lg_u32 s32, 0
	s_cbranch_scc1 .Lbt1_12
	global_load_lds_dwordx4 v[232:233], off
.Lbt1_12:
	v_lshl_add_u64 v[232:233], v[238:239], 0, s[52:53]
	s_mov_b32 m0, s95
	s_nop 0
	s_cmp_lg_u32 s32, 0
	s_cbranch_scc1 .Lbt1_13
	global_load_lds_dwordx4 v[232:233], off
.Lbt1_13:
	s_waitcnt vmcnt(8)
	s_waitcnt lgkmcnt(0)
	s_barrier
	s_setprio 1
	s_waitcnt lgkmcnt(0)
	v_mfma_f32_16x16x32_bf16 v[64:67], v[148:151], v[190:193], v[64:67]
	v_mfma_f32_16x16x32_bf16 v[60:63], v[156:159], v[190:193], v[60:63]
	v_mfma_f32_16x16x32_bf16 v[48:51], v[148:151], v[198:201], v[48:51]
	v_mfma_f32_16x16x32_bf16 v[44:47], v[156:159], v[198:201], v[44:47]
	v_mfma_f32_16x16x32_bf16 v[32:35], v[148:151], v[216:219], v[32:35]
	v_mfma_f32_16x16x32_bf16 v[28:31], v[156:159], v[216:219], v[28:31]
	v_mfma_f32_16x16x32_bf16 v[16:19], v[148:151], v[224:227], v[16:19]
	v_mfma_f32_16x16x32_bf16 v[12:15], v[156:159], v[224:227], v[12:15]
	v_mfma_f32_16x16x32_bf16 v[64:67], v[152:155], v[194:197], v[64:67]
	v_mfma_f32_16x16x32_bf16 v[60:63], v[160:163], v[194:197], v[60:63]
	v_mfma_f32_16x16x32_bf16 v[48:51], v[152:155], v[212:215], v[48:51]
	v_mfma_f32_16x16x32_bf16 v[44:47], v[160:163], v[212:215], v[44:47]
	v_mfma_f32_16x16x32_bf16 v[32:35], v[152:155], v[220:223], v[32:35]
	v_mfma_f32_16x16x32_bf16 v[28:31], v[160:163], v[220:223], v[28:31]
	v_mfma_f32_16x16x32_bf16 v[16:19], v[152:155], v[228:231], v[16:19]
	v_mfma_f32_16x16x32_bf16 v[12:15], v[160:163], v[228:231], v[12:15]
	s_setprio 0
	s_setprio 1
	v_mfma_f32_16x16x32_bf16 v[56:59], v[164:167], v[190:193], v[56:59]
	v_mfma_f32_16x16x32_bf16 v[52:55], v[182:185], v[190:193], v[52:55]
	v_mfma_f32_16x16x32_bf16 v[40:43], v[164:167], v[198:201], v[40:43]
	v_mfma_f32_16x16x32_bf16 v[36:39], v[182:185], v[198:201], v[36:39]
	v_mfma_f32_16x16x32_bf16 v[24:27], v[164:167], v[216:219], v[24:27]
	v_mfma_f32_16x16x32_bf16 v[20:23], v[182:185], v[216:219], v[20:23]
	v_mfma_f32_16x16x32_bf16 v[8:11], v[164:167], v[224:227], v[8:11]
	v_mfma_f32_16x16x32_bf16 v[4:7], v[182:185], v[224:227], v[4:7]
	v_mfma_f32_16x16x32_bf16 v[56:59], v[178:181], v[194:197], v[56:59]
	v_mfma_f32_16x16x32_bf16 v[52:55], v[186:189], v[194:197], v[52:55]
	v_mfma_f32_16x16x32_bf16 v[40:43], v[178:181], v[212:215], v[40:43]
	v_mfma_f32_16x16x32_bf16 v[36:39], v[186:189], v[212:215], v[36:39]
	v_mfma_f32_16x16x32_bf16 v[24:27], v[178:181], v[220:223], v[24:27]
	v_mfma_f32_16x16x32_bf16 v[20:23], v[186:189], v[220:223], v[20:23]
	v_mfma_f32_16x16x32_bf16 v[8:11], v[178:181], v[228:231], v[8:11]
	v_mfma_f32_16x16x32_bf16 v[4:7], v[186:189], v[228:231], v[4:7]
	s_setprio 0
	s_barrier
	s_add_i32 s67, s67, 2
	s_add_u32 s10, s10, 0x100
	s_addc_u32 s11, s11, 0
	s_add_u32 s43, s43, 0x100
	s_addc_u32 s66, s66, 0
	s_cmp_gt_u32 s67, 13
	s_cbranch_scc0 .LBB0_616
	s_and_b64 vcc, exec, s[36:37]
	s_cbranch_vccz .LBB0_619
	s_barrier

; #define PG8_STAGE(bufoff, gbase, voff) do { _Pragma("unroll") for (int _i = 0; _i < 2; ++_i) \
;         __builtin_amdgcn_global_load_lds((const unsigned*)((const char*)(gbase) + (voff)[_i]), (PG8_LAS unsigned*)(lds + (bufoff) + ldsw + _i * 8192), 16, 0, 0); } while (0)
; #define PG8_LDA(dst, b, h) do { _Pragma("unroll") for (int m = 0; m < 4; ++m) _Pragma("unroll") for (int k = 0; k < 2; ++k) dst[m][k] = *(const PG8_LAS bf16x8*)(lds + PG8_SA(b, h) + aoff + m * 2048 + k * 1024); } while (0)
; #define PG8_LDB(dst, b, h) do { _Pragma("unroll") for (int n = 0; n < 2; ++n) _Pragma("unroll") for (int k = 0; k < 2; ++k) dst[n][k] = *(const PG8_LAS bf16x8*)(lds + PG8_SB(b, h) + boff + n * 2048 + k * 1024); } while (0)
; #define PG8_WAIT_V(n) asm volatile("s_waitcnt vmcnt(" #n ")" ::: "memory")
; #define PG8_WAIT_L(n) asm volatile("s_waitcnt lgkmcnt(" #n ")" ::: "memory")
; #define PG8_BAR __builtin_amdgcn_s_barrier()
; #define PG8_SCHED __builtin_amdgcn_sched_barrier(0)
; template <class Epi, class Sched, bool ALIGN_EPI = false, bool SP2 = false>
; __device__ __forceinline__ void gemm_phase(PG8_LAS unsigned char* lds, const Gemm g, const Sched& S, const Epi& E, const int tid) {
;     ...
;         const char* nA = has_next ? (const char*)g.A + (size_t)nxt.pm * tstep : cA; const char* nB = has_next ? (const char*)g.Bt + (size_t)nxt.pn * tstep : cB;
;         for (int t = 0; t < nt; t += 2) {
;             const bool last = (t == nt - 2);
;             const char* a1 = cA + (size_t)(t + 1) * kstep;
;             const char* a2 = last ? nA : cA + (size_t)(t + 2) * kstep; const char* b2 = last ? nB : cB + (size_t)(t + 2) * kstep;
;             const char* a3 = a2 + kstep; const char* b3 = b2 + kstep;
;             if (last && has_next) S.a_ready(nxt);
;             if constexpr (SP2) {
;             PG8_LDB(B0, 0, 0); PG8_LDB(B1, 0, 1); PG8_SCHED; PG8_LDA(At, 0, 0); PG8_STAGE(PG8_SA(1, 1), a1 + hstep, voffA);
;             PG8_WAIT_V(8); PG8_WAIT_L(0); PG8_BAR; PG8_MMA(0, 0, At, B0); PG8_MMA(0, 1, At, B1); PG8_BAR; PG8_SCHED;
;             PG8_LDA(At, 0, 1); PG8_STAGE(PG8_SB(0, 0), b2, voffB); PG8_STAGE(PG8_SB(0, 1), b2 + hstepB, voffB); PG8_STAGE(PG8_SA(0, 0), a2, voffA);
;             PG8_WAIT_V(8); PG8_WAIT_L(0); PG8_BAR; PG8_MMA(1, 0, At, B0); PG8_MMA(1, 1, At, B1); PG8_BAR; PG8_SCHED;
.LBB0_979:
	s_add_u32 s36, s38, 0xfffc0080
	s_addc_u32 s37, s39, -1
	s_add_i32 s81, 0, 0x10000
	s_cmp_eq_u32 s80, 12
	s_cselect_b32 s41, s19, s37
	s_cselect_b32 s40, s25, s36
	v_add_u32_e32 v150, s81, v158
	s_cselect_b32 s37, s17, s79
	s_cselect_b32 s36, s76, s78
	s_cmp_eq_u32 s80, 12
	s_cselect_b32 s32, 1, 0
	s_andn2_b32 s32, s32, s30
	s_add_i32 s84, 0, 0x14000
	ds_read_b128 v[146:149], v150
	ds_read_b128 v[162:165], v150 offset:1024
	ds_read_b128 v[170:173], v150 offset:2048
	ds_read_b128 v[174:177], v150 offset:3072
	v_add_u32_e32 v150, s84, v158
	ds_read_b128 v[178:181], v150
	ds_read_b128 v[182:185], v150 offset:1024
	ds_read_b128 v[186:189], v150 offset:2048
	ds_read_b128 v[190:193], v150 offset:3072
	v_lshl_add_u64 v[150:151], s[38:39], 0, v[142:143]
	s_add_i32 m0, s29, 0xc000
	ds_read_b128 v[194:197], v160
	ds_read_b128 v[198:201], v160 offset:1024
	ds_read_b128 v[212:215], v160 offset:2048
	ds_read_b128 v[216:219], v160 offset:3072
	ds_read_b128 v[220:223], v160 offset:4096
	ds_read_b128 v[224:227], v160 offset:5120
	ds_read_b128 v[228:231], v160 offset:6144
	ds_read_b128 v[232:235], v160 offset:7168
	global_load_lds_dwordx4 v[150:151], off
	v_lshl_add_u64 v[150:151], s[38:39], 0, v[144:145]
	s_add_i32 m0, s29, 0xe000
	s_nop 0
	global_load_lds_dwordx4 v[150:151], off
	s_waitcnt vmcnt(8)
	s_waitcnt lgkmcnt(0)
	s_barrier
	s_setprio 1
	s_waitcnt lgkmcnt(0)
	v_mfma_f32_16x16x32_bf16 v[120:123], v[146:149], v[194:197], v[120:123]
	v_mfma_f32_16x16x32_bf16 v[128:131], v[170:173], v[194:197], v[128:131]
	v_mfma_f32_16x16x32_bf16 v[100:103], v[146:149], v[212:215], v[100:103]
	v_mfma_f32_16x16x32_bf16 v[108:111], v[170:173], v[212:215], v[108:111]
	v_mfma_f32_16x16x32_bf16 v[84:87], v[146:149], v[220:223], v[84:87]
	v_mfma_f32_16x16x32_bf16 v[92:95], v[170:173], v[220:223], v[92:95]
	v_mfma_f32_16x16x32_bf16 v[68:71], v[146:149], v[228:231], v[68:71]
	v_mfma_f32_16x16x32_bf16 v[76:79], v[170:173], v[228:231], v[76:79]
	v_mfma_f32_16x16x32_bf16 v[120:123], v[162:165], v[198:201], v[120:123]
	v_mfma_f32_16x16x32_bf16 v[128:131], v[174:177], v[198:201], v[128:131]
	v_mfma_f32_16x16x32_bf16 v[100:103], v[162:165], v[216:219], v[100:103]
	v_mfma_f32_16x16x32_bf16 v[108:111], v[174:177], v[216:219], v[108:111]
	v_mfma_f32_16x16x32_bf16 v[84:87], v[162:165], v[224:227], v[84:87]
	v_mfma_f32_16x16x32_bf16 v[92:95], v[174:177], v[224:227], v[92:95]
	v_mfma_f32_16x16x32_bf16 v[68:71], v[162:165], v[232:235], v[68:71]
	v_mfma_f32_16x16x32_bf16 v[76:79], v[174:177], v[232:235], v[76:79]
	s_setprio 0
	s_setprio 1
	v_mfma_f32_16x16x32_bf16 v[116:119], v[178:181], v[194:197], v[116:119]
	v_mfma_f32_16x16x32_bf16 v[124:127], v[186:189], v[194:197], v[124:127]
	v_mfma_f32_16x16x32_bf16 v[104:107], v[178:181], v[212:215], v[104:107]
	v_mfma_f32_16x16x32_bf16 v[112:115], v[186:189], v[212:215], v[112:115]
	v_mfma_f32_16x16x32_bf16 v[88:91], v[178:181], v[220:223], v[88:91]
	v_mfma_f32_16x16x32_bf16 v[96:99], v[186:189], v[220:223], v[96:99]
	v_mfma_f32_16x16x32_bf16 v[72:75], v[178:181], v[228:231], v[72:75]
	v_mfma_f32_16x16x32_bf16 v[80:83], v[186:189], v[228:231], v[80:83]
	v_mfma_f32_16x16x32_bf16 v[116:119], v[182:185], v[198:201], v[116:119]
	v_mfma_f32_16x16x32_bf16 v[124:127], v[190:193], v[198:201], v[124:127]
	v_mfma_f32_16x16x32_bf16 v[104:107], v[182:185], v[216:219], v[104:107]
	v_mfma_f32_16x16x32_bf16 v[112:115], v[190:193], v[216:219], v[112:115]
	v_mfma_f32_16x16x32_bf16 v[88:91], v[182:185], v[224:227], v[88:91]
	v_mfma_f32_16x16x32_bf16 v[96:99], v[190:193], v[224:227], v[96:99]
	v_mfma_f32_16x16x32_bf16 v[72:75], v[182:185], v[232:235], v[72:75]
	v_mfma_f32_16x16x32_bf16 v[80:83], v[190:193], v[232:235], v[80:83]
	s_setprio 0
	s_barrier
	s_add_i32 s81, s81, s43
	v_lshl_add_u64 v[150:151], s[36:37], 0, v[136:137]
	s_mov_b32 m0, s81
	ds_read_b128 v[194:197], v160 offset:16384
	ds_read_b128 v[198:201], v160 offset:17408
	ds_read_b128 v[212:215], v160 offset:18432
	ds_read_b128 v[216:219], v160 offset:19456
	ds_read_b128 v[220:223], v160 offset:20480
	ds_read_b128 v[224:227], v160 offset:21504
	ds_read_b128 v[228:231], v160 offset:22528
	ds_read_b128 v[232:235], v160 offset:23552
	s_cmp_lg_u32 s32, 0
	s_cbranch_scc1 .Lbt2_0
	global_load_lds_dwordx4 v[150:151], off
.Lbt2_0:
	s_add_i32 m0, s81, 0x2000
	s_add_u32 s82, s36, 0x10000
	v_lshl_add_u64 v[166:167], s[36:37], 0, v[140:141]
	s_addc_u32 s83, s37, 0
	s_add_i32 s81, s84, s43
	s_cmp_lg_u32 s32, 0
	s_cbranch_scc1 .Lbt2_1
	global_load_lds_dwordx4 v[166:167], off
.Lbt2_1:
	v_lshl_add_u64 v[236:237], s[82:83], 0, v[136:137]
	s_mov_b32 m0, s81
	v_lshl_add_u64 v[238:239], s[40:41], 0, v[138:139]
	s_cmp_lg_u32 s32, 0
	s_cbranch_scc1 .Lbt2_2
	global_load_lds_dwordx4 v[236:237], off
.Lbt2_2:
	v_lshl_add_u64 v[236:237], s[82:83], 0, v[140:141]
	s_add_i32 m0, s81, 0x2000
	s_nop 0
	s_cmp_lg_u32 s32, 0
	s_cbranch_scc1 .Lbt2_3
	global_load_lds_dwordx4 v[236:237], off
.Lbt2_3:
	v_lshl_add_u64 v[236:237], s[40:41], 0, v[134:135]
	s_mov_b32 m0, s29
	s_nop 0
	s_cmp_lg_u32 s32, 0
	s_cbranch_scc1 .Lbt2_4
	global_load_lds_dwordx4 v[236:237], off
.Lbt2_4:
	s_mov_b32 m0, s55
	s_nop 0
	s_cmp_lg_u32 s32, 0
	s_cbranch_scc1 .Lbt2_5
	global_load_lds_dwordx4 v[238:239], off

; #define PG8_STAGE(bufoff, gbase, voff) do { _Pragma("unroll") for (int _i = 0; _i < 2; ++_i) \
;         __builtin_amdgcn_global_load_lds((const unsigned*)((const char*)(gbase) + (voff)[_i]), (PG8_LAS unsigned*)(lds + (bufoff) + ldsw + _i * 8192), 16, 0, 0); } while (0)
; #define PG8_LDA(dst, b, h) do { _Pragma("unroll") for (int m = 0; m < 4; ++m) _Pragma("unroll") for (int k = 0; k < 2; ++k) dst[m][k] = *(const PG8_LAS bf16x8*)(lds + PG8_SA(b, h) + aoff + m * 2048 + k * 1024); } while (0)
; #define PG8_LDB(dst, b, h) do { _Pragma("unroll") for (int n = 0; n < 2; ++n) _Pragma("unroll") for (int k = 0; k < 2; ++k) dst[n][k] = *(const PG8_LAS bf16x8*)(lds + PG8_SB(b, h) + boff + n * 2048 + k * 1024); } while (0)
; #define PG8_MMA(ai, bj, At, Bt) do { __builtin_amdgcn_s_setprio(1); _Pragma("unroll") for (int m = 0; m < 4; ++m) _Pragma("unroll") for (int n = 0; n < 2; ++n) _Pragma("unroll") for (int k = 0; k < 2; ++k) \
;         acc[ai][bj][m][n] = __builtin_amdgcn_mfma_f32_16x16x32_bf16(Bt[n][k], At[m][k], acc[ai][bj][m][n], 0, 0, 0); __builtin_amdgcn_s_setprio(0); } while (0)
; #define PG8_WAIT_V(n) asm volatile("s_waitcnt vmcnt(" #n ")" ::: "memory")
; #define PG8_WAIT_L(n) asm volatile("s_waitcnt lgkmcnt(" #n ")" ::: "memory")
; #define PG8_BAR __builtin_amdgcn_s_barrier()
; #define PG8_SCHED __builtin_amdgcn_sched_barrier(0)
; template <class Epi, class Sched, bool ALIGN_EPI = false, bool SP2 = false>
; __device__ __forceinline__ void gemm_phase(PG8_LAS unsigned char* lds, const Gemm g, const Sched& S, const Epi& E, const int tid) {
;     ...
;             PG8_WAIT_V(8); PG8_WAIT_L(0); PG8_BAR; PG8_MMA(1, 0, At, B0); PG8_MMA(1, 1, At, B1); PG8_BAR; PG8_SCHED;
;             PG8_LDB(B0, 1, 0); PG8_LDB(B1, 1, 1); PG8_SCHED; PG8_LDA(At, 1, 0); PG8_STAGE(PG8_SA(0, 1), a2 + hstep, voffA);
;             PG8_WAIT_V(8); PG8_WAIT_L(0); PG8_BAR; PG8_MMA(0, 0, At, B0); PG8_MMA(0, 1, At, B1); PG8_BAR; PG8_SCHED;
.Lbw2_2:
	s_waitcnt lgkmcnt(0)
	s_barrier
	s_setprio 1
	s_waitcnt lgkmcnt(0)
	v_mfma_f32_16x16x32_bf16 v[52:55], v[146:149], v[194:197], v[52:55]
	v_mfma_f32_16x16x32_bf16 v[60:63], v[170:173], v[194:197], v[60:63]
	v_mfma_f32_16x16x32_bf16 v[36:39], v[146:149], v[212:215], v[36:39]
	v_mfma_f32_16x16x32_bf16 v[44:47], v[170:173], v[212:215], v[44:47]
	v_mfma_f32_16x16x32_bf16 v[20:23], v[146:149], v[220:223], v[20:23]
	v_mfma_f32_16x16x32_bf16 v[28:31], v[170:173], v[220:223], v[28:31]
	v_mfma_f32_16x16x32_bf16 v[4:7], v[146:149], v[228:231], v[4:7]
	v_mfma_f32_16x16x32_bf16 v[12:15], v[170:173], v[228:231], v[12:15]
	v_mfma_f32_16x16x32_bf16 v[52:55], v[162:165], v[198:201], v[52:55]
	v_mfma_f32_16x16x32_bf16 v[60:63], v[174:177], v[198:201], v[60:63]
	v_mfma_f32_16x16x32_bf16 v[36:39], v[162:165], v[216:219], v[36:39]
	v_mfma_f32_16x16x32_bf16 v[44:47], v[174:177], v[216:219], v[44:47]
	v_mfma_f32_16x16x32_bf16 v[20:23], v[162:165], v[224:227], v[20:23]
	v_mfma_f32_16x16x32_bf16 v[28:31], v[174:177], v[224:227], v[28:31]
	v_mfma_f32_16x16x32_bf16 v[4:7], v[162:165], v[232:235], v[4:7]
	v_mfma_f32_16x16x32_bf16 v[12:15], v[174:177], v[232:235], v[12:15]
	s_setprio 0
	s_setprio 1
	v_mfma_f32_16x16x32_bf16 v[56:59], v[178:181], v[194:197], v[56:59]
	v_mfma_f32_16x16x32_bf16 v[64:67], v[186:189], v[194:197], v[64:67]
	v_mfma_f32_16x16x32_bf16 v[40:43], v[178:181], v[212:215], v[40:43]
	v_mfma_f32_16x16x32_bf16 v[48:51], v[186:189], v[212:215], v[48:51]
	v_mfma_f32_16x16x32_bf16 v[24:27], v[178:181], v[220:223], v[24:27]
	v_mfma_f32_16x16x32_bf16 v[32:35], v[186:189], v[220:223], v[32:35]
	v_mfma_f32_16x16x32_bf16 v[8:11], v[178:181], v[228:231], v[8:11]
	v_mfma_f32_16x16x32_bf16 v[16:19], v[186:189], v[228:231], v[16:19]
	v_mfma_f32_16x16x32_bf16 v[56:59], v[182:185], v[198:201], v[56:59]
	v_mfma_f32_16x16x32_bf16 v[64:67], v[190:193], v[198:201], v[64:67]
	v_mfma_f32_16x16x32_bf16 v[40:43], v[182:185], v[216:219], v[40:43]
	v_mfma_f32_16x16x32_bf16 v[48:51], v[190:193], v[216:219], v[48:51]
	v_mfma_f32_16x16x32_bf16 v[24:27], v[182:185], v[224:227], v[24:27]
	v_mfma_f32_16x16x32_bf16 v[32:35], v[190:193], v[224:227], v[32:35]
	v_mfma_f32_16x16x32_bf16 v[8:11], v[182:185], v[232:235], v[8:11]
	v_mfma_f32_16x16x32_bf16 v[16:19], v[190:193], v[232:235], v[16:19]
	s_setprio 0
	s_barrier
	s_add_i32 s81, 0, 0x18000
	v_add_u32_e32 v161, s81, v158
	s_add_i32 s82, 0, 0x1c000
	ds_read_b128 v[146:149], v161
	ds_read_b128 v[162:165], v161 offset:1024
	ds_read_b128 v[170:173], v161 offset:2048
	ds_read_b128 v[174:177], v161 offset:3072
	v_add_u32_e32 v161, s82, v158
	ds_read_b128 v[178:181], v161
	ds_read_b128 v[182:185], v161 offset:1024
	ds_read_b128 v[186:189], v161 offset:2048
	ds_read_b128 v[190:193], v161 offset:3072
	s_add_u32 s40, s40, 0x40000
	s_addc_u32 s41, s41, 0
	s_mov_b32 m0, s62
	v_lshl_add_u64 v[240:241], s[40:41], 0, v[134:135]
	ds_read_b128 v[194:197], v160 offset:32768
	ds_read_b128 v[198:201], v160 offset:33792
	ds_read_b128 v[212:215], v160 offset:34816
	ds_read_b128 v[216:219], v160 offset:35840
	ds_read_b128 v[220:223], v160 offset:36864
	ds_read_b128 v[224:227], v160 offset:37888
	ds_read_b128 v[228:231], v160 offset:38912
	ds_read_b128 v[232:235], v160 offset:39936
	s_cmp_lg_u32 s32, 0
	s_cbranch_scc1 .Lbt2_6
	global_load_lds_dwordx4 v[240:241], off
.Lbt2_6:
	v_lshl_add_u64 v[240:241], s[40:41], 0, v[138:139]
	s_mov_b32 m0, s63
	s_nop 0
	s_cmp_lg_u32 s32, 0
	s_cbranch_scc1 .Lbt2_7
	global_load_lds_dwordx4 v[240:241], off

; #define PG8_STAGE(bufoff, gbase, voff) do { _Pragma("unroll") for (int _i = 0; _i < 2; ++_i) \
;         __builtin_amdgcn_global_load_lds((const unsigned*)((const char*)(gbase) + (voff)[_i]), (PG8_LAS unsigned*)(lds + (bufoff) + ldsw + _i * 8192), 16, 0, 0); } while (0)
; #define PG8_LDA(dst, b, h) do { _Pragma("unroll") for (int m = 0; m < 4; ++m) _Pragma("unroll") for (int k = 0; k < 2; ++k) dst[m][k] = *(const PG8_LAS bf16x8*)(lds + PG8_SA(b, h) + aoff + m * 2048 + k * 1024); } while (0)
; #define PG8_LDB(dst, b, h) do { _Pragma("unroll") for (int n = 0; n < 2; ++n) _Pragma("unroll") for (int k = 0; k < 2; ++k) dst[n][k] = *(const PG8_LAS bf16x8*)(lds + PG8_SB(b, h) + boff + n * 2048 + k * 1024); } while (0)
; #define PG8_MMA(ai, bj, At, Bt) do { __builtin_amdgcn_s_setprio(1); _Pragma("unroll") for (int m = 0; m < 4; ++m) _Pragma("unroll") for (int n = 0; n < 2; ++n) _Pragma("unroll") for (int k = 0; k < 2; ++k) \
;         acc[ai][bj][m][n] = __builtin_amdgcn_mfma_f32_16x16x32_bf16(Bt[n][k], At[m][k], acc[ai][bj][m][n], 0, 0, 0); __builtin_amdgcn_s_setprio(0); } while (0)
; #define PG8_WAIT_V(n) asm volatile("s_waitcnt vmcnt(" #n ")" ::: "memory")
; #define PG8_WAIT_L(n) asm volatile("s_waitcnt lgkmcnt(" #n ")" ::: "memory")
; #define PG8_BAR __builtin_amdgcn_s_barrier()
; #define PG8_SCHED __builtin_amdgcn_sched_barrier(0)
; template <class Epi, class Sched, bool ALIGN_EPI = false, bool SP2 = false>
; __device__ __forceinline__ void gemm_phase(PG8_LAS unsigned char* lds, const Gemm g, const Sched& S, const Epi& E, const int tid) {
;     ...
;             PG8_WAIT_V(8); PG8_WAIT_L(0); PG8_BAR; PG8_MMA(1, 0, At, B0); PG8_MMA(1, 1, At, B1); PG8_BAR; PG8_SCHED;
;             PG8_LDB(B0, 1, 0); PG8_LDB(B1, 1, 1); PG8_SCHED; PG8_LDA(At, 1, 0); PG8_STAGE(PG8_SA(0, 1), a2 + hstep, voffA);
;             PG8_WAIT_V(8); PG8_WAIT_L(0); PG8_BAR; PG8_MMA(0, 0, At, B0); PG8_MMA(0, 1, At, B1); PG8_BAR; PG8_SCHED;
;             PG8_LDA(At, 1, 1); PG8_STAGE(PG8_SB(1, 0), b3, voffB); PG8_STAGE(PG8_SB(1, 1), b3 + hstepB, voffB); PG8_STAGE(PG8_SA(1, 0), a3, voffA);
;             PG8_WAIT_V(8); PG8_WAIT_L(0); PG8_BAR; PG8_MMA(1, 0, At, B0); PG8_MMA(1, 1, At, B1); PG8_BAR; PG8_SCHED;
.Lbw2_0:
	s_waitcnt lgkmcnt(0)
	s_barrier
	s_setprio 1
	s_waitcnt lgkmcnt(0)
	v_mfma_f32_16x16x32_bf16 v[120:123], v[146:149], v[194:197], v[120:123]
	v_mfma_f32_16x16x32_bf16 v[128:131], v[170:173], v[194:197], v[128:131]
	v_mfma_f32_16x16x32_bf16 v[100:103], v[146:149], v[212:215], v[100:103]
	v_mfma_f32_16x16x32_bf16 v[108:111], v[170:173], v[212:215], v[108:111]
	v_mfma_f32_16x16x32_bf16 v[84:87], v[146:149], v[220:223], v[84:87]
	v_mfma_f32_16x16x32_bf16 v[92:95], v[170:173], v[220:223], v[92:95]
	v_mfma_f32_16x16x32_bf16 v[68:71], v[146:149], v[228:231], v[68:71]
	v_mfma_f32_16x16x32_bf16 v[76:79], v[170:173], v[228:231], v[76:79]
	v_mfma_f32_16x16x32_bf16 v[120:123], v[162:165], v[198:201], v[120:123]
	v_mfma_f32_16x16x32_bf16 v[128:131], v[174:177], v[198:201], v[128:131]
	v_mfma_f32_16x16x32_bf16 v[100:103], v[162:165], v[216:219], v[100:103]
	v_mfma_f32_16x16x32_bf16 v[108:111], v[174:177], v[216:219], v[108:111]
	v_mfma_f32_16x16x32_bf16 v[84:87], v[162:165], v[224:227], v[84:87]
	v_mfma_f32_16x16x32_bf16 v[92:95], v[174:177], v[224:227], v[92:95]
	v_mfma_f32_16x16x32_bf16 v[68:71], v[162:165], v[232:235], v[68:71]
	v_mfma_f32_16x16x32_bf16 v[76:79], v[174:177], v[232:235], v[76:79]
	s_setprio 0
	s_setprio 1
	v_mfma_f32_16x16x32_bf16 v[116:119], v[178:181], v[194:197], v[116:119]
	v_mfma_f32_16x16x32_bf16 v[124:127], v[186:189], v[194:197], v[124:127]
	v_mfma_f32_16x16x32_bf16 v[104:107], v[178:181], v[212:215], v[104:107]
	v_mfma_f32_16x16x32_bf16 v[112:115], v[186:189], v[212:215], v[112:115]
	v_mfma_f32_16x16x32_bf16 v[88:91], v[178:181], v[220:223], v[88:91]
	v_mfma_f32_16x16x32_bf16 v[96:99], v[186:189], v[220:223], v[96:99]
	v_mfma_f32_16x16x32_bf16 v[72:75], v[178:181], v[228:231], v[72:75]
	v_mfma_f32_16x16x32_bf16 v[80:83], v[186:189], v[228:231], v[80:83]
	v_mfma_f32_16x16x32_bf16 v[116:119], v[182:185], v[198:201], v[116:119]
	v_mfma_f32_16x16x32_bf16 v[124:127], v[190:193], v[198:201], v[124:127]
	v_mfma_f32_16x16x32_bf16 v[104:107], v[182:185], v[216:219], v[104:107]
	v_mfma_f32_16x16x32_bf16 v[112:115], v[190:193], v[216:219], v[112:115]
	v_mfma_f32_16x16x32_bf16 v[88:91], v[182:185], v[224:227], v[88:91]
	v_mfma_f32_16x16x32_bf16 v[96:99], v[190:193], v[224:227], v[96:99]
	v_mfma_f32_16x16x32_bf16 v[72:75], v[182:185], v[232:235], v[72:75]
	v_mfma_f32_16x16x32_bf16 v[80:83], v[190:193], v[232:235], v[80:83]
	s_setprio 0
	s_barrier
	s_add_i32 s40, s81, s43
	v_lshl_add_u64 v[150:151], v[150:151], 0, s[52:53]
	s_mov_b32 m0, s40
	ds_read_b128 v[194:197], v160 offset:49152
	ds_read_b128 v[198:201], v160 offset:50176
	ds_read_b128 v[212:215], v160 offset:51200
	ds_read_b128 v[216:219], v160 offset:52224
	ds_read_b128 v[220:223], v160 offset:53248
	ds_read_b128 v[224:227], v160 offset:54272
	ds_read_b128 v[228:231], v160 offset:55296
	ds_read_b128 v[232:235], v160 offset:56320
	s_cmp_lg_u32 s32, 0
	s_cbranch_scc1 .Lbt2_8
	global_load_lds_dwordx4 v[150:151], off
.Lbt2_8:
	s_add_i32 m0, s40, 0x2000
	s_add_u32 s36, s36, 0x10080
	v_lshl_add_u64 v[150:151], v[166:167], 0, s[52:53]
	s_addc_u32 s37, s37, 0
	s_add_i32 s40, s82, s43
	s_cmp_lg_u32 s32, 0
	s_cbranch_scc1 .Lbt2_9
	global_load_lds_dwordx4 v[150:151], off
.Lbt2_9:
	v_lshl_add_u64 v[150:151], s[36:37], 0, v[136:137]
	s_mov_b32 m0, s40
	s_nop 0
	s_cmp_lg_u32 s32, 0
	s_cbranch_scc1 .Lbt2_10
	global_load_lds_dwordx4 v[150:151], off
.Lbt2_10:
	v_lshl_add_u64 v[150:151], s[36:37], 0, v[140:141]
	s_add_i32 m0, s40, 0x2000
	s_nop 0
	s_cmp_lg_u32 s32, 0
	s_cbranch_scc1 .Lbt2_11
	global_load_lds_dwordx4 v[150:151], off
.Lbt2_11:
	v_lshl_add_u64 v[150:151], v[236:237], 0, s[52:53]
	s_mov_b32 m0, s64
	s_nop 0
	s_cmp_lg_u32 s32, 0
	s_cbranch_scc1 .Lbt2_12
	global_load_lds_dwordx4 v[150:151], off
.Lbt2_12:
	v_lshl_add_u64 v[150:151], v[238:239], 0, s[52:53]
	s_mov_b32 m0, s65
	s_nop 0
	s_cmp_lg_u32 s32, 0
	s_cbranch_scc1 .Lbt2_13
	global_load_lds_dwordx4 v[150:151], off
.Lbt2_13:
	s_waitcnt vmcnt(8)
	s_waitcnt lgkmcnt(0)
	s_barrier
	s_setprio 1
	s_waitcnt lgkmcnt(0)
	v_mfma_f32_16x16x32_bf16 v[52:55], v[146:149], v[194:197], v[52:55]
	v_mfma_f32_16x16x32_bf16 v[60:63], v[170:173], v[194:197], v[60:63]
	v_mfma_f32_16x16x32_bf16 v[36:39], v[146:149], v[212:215], v[36:39]
	v_mfma_f32_16x16x32_bf16 v[44:47], v[170:173], v[212:215], v[44:47]
	v_mfma_f32_16x16x32_bf16 v[20:23], v[146:149], v[220:223], v[20:23]
	v_mfma_f32_16x16x32_bf16 v[28:31], v[170:173], v[220:223], v[28:31]
	v_mfma_f32_16x16x32_bf16 v[4:7], v[146:149], v[228:231], v[4:7]
	v_mfma_f32_16x16x32_bf16 v[12:15], v[170:173], v[228:231], v[12:15]
	v_mfma_f32_16x16x32_bf16 v[52:55], v[162:165], v[198:201], v[52:55]
	v_mfma_f32_16x16x32_bf16 v[60:63], v[174:177], v[198:201], v[60:63]
	v_mfma_f32_16x16x32_bf16 v[36:39], v[162:165], v[216:219], v[36:39]
	v_mfma_f32_16x16x32_bf16 v[44:47], v[174:177], v[216:219], v[44:47]
	v_mfma_f32_16x16x32_bf16 v[20:23], v[162:165], v[224:227], v[20:23]
	v_mfma_f32_16x16x32_bf16 v[28:31], v[174:177], v[224:227], v[28:31]
	v_mfma_f32_16x16x32_bf16 v[4:7], v[162:165], v[232:235], v[4:7]
	v_mfma_f32_16x16x32_bf16 v[12:15], v[174:177], v[232:235], v[12:15]
	s_setprio 0
	s_setprio 1
	v_mfma_f32_16x16x32_bf16 v[56:59], v[178:181], v[194:197], v[56:59]
	v_mfma_f32_16x16x32_bf16 v[64:67], v[186:189], v[194:197], v[64:67]
	v_mfma_f32_16x16x32_bf16 v[40:43], v[178:181], v[212:215], v[40:43]
	v_mfma_f32_16x16x32_bf16 v[48:51], v[186:189], v[212:215], v[48:51]
	v_mfma_f32_16x16x32_bf16 v[24:27], v[178:181], v[220:223], v[24:27]
	v_mfma_f32_16x16x32_bf16 v[32:35], v[186:189], v[220:223], v[32:35]
	v_mfma_f32_16x16x32_bf16 v[8:11], v[178:181], v[228:231], v[8:11]
	v_mfma_f32_16x16x32_bf16 v[16:19], v[186:189], v[228:231], v[16:19]
	v_mfma_f32_16x16x32_bf16 v[56:59], v[182:185], v[198:201], v[56:59]
	v_mfma_f32_16x16x32_bf16 v[64:67], v[190:193], v[198:201], v[64:67]
	v_mfma_f32_16x16x32_bf16 v[40:43], v[182:185], v[216:219], v[40:43]
	v_mfma_f32_16x16x32_bf16 v[48:51], v[190:193], v[216:219], v[48:51]
	v_mfma_f32_16x16x32_bf16 v[24:27], v[182:185], v[224:227], v[24:27]
	v_mfma_f32_16x16x32_bf16 v[32:35], v[190:193], v[224:227], v[32:35]
	v_mfma_f32_16x16x32_bf16 v[8:11], v[182:185], v[232:235], v[8:11]
	v_mfma_f32_16x16x32_bf16 v[16:19], v[190:193], v[232:235], v[16:19]
	s_setprio 0
	s_barrier
	s_add_i32 s80, s80, 2
	s_add_u32 s38, s38, 0x100
	s_addc_u32 s39, s39, 0
	s_add_u32 s78, s78, 0x100
	s_addc_u32 s79, s79, 0
	s_cmp_gt_u32 s80, 13
	s_cbranch_scc0 .LBB0_979
	s_and_b64 vcc, exec, s[14:15]
	s_cbranch_vccz .LBB0_982
	s_barrier

; #define PG8_STAGE(bufoff, gbase, voff) do { _Pragma("unroll") for (int _i = 0; _i < 2; ++_i) \
;         __builtin_amdgcn_global_load_lds((const unsigned*)((const char*)(gbase) + (voff)[_i]), (PG8_LAS unsigned*)(lds + (bufoff) + ldsw + _i * 8192), 16, 0, 0); } while (0)
; #define PG8_LDA(dst, b, h) do { _Pragma("unroll") for (int m = 0; m < 4; ++m) _Pragma("unroll") for (int k = 0; k < 2; ++k) dst[m][k] = *(const PG8_LAS bf16x8*)(lds + PG8_SA(b, h) + aoff + m * 2048 + k * 1024); } while (0)
; #define PG8_LDB(dst, b, h) do { _Pragma("unroll") for (int n = 0; n < 2; ++n) _Pragma("unroll") for (int k = 0; k < 2; ++k) dst[n][k] = *(const PG8_LAS bf16x8*)(lds + PG8_SB(b, h) + boff + n * 2048 + k * 1024); } while (0)
; #define PG8_WAIT_V(n) asm volatile("s_waitcnt vmcnt(" #n ")" ::: "memory")
; #define PG8_WAIT_L(n) asm volatile("s_waitcnt lgkmcnt(" #n ")" ::: "memory")
; #define PG8_BAR __builtin_amdgcn_s_barrier()
; #define PG8_SCHED __builtin_amdgcn_sched_barrier(0)
; template <class Epi, class Sched, bool ALIGN_EPI = false, bool SP2 = false>
; __device__ __forceinline__ void gemm_phase(PG8_LAS unsigned char* lds, const Gemm g, const Sched& S, const Epi& E, const int tid) {
;     ...
;         const char* nA = has_next ? (const char*)g.A + (size_t)nxt.pm * tstep : cA; const char* nB = has_next ? (const char*)g.Bt + (size_t)nxt.pn * tstep : cB;
;         for (int t = 0; t < nt; t += 2) {
;             const bool last = (t == nt - 2);
;             const char* a1 = cA + (size_t)(t + 1) * kstep;
;             const char* a2 = last ? nA : cA + (size_t)(t + 2) * kstep; const char* b2 = last ? nB : cB + (size_t)(t + 2) * kstep;
;             const char* a3 = a2 + kstep; const char* b3 = b2 + kstep;
;             if (last && has_next) S.a_ready(nxt);
;             if constexpr (SP2) {
;             PG8_LDB(B0, 0, 0); PG8_LDB(B1, 0, 1); PG8_SCHED; PG8_LDA(At, 0, 0); PG8_STAGE(PG8_SA(1, 1), a1 + hstep, voffA);
;             PG8_WAIT_V(8); PG8_WAIT_L(0); PG8_BAR; PG8_MMA(0, 0, At, B0); PG8_MMA(0, 1, At, B1); PG8_BAR; PG8_SCHED;
;             PG8_LDA(At, 0, 1); PG8_STAGE(PG8_SB(0, 0), b2, voffB); PG8_STAGE(PG8_SB(0, 1), b2 + hstepB, voffB); PG8_STAGE(PG8_SA(0, 0), a2, voffA);
;             PG8_WAIT_V(8); PG8_WAIT_L(0); PG8_BAR; PG8_MMA(1, 0, At, B0); PG8_MMA(1, 1, At, B1); PG8_BAR; PG8_SCHED;
.LBB0_1108:
	s_add_u32 s42, s40, 0xfffc0080
	s_addc_u32 s43, s41, -1
	s_add_i32 s84, 0, 0x10000
	s_cmp_eq_u32 s83, 12
	s_cselect_b32 s55, s23, s43
	s_cselect_b32 s54, s79, s42
	v_add_u32_e32 v163, s84, v157
	s_cselect_b32 s43, s21, s82
	s_cselect_b32 s42, s80, s81
	s_cmp_eq_u32 s83, 12
	s_cselect_b32 s32, 1, 0
	s_andn2_b32 s32, s32, s28
	s_add_i32 s86, 0, 0x14000
	ds_read_b128 v[146:149], v163
	ds_read_b128 v[164:167], v163 offset:1024
	ds_read_b128 v[170:173], v163 offset:2048
	ds_read_b128 v[174:177], v163 offset:3072
	v_add_u32_e32 v163, s86, v157
	ds_read_b128 v[178:181], v163
	ds_read_b128 v[182:185], v163 offset:1024
	ds_read_b128 v[186:189], v163 offset:2048
	ds_read_b128 v[190:193], v163 offset:3072
	v_lshl_add_u64 v[236:237], s[40:41], 0, v[142:143]
	s_add_i32 m0, s37, 0xc000
	ds_read_b128 v[194:197], v162
	ds_read_b128 v[198:201], v162 offset:1024
	ds_read_b128 v[212:215], v162 offset:2048
	ds_read_b128 v[216:219], v162 offset:3072
	ds_read_b128 v[220:223], v162 offset:4096
	ds_read_b128 v[224:227], v162 offset:5120
	ds_read_b128 v[228:231], v162 offset:6144
	ds_read_b128 v[232:235], v162 offset:7168
	global_load_lds_dwordx4 v[236:237], off
	v_lshl_add_u64 v[236:237], s[40:41], 0, v[144:145]
	s_add_i32 m0, s37, 0xe000
	s_nop 0
	global_load_lds_dwordx4 v[236:237], off
	s_waitcnt vmcnt(8)
	s_waitcnt lgkmcnt(0)
	s_barrier
	s_setprio 1
	s_waitcnt lgkmcnt(0)
	v_mfma_f32_16x16x32_bf16 v[128:131], v[146:149], v[194:197], v[128:131]
	v_mfma_f32_16x16x32_bf16 v[124:127], v[170:173], v[194:197], v[124:127]
	v_mfma_f32_16x16x32_bf16 v[112:115], v[146:149], v[212:215], v[112:115]
	v_mfma_f32_16x16x32_bf16 v[108:111], v[170:173], v[212:215], v[108:111]
	v_mfma_f32_16x16x32_bf16 v[96:99], v[146:149], v[220:223], v[96:99]
	v_mfma_f32_16x16x32_bf16 v[92:95], v[170:173], v[220:223], v[92:95]
	v_mfma_f32_16x16x32_bf16 v[80:83], v[146:149], v[228:231], v[80:83]
	v_mfma_f32_16x16x32_bf16 v[76:79], v[170:173], v[228:231], v[76:79]
	v_mfma_f32_16x16x32_bf16 v[128:131], v[164:167], v[198:201], v[128:131]
	v_mfma_f32_16x16x32_bf16 v[124:127], v[174:177], v[198:201], v[124:127]
	v_mfma_f32_16x16x32_bf16 v[112:115], v[164:167], v[216:219], v[112:115]
	v_mfma_f32_16x16x32_bf16 v[108:111], v[174:177], v[216:219], v[108:111]
	v_mfma_f32_16x16x32_bf16 v[96:99], v[164:167], v[224:227], v[96:99]
	v_mfma_f32_16x16x32_bf16 v[92:95], v[174:177], v[224:227], v[92:95]
	v_mfma_f32_16x16x32_bf16 v[80:83], v[164:167], v[232:235], v[80:83]
	v_mfma_f32_16x16x32_bf16 v[76:79], v[174:177], v[232:235], v[76:79]
	s_setprio 0
	s_setprio 1
	v_mfma_f32_16x16x32_bf16 v[120:123], v[178:181], v[194:197], v[120:123]
	v_mfma_f32_16x16x32_bf16 v[116:119], v[186:189], v[194:197], v[116:119]
	v_mfma_f32_16x16x32_bf16 v[104:107], v[178:181], v[212:215], v[104:107]
	v_mfma_f32_16x16x32_bf16 v[100:103], v[186:189], v[212:215], v[100:103]
	v_mfma_f32_16x16x32_bf16 v[88:91], v[178:181], v[220:223], v[88:91]
	v_mfma_f32_16x16x32_bf16 v[84:87], v[186:189], v[220:223], v[84:87]
	v_mfma_f32_16x16x32_bf16 v[72:75], v[178:181], v[228:231], v[72:75]
	v_mfma_f32_16x16x32_bf16 v[68:71], v[186:189], v[228:231], v[68:71]
	v_mfma_f32_16x16x32_bf16 v[120:123], v[182:185], v[198:201], v[120:123]
	v_mfma_f32_16x16x32_bf16 v[116:119], v[190:193], v[198:201], v[116:119]
	v_mfma_f32_16x16x32_bf16 v[104:107], v[182:185], v[216:219], v[104:107]
	v_mfma_f32_16x16x32_bf16 v[100:103], v[190:193], v[216:219], v[100:103]
	v_mfma_f32_16x16x32_bf16 v[88:91], v[182:185], v[224:227], v[88:91]
	v_mfma_f32_16x16x32_bf16 v[84:87], v[190:193], v[224:227], v[84:87]
	v_mfma_f32_16x16x32_bf16 v[72:75], v[182:185], v[232:235], v[72:75]
	v_mfma_f32_16x16x32_bf16 v[68:71], v[190:193], v[232:235], v[68:71]
	s_setprio 0
	s_barrier
	s_add_i32 s84, s84, s63
	v_lshl_add_u64 v[236:237], s[42:43], 0, v[138:139]
	s_mov_b32 m0, s84
	ds_read_b128 v[194:197], v162 offset:16384
	ds_read_b128 v[198:201], v162 offset:17408
	ds_read_b128 v[212:215], v162 offset:18432
	ds_read_b128 v[216:219], v162 offset:19456
	ds_read_b128 v[220:223], v162 offset:20480
	ds_read_b128 v[224:227], v162 offset:21504
	ds_read_b128 v[228:231], v162 offset:22528
	ds_read_b128 v[232:235], v162 offset:23552
	s_cmp_lg_u32 s32, 0
	s_cbranch_scc1 .Lbt3_0
	global_load_lds_dwordx4 v[236:237], off
.Lbt3_0:
	s_add_i32 m0, s84, 0x2000
	s_add_u32 s84, s42, 0x10000
	v_lshl_add_u64 v[238:239], s[42:43], 0, v[134:135]
	s_addc_u32 s85, s43, 0
	s_add_i32 s86, s86, s63
	s_cmp_lg_u32 s32, 0
	s_cbranch_scc1 .Lbt3_1
	global_load_lds_dwordx4 v[238:239], off
.Lbt3_1:
	v_lshl_add_u64 v[240:241], s[84:85], 0, v[138:139]
	s_mov_b32 m0, s86
	v_lshl_add_u64 v[242:243], s[54:55], 0, v[136:137]
	s_cmp_lg_u32 s32, 0
	s_cbranch_scc1 .Lbt3_2
	global_load_lds_dwordx4 v[240:241], off
.Lbt3_2:
	v_lshl_add_u64 v[240:241], s[84:85], 0, v[134:135]
	s_add_i32 m0, s86, 0x2000
	s_nop 0
	s_cmp_lg_u32 s32, 0
	s_cbranch_scc1 .Lbt3_3
	global_load_lds_dwordx4 v[240:241], off
.Lbt3_3:
	v_lshl_add_u64 v[240:241], s[54:55], 0, v[140:141]
	s_mov_b32 m0, s37
	s_nop 0
	s_cmp_lg_u32 s32, 0
	s_cbranch_scc1 .Lbt3_4
	global_load_lds_dwordx4 v[240:241], off
.Lbt3_4:
	s_mov_b32 m0, s39
	s_nop 0
	s_cmp_lg_u32 s32, 0
	s_cbranch_scc1 .Lbt3_5
	global_load_lds_dwordx4 v[242:243], off

; #define PG8_STAGE(bufoff, gbase, voff) do { _Pragma("unroll") for (int _i = 0; _i < 2; ++_i) \
;         __builtin_amdgcn_global_load_lds((const unsigned*)((const char*)(gbase) + (voff)[_i]), (PG8_LAS unsigned*)(lds + (bufoff) + ldsw + _i * 8192), 16, 0, 0); } while (0)
; #define PG8_LDA(dst, b, h) do { _Pragma("unroll") for (int m = 0; m < 4; ++m) _Pragma("unroll") for (int k = 0; k < 2; ++k) dst[m][k] = *(const PG8_LAS bf16x8*)(lds + PG8_SA(b, h) + aoff + m * 2048 + k * 1024); } while (0)
; #define PG8_LDB(dst, b, h) do { _Pragma("unroll") for (int n = 0; n < 2; ++n) _Pragma("unroll") for (int k = 0; k < 2; ++k) dst[n][k] = *(const PG8_LAS bf16x8*)(lds + PG8_SB(b, h) + boff + n * 2048 + k * 1024); } while (0)
; #define PG8_MMA(ai, bj, At, Bt) do { __builtin_amdgcn_s_setprio(1); _Pragma("unroll") for (int m = 0; m < 4; ++m) _Pragma("unroll") for (int n = 0; n < 2; ++n) _Pragma("unroll") for (int k = 0; k < 2; ++k) \
;         acc[ai][bj][m][n] = __builtin_amdgcn_mfma_f32_16x16x32_bf16(Bt[n][k], At[m][k], acc[ai][bj][m][n], 0, 0, 0); __builtin_amdgcn_s_setprio(0); } while (0)
; #define PG8_WAIT_V(n) asm volatile("s_waitcnt vmcnt(" #n ")" ::: "memory")
; #define PG8_WAIT_L(n) asm volatile("s_waitcnt lgkmcnt(" #n ")" ::: "memory")
; #define PG8_BAR __builtin_amdgcn_s_barrier()
; #define PG8_SCHED __builtin_amdgcn_sched_barrier(0)
; template <class Epi, class Sched, bool ALIGN_EPI = false, bool SP2 = false>
; __device__ __forceinline__ void gemm_phase(PG8_LAS unsigned char* lds, const Gemm g, const Sched& S, const Epi& E, const int tid) {
;     ...
;             PG8_WAIT_V(8); PG8_WAIT_L(0); PG8_BAR; PG8_MMA(1, 0, At, B0); PG8_MMA(1, 1, At, B1); PG8_BAR; PG8_SCHED;
;             PG8_LDB(B0, 1, 0); PG8_LDB(B1, 1, 1); PG8_SCHED; PG8_LDA(At, 1, 0); PG8_STAGE(PG8_SA(0, 1), a2 + hstep, voffA);
;             PG8_WAIT_V(8); PG8_WAIT_L(0); PG8_BAR; PG8_MMA(0, 0, At, B0); PG8_MMA(0, 1, At, B1); PG8_BAR; PG8_SCHED;
.Lbw3_2:
	s_waitcnt lgkmcnt(0)
	s_barrier
	s_setprio 1
	s_waitcnt lgkmcnt(0)
	v_mfma_f32_16x16x32_bf16 v[64:67], v[146:149], v[194:197], v[64:67]
	v_mfma_f32_16x16x32_bf16 v[60:63], v[170:173], v[194:197], v[60:63]
	v_mfma_f32_16x16x32_bf16 v[48:51], v[146:149], v[212:215], v[48:51]
	v_mfma_f32_16x16x32_bf16 v[44:47], v[170:173], v[212:215], v[44:47]
	v_mfma_f32_16x16x32_bf16 v[32:35], v[146:149], v[220:223], v[32:35]
	v_mfma_f32_16x16x32_bf16 v[28:31], v[170:173], v[220:223], v[28:31]
	v_mfma_f32_16x16x32_bf16 v[16:19], v[146:149], v[228:231], v[16:19]
	v_mfma_f32_16x16x32_bf16 v[12:15], v[170:173], v[228:231], v[12:15]
	v_mfma_f32_16x16x32_bf16 v[64:67], v[164:167], v[198:201], v[64:67]
	v_mfma_f32_16x16x32_bf16 v[60:63], v[174:177], v[198:201], v[60:63]
	v_mfma_f32_16x16x32_bf16 v[48:51], v[164:167], v[216:219], v[48:51]
	v_mfma_f32_16x16x32_bf16 v[44:47], v[174:177], v[216:219], v[44:47]
	v_mfma_f32_16x16x32_bf16 v[32:35], v[164:167], v[224:227], v[32:35]
	v_mfma_f32_16x16x32_bf16 v[28:31], v[174:177], v[224:227], v[28:31]
	v_mfma_f32_16x16x32_bf16 v[16:19], v[164:167], v[232:235], v[16:19]
	v_mfma_f32_16x16x32_bf16 v[12:15], v[174:177], v[232:235], v[12:15]
	s_setprio 0
	s_setprio 1
	v_mfma_f32_16x16x32_bf16 v[56:59], v[178:181], v[194:197], v[56:59]
	v_mfma_f32_16x16x32_bf16 v[52:55], v[186:189], v[194:197], v[52:55]
	v_mfma_f32_16x16x32_bf16 v[40:43], v[178:181], v[212:215], v[40:43]
	v_mfma_f32_16x16x32_bf16 v[36:39], v[186:189], v[212:215], v[36:39]
	v_mfma_f32_16x16x32_bf16 v[24:27], v[178:181], v[220:223], v[24:27]
	v_mfma_f32_16x16x32_bf16 v[20:23], v[186:189], v[220:223], v[20:23]
	v_mfma_f32_16x16x32_bf16 v[8:11], v[178:181], v[228:231], v[8:11]
	v_mfma_f32_16x16x32_bf16 v[4:7], v[186:189], v[228:231], v[4:7]
	v_mfma_f32_16x16x32_bf16 v[56:59], v[182:185], v[198:201], v[56:59]
	v_mfma_f32_16x16x32_bf16 v[52:55], v[190:193], v[198:201], v[52:55]
	v_mfma_f32_16x16x32_bf16 v[40:43], v[182:185], v[216:219], v[40:43]
	v_mfma_f32_16x16x32_bf16 v[36:39], v[190:193], v[216:219], v[36:39]
	v_mfma_f32_16x16x32_bf16 v[24:27], v[182:185], v[224:227], v[24:27]
	v_mfma_f32_16x16x32_bf16 v[20:23], v[190:193], v[224:227], v[20:23]
	v_mfma_f32_16x16x32_bf16 v[8:11], v[182:185], v[232:235], v[8:11]
	v_mfma_f32_16x16x32_bf16 v[4:7], v[190:193], v[232:235], v[4:7]
	s_setprio 0
	s_barrier
	s_add_i32 s84, 0, 0x18000
	v_add_u32_e32 v163, s84, v157
	s_add_i32 s85, 0, 0x1c000
	ds_read_b128 v[146:149], v163
	ds_read_b128 v[164:167], v163 offset:1024
	ds_read_b128 v[170:173], v163 offset:2048
	ds_read_b128 v[174:177], v163 offset:3072
	v_add_u32_e32 v163, s85, v157
	ds_read_b128 v[178:181], v163
	ds_read_b128 v[182:185], v163 offset:1024
	ds_read_b128 v[186:189], v163 offset:2048
	ds_read_b128 v[190:193], v163 offset:3072
	s_add_u32 s54, s54, 0x40000
	s_addc_u32 s55, s55, 0
	s_mov_b32 m0, s65
	v_lshl_add_u64 v[244:245], s[54:55], 0, v[140:141]
	ds_read_b128 v[194:197], v162 offset:32768
	ds_read_b128 v[198:201], v162 offset:33792
	ds_read_b128 v[212:215], v162 offset:34816
	ds_read_b128 v[216:219], v162 offset:35840
	ds_read_b128 v[220:223], v162 offset:36864
	ds_read_b128 v[224:227], v162 offset:37888
	ds_read_b128 v[228:231], v162 offset:38912
	ds_read_b128 v[232:235], v162 offset:39936
	s_cmp_lg_u32 s32, 0
	s_cbranch_scc1 .Lbt3_6
	global_load_lds_dwordx4 v[244:245], off
.Lbt3_6:
	v_lshl_add_u64 v[244:245], s[54:55], 0, v[136:137]
	s_mov_b32 m0, s66
	s_nop 0
	s_cmp_lg_u32 s32, 0
	s_cbranch_scc1 .Lbt3_7
	global_load_lds_dwordx4 v[244:245], off

; #define PG8_STAGE(bufoff, gbase, voff) do { _Pragma("unroll") for (int _i = 0; _i < 2; ++_i) \
;         __builtin_amdgcn_global_load_lds((const unsigned*)((const char*)(gbase) + (voff)[_i]), (PG8_LAS unsigned*)(lds + (bufoff) + ldsw + _i * 8192), 16, 0, 0); } while (0)
; #define PG8_LDA(dst, b, h) do { _Pragma("unroll") for (int m = 0; m < 4; ++m) _Pragma("unroll") for (int k = 0; k < 2; ++k) dst[m][k] = *(const PG8_LAS bf16x8*)(lds + PG8_SA(b, h) + aoff + m * 2048 + k * 1024); } while (0)
; #define PG8_LDB(dst, b, h) do { _Pragma("unroll") for (int n = 0; n < 2; ++n) _Pragma("unroll") for (int k = 0; k < 2; ++k) dst[n][k] = *(const PG8_LAS bf16x8*)(lds + PG8_SB(b, h) + boff + n * 2048 + k * 1024); } while (0)
; #define PG8_MMA(ai, bj, At, Bt) do { __builtin_amdgcn_s_setprio(1); _Pragma("unroll") for (int m = 0; m < 4; ++m) _Pragma("unroll") for (int n = 0; n < 2; ++n) _Pragma("unroll") for (int k = 0; k < 2; ++k) \
;         acc[ai][bj][m][n] = __builtin_amdgcn_mfma_f32_16x16x32_bf16(Bt[n][k], At[m][k], acc[ai][bj][m][n], 0, 0, 0); __builtin_amdgcn_s_setprio(0); } while (0)
; #define PG8_WAIT_V(n) asm volatile("s_waitcnt vmcnt(" #n ")" ::: "memory")
; #define PG8_WAIT_L(n) asm volatile("s_waitcnt lgkmcnt(" #n ")" ::: "memory")
; #define PG8_BAR __builtin_amdgcn_s_barrier()
; #define PG8_SCHED __builtin_amdgcn_sched_barrier(0)
; template <class Epi, class Sched, bool ALIGN_EPI = false, bool SP2 = false>
; __device__ __forceinline__ void gemm_phase(PG8_LAS unsigned char* lds, const Gemm g, const Sched& S, const Epi& E, const int tid) {
;     ...
;             PG8_WAIT_V(8); PG8_WAIT_L(0); PG8_BAR; PG8_MMA(1, 0, At, B0); PG8_MMA(1, 1, At, B1); PG8_BAR; PG8_SCHED;
;             PG8_LDB(B0, 1, 0); PG8_LDB(B1, 1, 1); PG8_SCHED; PG8_LDA(At, 1, 0); PG8_STAGE(PG8_SA(0, 1), a2 + hstep, voffA);
;             PG8_WAIT_V(8); PG8_WAIT_L(0); PG8_BAR; PG8_MMA(0, 0, At, B0); PG8_MMA(0, 1, At, B1); PG8_BAR; PG8_SCHED;
;             PG8_LDA(At, 1, 1); PG8_STAGE(PG8_SB(1, 0), b3, voffB); PG8_STAGE(PG8_SB(1, 1), b3 + hstepB, voffB); PG8_STAGE(PG8_SA(1, 0), a3, voffA);
;             PG8_WAIT_V(8); PG8_WAIT_L(0); PG8_BAR; PG8_MMA(1, 0, At, B0); PG8_MMA(1, 1, At, B1); PG8_BAR; PG8_SCHED;
.Lbw3_0:
	s_waitcnt lgkmcnt(0)
	s_barrier
	s_setprio 1
	s_waitcnt lgkmcnt(0)
	v_mfma_f32_16x16x32_bf16 v[128:131], v[146:149], v[194:197], v[128:131]
	v_mfma_f32_16x16x32_bf16 v[124:127], v[170:173], v[194:197], v[124:127]
	v_mfma_f32_16x16x32_bf16 v[112:115], v[146:149], v[212:215], v[112:115]
	v_mfma_f32_16x16x32_bf16 v[108:111], v[170:173], v[212:215], v[108:111]
	v_mfma_f32_16x16x32_bf16 v[96:99], v[146:149], v[220:223], v[96:99]
	v_mfma_f32_16x16x32_bf16 v[92:95], v[170:173], v[220:223], v[92:95]
	v_mfma_f32_16x16x32_bf16 v[80:83], v[146:149], v[228:231], v[80:83]
	v_mfma_f32_16x16x32_bf16 v[76:79], v[170:173], v[228:231], v[76:79]
	v_mfma_f32_16x16x32_bf16 v[128:131], v[164:167], v[198:201], v[128:131]
	v_mfma_f32_16x16x32_bf16 v[124:127], v[174:177], v[198:201], v[124:127]
	v_mfma_f32_16x16x32_bf16 v[112:115], v[164:167], v[216:219], v[112:115]
	v_mfma_f32_16x16x32_bf16 v[108:111], v[174:177], v[216:219], v[108:111]
	v_mfma_f32_16x16x32_bf16 v[96:99], v[164:167], v[224:227], v[96:99]
	v_mfma_f32_16x16x32_bf16 v[92:95], v[174:177], v[224:227], v[92:95]
	v_mfma_f32_16x16x32_bf16 v[80:83], v[164:167], v[232:235], v[80:83]
	v_mfma_f32_16x16x32_bf16 v[76:79], v[174:177], v[232:235], v[76:79]
	s_setprio 0
	s_setprio 1
	v_mfma_f32_16x16x32_bf16 v[120:123], v[178:181], v[194:197], v[120:123]
	v_mfma_f32_16x16x32_bf16 v[116:119], v[186:189], v[194:197], v[116:119]
	v_mfma_f32_16x16x32_bf16 v[104:107], v[178:181], v[212:215], v[104:107]
	v_mfma_f32_16x16x32_bf16 v[100:103], v[186:189], v[212:215], v[100:103]
	v_mfma_f32_16x16x32_bf16 v[88:91], v[178:181], v[220:223], v[88:91]
	v_mfma_f32_16x16x32_bf16 v[84:87], v[186:189], v[220:223], v[84:87]
	v_mfma_f32_16x16x32_bf16 v[72:75], v[178:181], v[228:231], v[72:75]
	v_mfma_f32_16x16x32_bf16 v[68:71], v[186:189], v[228:231], v[68:71]
	v_mfma_f32_16x16x32_bf16 v[120:123], v[182:185], v[198:201], v[120:123]
	v_mfma_f32_16x16x32_bf16 v[116:119], v[190:193], v[198:201], v[116:119]
	v_mfma_f32_16x16x32_bf16 v[104:107], v[182:185], v[216:219], v[104:107]
	v_mfma_f32_16x16x32_bf16 v[100:103], v[190:193], v[216:219], v[100:103]
	v_mfma_f32_16x16x32_bf16 v[88:91], v[182:185], v[224:227], v[88:91]
	v_mfma_f32_16x16x32_bf16 v[84:87], v[190:193], v[224:227], v[84:87]
	v_mfma_f32_16x16x32_bf16 v[72:75], v[182:185], v[232:235], v[72:75]
	v_mfma_f32_16x16x32_bf16 v[68:71], v[190:193], v[232:235], v[68:71]
	s_setprio 0
	s_barrier
	s_add_i32 s54, s84, s63
	v_lshl_add_u64 v[236:237], v[236:237], 0, s[52:53]
	s_mov_b32 m0, s54
	ds_read_b128 v[194:197], v162 offset:49152
	ds_read_b128 v[198:201], v162 offset:50176
	ds_read_b128 v[212:215], v162 offset:51200
	ds_read_b128 v[216:219], v162 offset:52224
	ds_read_b128 v[220:223], v162 offset:53248
	ds_read_b128 v[224:227], v162 offset:54272
	ds_read_b128 v[228:231], v162 offset:55296
	ds_read_b128 v[232:235], v162 offset:56320
	s_cmp_lg_u32 s32, 0
	s_cbranch_scc1 .Lbt3_8
	global_load_lds_dwordx4 v[236:237], off
.Lbt3_8:
	s_add_i32 m0, s54, 0x2000
	s_add_u32 s42, s42, 0x10080
	v_lshl_add_u64 v[236:237], v[238:239], 0, s[52:53]
	s_addc_u32 s43, s43, 0
	s_add_i32 s54, s85, s63
	s_cmp_lg_u32 s32, 0
	s_cbranch_scc1 .Lbt3_9
	global_load_lds_dwordx4 v[236:237], off
.Lbt3_9:
	v_lshl_add_u64 v[236:237], s[42:43], 0, v[138:139]
	s_mov_b32 m0, s54
	s_nop 0
	s_cmp_lg_u32 s32, 0
	s_cbranch_scc1 .Lbt3_10
	global_load_lds_dwordx4 v[236:237], off
.Lbt3_10:
	v_lshl_add_u64 v[236:237], s[42:43], 0, v[134:135]
	s_add_i32 m0, s54, 0x2000
	s_nop 0
	s_cmp_lg_u32 s32, 0
	s_cbranch_scc1 .Lbt3_11
	global_load_lds_dwordx4 v[236:237], off
.Lbt3_11:
	v_lshl_add_u64 v[236:237], v[240:241], 0, s[52:53]
	s_mov_b32 m0, s67
	s_nop 0
	s_cmp_lg_u32 s32, 0
	s_cbranch_scc1 .Lbt3_12
	global_load_lds_dwordx4 v[236:237], off
.Lbt3_12:
	v_lshl_add_u64 v[236:237], v[242:243], 0, s[52:53]
	s_mov_b32 m0, s76
	s_nop 0
	s_cmp_lg_u32 s32, 0
	s_cbranch_scc1 .Lbt3_13
	global_load_lds_dwordx4 v[236:237], off
.Lbt3_13:
	s_waitcnt vmcnt(8)
	s_waitcnt lgkmcnt(0)
	s_barrier
	s_setprio 1
	s_waitcnt lgkmcnt(0)
	v_mfma_f32_16x16x32_bf16 v[64:67], v[146:149], v[194:197], v[64:67]
	v_mfma_f32_16x16x32_bf16 v[60:63], v[170:173], v[194:197], v[60:63]
	v_mfma_f32_16x16x32_bf16 v[48:51], v[146:149], v[212:215], v[48:51]
	v_mfma_f32_16x16x32_bf16 v[44:47], v[170:173], v[212:215], v[44:47]
	v_mfma_f32_16x16x32_bf16 v[32:35], v[146:149], v[220:223], v[32:35]
	v_mfma_f32_16x16x32_bf16 v[28:31], v[170:173], v[220:223], v[28:31]
	v_mfma_f32_16x16x32_bf16 v[16:19], v[146:149], v[228:231], v[16:19]
	v_mfma_f32_16x16x32_bf16 v[12:15], v[170:173], v[228:231], v[12:15]
	v_mfma_f32_16x16x32_bf16 v[64:67], v[164:167], v[198:201], v[64:67]
	v_mfma_f32_16x16x32_bf16 v[60:63], v[174:177], v[198:201], v[60:63]
	v_mfma_f32_16x16x32_bf16 v[48:51], v[164:167], v[216:219], v[48:51]
	v_mfma_f32_16x16x32_bf16 v[44:47], v[174:177], v[216:219], v[44:47]
	v_mfma_f32_16x16x32_bf16 v[32:35], v[164:167], v[224:227], v[32:35]
	v_mfma_f32_16x16x32_bf16 v[28:31], v[174:177], v[224:227], v[28:31]
	v_mfma_f32_16x16x32_bf16 v[16:19], v[164:167], v[232:235], v[16:19]
	v_mfma_f32_16x16x32_bf16 v[12:15], v[174:177], v[232:235], v[12:15]
	s_setprio 0
	s_setprio 1
	v_mfma_f32_16x16x32_bf16 v[56:59], v[178:181], v[194:197], v[56:59]
	v_mfma_f32_16x16x32_bf16 v[52:55], v[186:189], v[194:197], v[52:55]
	v_mfma_f32_16x16x32_bf16 v[40:43], v[178:181], v[212:215], v[40:43]
	v_mfma_f32_16x16x32_bf16 v[36:39], v[186:189], v[212:215], v[36:39]
	v_mfma_f32_16x16x32_bf16 v[24:27], v[178:181], v[220:223], v[24:27]
	v_mfma_f32_16x16x32_bf16 v[20:23], v[186:189], v[220:223], v[20:23]
	v_mfma_f32_16x16x32_bf16 v[8:11], v[178:181], v[228:231], v[8:11]
	v_mfma_f32_16x16x32_bf16 v[4:7], v[186:189], v[228:231], v[4:7]
	v_mfma_f32_16x16x32_bf16 v[56:59], v[182:185], v[198:201], v[56:59]
	v_mfma_f32_16x16x32_bf16 v[52:55], v[190:193], v[198:201], v[52:55]
	v_mfma_f32_16x16x32_bf16 v[40:43], v[182:185], v[216:219], v[40:43]
	v_mfma_f32_16x16x32_bf16 v[36:39], v[190:193], v[216:219], v[36:39]
	v_mfma_f32_16x16x32_bf16 v[24:27], v[182:185], v[224:227], v[24:27]
	v_mfma_f32_16x16x32_bf16 v[20:23], v[190:193], v[224:227], v[20:23]
	v_mfma_f32_16x16x32_bf16 v[8:11], v[182:185], v[232:235], v[8:11]
	v_mfma_f32_16x16x32_bf16 v[4:7], v[190:193], v[232:235], v[4:7]
	s_setprio 0
	s_barrier
	s_add_i32 s83, s83, 2
	s_add_u32 s40, s40, 0x100
	s_addc_u32 s41, s41, 0
	s_add_u32 s81, s81, 0x100
	s_addc_u32 s82, s82, 0
	s_cmp_gt_u32 s83, 13
	s_cbranch_scc0 .LBB0_1108
	s_and_b64 vcc, exec, s[18:19]
	s_cbranch_vccz .LBB0_1111
	s_barrier

; #define PG8_STAGE(bufoff, gbase, voff) do { _Pragma("unroll") for (int _i = 0; _i < 2; ++_i) \
;         __builtin_amdgcn_global_load_lds((const unsigned*)((const char*)(gbase) + (voff)[_i]), (PG8_LAS unsigned*)(lds + (bufoff) + ldsw + _i * 8192), 16, 0, 0); } while (0)
; #define PG8_LDA(dst, b, h) do { _Pragma("unroll") for (int m = 0; m < 4; ++m) _Pragma("unroll") for (int k = 0; k < 2; ++k) dst[m][k] = *(const PG8_LAS bf16x8*)(lds + PG8_SA(b, h) + aoff + m * 2048 + k * 1024); } while (0)
; #define PG8_LDB(dst, b, h) do { _Pragma("unroll") for (int n = 0; n < 2; ++n) _Pragma("unroll") for (int k = 0; k < 2; ++k) dst[n][k] = *(const PG8_LAS bf16x8*)(lds + PG8_SB(b, h) + boff + n * 2048 + k * 1024); } while (0)
; #define PG8_WAIT_V(n) asm volatile("s_waitcnt vmcnt(" #n ")" ::: "memory")
; #define PG8_WAIT_L(n) asm volatile("s_waitcnt lgkmcnt(" #n ")" ::: "memory")
; #define PG8_BAR __builtin_amdgcn_s_barrier()
; #define PG8_SCHED __builtin_amdgcn_sched_barrier(0)
; template <class Epi, class Sched, bool ALIGN_EPI = false, bool SP2 = false>
; __device__ __forceinline__ void gemm_phase(PG8_LAS unsigned char* lds, const Gemm g, const Sched& S, const Epi& E, const int tid) {
;     ...
;         const char* nA = has_next ? (const char*)g.A + (size_t)nxt.pm * tstep : cA; const char* nB = has_next ? (const char*)g.Bt + (size_t)nxt.pn * tstep : cB;
;         for (int t = 0; t < nt; t += 2) {
;             const bool last = (t == nt - 2);
;             const char* a1 = cA + (size_t)(t + 1) * kstep;
;             const char* a2 = last ? nA : cA + (size_t)(t + 2) * kstep; const char* b2 = last ? nB : cB + (size_t)(t + 2) * kstep;
;             const char* a3 = a2 + kstep; const char* b3 = b2 + kstep;
;             if (last && has_next) S.a_ready(nxt);
;             if constexpr (SP2) {
;             PG8_LDB(B0, 0, 0); PG8_LDB(B1, 0, 1); PG8_SCHED; PG8_LDA(At, 0, 0); PG8_STAGE(PG8_SA(1, 1), a1 + hstep, voffA);
;             PG8_WAIT_V(8); PG8_WAIT_L(0); PG8_BAR; PG8_MMA(0, 0, At, B0); PG8_MMA(0, 1, At, B1); PG8_BAR; PG8_SCHED;
;             PG8_LDA(At, 0, 1); PG8_STAGE(PG8_SB(0, 0), b2, voffB); PG8_STAGE(PG8_SB(0, 1), b2 + hstepB, voffB); PG8_STAGE(PG8_SA(0, 0), a2, voffA);
;             PG8_WAIT_V(8); PG8_WAIT_L(0); PG8_BAR; PG8_MMA(1, 0, At, B0); PG8_MMA(1, 1, At, B1); PG8_BAR; PG8_SCHED;
.LBB0_1266:
	s_add_u32 s38, s40, 0xfffc0080
	s_addc_u32 s39, s41, -1
	s_add_i32 s83, 0, 0x10000
	s_cmp_eq_u32 s82, 12
	s_cselect_b32 s43, s21, s39
	s_cselect_b32 s42, s29, s38
	v_add_u32_e32 v150, s83, v158
	s_cselect_b32 s39, s19, s81
	s_cselect_b32 s38, s79, s80
	s_cmp_eq_u32 s82, 12
	s_cselect_b32 s32, 1, 0
	s_andn2_b32 s32, s32, s36
	s_add_i32 s86, 0, 0x14000
	ds_read_b128 v[146:149], v150
	ds_read_b128 v[162:165], v150 offset:1024
	ds_read_b128 v[170:173], v150 offset:2048
	ds_read_b128 v[174:177], v150 offset:3072
	v_add_u32_e32 v150, s86, v158
	ds_read_b128 v[178:181], v150
	ds_read_b128 v[182:185], v150 offset:1024
	ds_read_b128 v[186:189], v150 offset:2048
	ds_read_b128 v[190:193], v150 offset:3072
	v_lshl_add_u64 v[150:151], s[40:41], 0, v[142:143]
	s_add_i32 m0, s31, 0xc000
	ds_read_b128 v[194:197], v160
	ds_read_b128 v[198:201], v160 offset:1024
	ds_read_b128 v[212:215], v160 offset:2048
	ds_read_b128 v[216:219], v160 offset:3072
	ds_read_b128 v[220:223], v160 offset:4096
	ds_read_b128 v[224:227], v160 offset:5120
	ds_read_b128 v[228:231], v160 offset:6144
	ds_read_b128 v[232:235], v160 offset:7168
	global_load_lds_dwordx4 v[150:151], off
	v_lshl_add_u64 v[150:151], s[40:41], 0, v[144:145]
	s_add_i32 m0, s31, 0xe000
	s_nop 0
	global_load_lds_dwordx4 v[150:151], off
	s_waitcnt vmcnt(8)
	s_waitcnt lgkmcnt(0)
	s_barrier
	s_setprio 1
	s_waitcnt lgkmcnt(0)
	v_mfma_f32_16x16x32_bf16 v[120:123], v[146:149], v[194:197], v[120:123]
	v_mfma_f32_16x16x32_bf16 v[128:131], v[170:173], v[194:197], v[128:131]
	v_mfma_f32_16x16x32_bf16 v[100:103], v[146:149], v[212:215], v[100:103]
	v_mfma_f32_16x16x32_bf16 v[108:111], v[170:173], v[212:215], v[108:111]
	v_mfma_f32_16x16x32_bf16 v[84:87], v[146:149], v[220:223], v[84:87]
	v_mfma_f32_16x16x32_bf16 v[92:95], v[170:173], v[220:223], v[92:95]
	v_mfma_f32_16x16x32_bf16 v[68:71], v[146:149], v[228:231], v[68:71]
	v_mfma_f32_16x16x32_bf16 v[76:79], v[170:173], v[228:231], v[76:79]
	v_mfma_f32_16x16x32_bf16 v[120:123], v[162:165], v[198:201], v[120:123]
	v_mfma_f32_16x16x32_bf16 v[128:131], v[174:177], v[198:201], v[128:131]
	v_mfma_f32_16x16x32_bf16 v[100:103], v[162:165], v[216:219], v[100:103]
	v_mfma_f32_16x16x32_bf16 v[108:111], v[174:177], v[216:219], v[108:111]
	v_mfma_f32_16x16x32_bf16 v[84:87], v[162:165], v[224:227], v[84:87]
	v_mfma_f32_16x16x32_bf16 v[92:95], v[174:177], v[224:227], v[92:95]
	v_mfma_f32_16x16x32_bf16 v[68:71], v[162:165], v[232:235], v[68:71]
	v_mfma_f32_16x16x32_bf16 v[76:79], v[174:177], v[232:235], v[76:79]
	s_setprio 0
	s_setprio 1
	v_mfma_f32_16x16x32_bf16 v[116:119], v[178:181], v[194:197], v[116:119]
	v_mfma_f32_16x16x32_bf16 v[124:127], v[186:189], v[194:197], v[124:127]
	v_mfma_f32_16x16x32_bf16 v[104:107], v[178:181], v[212:215], v[104:107]
	v_mfma_f32_16x16x32_bf16 v[112:115], v[186:189], v[212:215], v[112:115]
	v_mfma_f32_16x16x32_bf16 v[88:91], v[178:181], v[220:223], v[88:91]
	v_mfma_f32_16x16x32_bf16 v[96:99], v[186:189], v[220:223], v[96:99]
	v_mfma_f32_16x16x32_bf16 v[72:75], v[178:181], v[228:231], v[72:75]
	v_mfma_f32_16x16x32_bf16 v[80:83], v[186:189], v[228:231], v[80:83]
	v_mfma_f32_16x16x32_bf16 v[116:119], v[182:185], v[198:201], v[116:119]
	v_mfma_f32_16x16x32_bf16 v[124:127], v[190:193], v[198:201], v[124:127]
	v_mfma_f32_16x16x32_bf16 v[104:107], v[182:185], v[216:219], v[104:107]
	v_mfma_f32_16x16x32_bf16 v[112:115], v[190:193], v[216:219], v[112:115]
	v_mfma_f32_16x16x32_bf16 v[88:91], v[182:185], v[224:227], v[88:91]
	v_mfma_f32_16x16x32_bf16 v[96:99], v[190:193], v[224:227], v[96:99]
	v_mfma_f32_16x16x32_bf16 v[72:75], v[182:185], v[232:235], v[72:75]
	v_mfma_f32_16x16x32_bf16 v[80:83], v[190:193], v[232:235], v[80:83]
	s_setprio 0
	s_barrier
	s_add_i32 s83, s83, s55
	v_lshl_add_u64 v[150:151], s[38:39], 0, v[136:137]
	s_mov_b32 m0, s83
	ds_read_b128 v[194:197], v160 offset:16384
	ds_read_b128 v[198:201], v160 offset:17408
	ds_read_b128 v[212:215], v160 offset:18432
	ds_read_b128 v[216:219], v160 offset:19456
	ds_read_b128 v[220:223], v160 offset:20480
	ds_read_b128 v[224:227], v160 offset:21504
	ds_read_b128 v[228:231], v160 offset:22528
	ds_read_b128 v[232:235], v160 offset:23552
	s_cmp_lg_u32 s32, 0
	s_cbranch_scc1 .Lbt4_0
	global_load_lds_dwordx4 v[150:151], off
.Lbt4_0:
	s_add_i32 m0, s83, 0x2000
	s_add_u32 s84, s38, 0x10000
	v_lshl_add_u64 v[166:167], s[38:39], 0, v[140:141]
	s_addc_u32 s85, s39, 0
	s_add_i32 s83, s86, s55
	s_cmp_lg_u32 s32, 0
	s_cbranch_scc1 .Lbt4_1
	global_load_lds_dwordx4 v[166:167], off
.Lbt4_1:
	v_lshl_add_u64 v[236:237], s[84:85], 0, v[136:137]
	s_mov_b32 m0, s83
	v_lshl_add_u64 v[238:239], s[42:43], 0, v[138:139]
	s_cmp_lg_u32 s32, 0
	s_cbranch_scc1 .Lbt4_2
	global_load_lds_dwordx4 v[236:237], off
.Lbt4_2:
	v_lshl_add_u64 v[236:237], s[84:85], 0, v[140:141]
	s_add_i32 m0, s83, 0x2000
	s_nop 0
	s_cmp_lg_u32 s32, 0
	s_cbranch_scc1 .Lbt4_3
	global_load_lds_dwordx4 v[236:237], off
.Lbt4_3:
	v_lshl_add_u64 v[236:237], s[42:43], 0, v[134:135]
	s_mov_b32 m0, s31
	s_nop 0
	s_cmp_lg_u32 s32, 0
	s_cbranch_scc1 .Lbt4_4
	global_load_lds_dwordx4 v[236:237], off
.Lbt4_4:
	s_mov_b32 m0, s63
	s_nop 0
	s_cmp_lg_u32 s32, 0
	s_cbranch_scc1 .Lbt4_5
	global_load_lds_dwordx4 v[238:239], off

; #define PG8_STAGE(bufoff, gbase, voff) do { _Pragma("unroll") for (int _i = 0; _i < 2; ++_i) \
;         __builtin_amdgcn_global_load_lds((const unsigned*)((const char*)(gbase) + (voff)[_i]), (PG8_LAS unsigned*)(lds + (bufoff) + ldsw + _i * 8192), 16, 0, 0); } while (0)
; #define PG8_LDA(dst, b, h) do { _Pragma("unroll") for (int m = 0; m < 4; ++m) _Pragma("unroll") for (int k = 0; k < 2; ++k) dst[m][k] = *(const PG8_LAS bf16x8*)(lds + PG8_SA(b, h) + aoff + m * 2048 + k * 1024); } while (0)
; #define PG8_LDB(dst, b, h) do { _Pragma("unroll") for (int n = 0; n < 2; ++n) _Pragma("unroll") for (int k = 0; k < 2; ++k) dst[n][k] = *(const PG8_LAS bf16x8*)(lds + PG8_SB(b, h) + boff + n * 2048 + k * 1024); } while (0)
; #define PG8_MMA(ai, bj, At, Bt) do { __builtin_amdgcn_s_setprio(1); _Pragma("unroll") for (int m = 0; m < 4; ++m) _Pragma("unroll") for (int n = 0; n < 2; ++n) _Pragma("unroll") for (int k = 0; k < 2; ++k) \
;         acc[ai][bj][m][n] = __builtin_amdgcn_mfma_f32_16x16x32_bf16(Bt[n][k], At[m][k], acc[ai][bj][m][n], 0, 0, 0); __builtin_amdgcn_s_setprio(0); } while (0)
; #define PG8_WAIT_V(n) asm volatile("s_waitcnt vmcnt(" #n ")" ::: "memory")
; #define PG8_WAIT_L(n) asm volatile("s_waitcnt lgkmcnt(" #n ")" ::: "memory")
; #define PG8_BAR __builtin_amdgcn_s_barrier()
; #define PG8_SCHED __builtin_amdgcn_sched_barrier(0)
; template <class Epi, class Sched, bool ALIGN_EPI = false, bool SP2 = false>
; __device__ __forceinline__ void gemm_phase(PG8_LAS unsigned char* lds, const Gemm g, const Sched& S, const Epi& E, const int tid) {
;     ...
;             PG8_WAIT_V(8); PG8_WAIT_L(0); PG8_BAR; PG8_MMA(1, 0, At, B0); PG8_MMA(1, 1, At, B1); PG8_BAR; PG8_SCHED;
;             PG8_LDB(B0, 1, 0); PG8_LDB(B1, 1, 1); PG8_SCHED; PG8_LDA(At, 1, 0); PG8_STAGE(PG8_SA(0, 1), a2 + hstep, voffA);
;             PG8_WAIT_V(8); PG8_WAIT_L(0); PG8_BAR; PG8_MMA(0, 0, At, B0); PG8_MMA(0, 1, At, B1); PG8_BAR; PG8_SCHED;
.Lbw4_2:
	s_waitcnt lgkmcnt(0)
	s_barrier
	s_setprio 1
	s_waitcnt lgkmcnt(0)
	v_mfma_f32_16x16x32_bf16 v[52:55], v[146:149], v[194:197], v[52:55]
	v_mfma_f32_16x16x32_bf16 v[60:63], v[170:173], v[194:197], v[60:63]
	v_mfma_f32_16x16x32_bf16 v[36:39], v[146:149], v[212:215], v[36:39]
	v_mfma_f32_16x16x32_bf16 v[44:47], v[170:173], v[212:215], v[44:47]
	v_mfma_f32_16x16x32_bf16 v[20:23], v[146:149], v[220:223], v[20:23]
	v_mfma_f32_16x16x32_bf16 v[28:31], v[170:173], v[220:223], v[28:31]
	v_mfma_f32_16x16x32_bf16 v[4:7], v[146:149], v[228:231], v[4:7]
	v_mfma_f32_16x16x32_bf16 v[12:15], v[170:173], v[228:231], v[12:15]
	v_mfma_f32_16x16x32_bf16 v[52:55], v[162:165], v[198:201], v[52:55]
	v_mfma_f32_16x16x32_bf16 v[60:63], v[174:177], v[198:201], v[60:63]
	v_mfma_f32_16x16x32_bf16 v[36:39], v[162:165], v[216:219], v[36:39]
	v_mfma_f32_16x16x32_bf16 v[44:47], v[174:177], v[216:219], v[44:47]
	v_mfma_f32_16x16x32_bf16 v[20:23], v[162:165], v[224:227], v[20:23]
	v_mfma_f32_16x16x32_bf16 v[28:31], v[174:177], v[224:227], v[28:31]
	v_mfma_f32_16x16x32_bf16 v[4:7], v[162:165], v[232:235], v[4:7]
	v_mfma_f32_16x16x32_bf16 v[12:15], v[174:177], v[232:235], v[12:15]
	s_setprio 0
	s_setprio 1
	v_mfma_f32_16x16x32_bf16 v[56:59], v[178:181], v[194:197], v[56:59]
	v_mfma_f32_16x16x32_bf16 v[64:67], v[186:189], v[194:197], v[64:67]
	v_mfma_f32_16x16x32_bf16 v[40:43], v[178:181], v[212:215], v[40:43]
	v_mfma_f32_16x16x32_bf16 v[48:51], v[186:189], v[212:215], v[48:51]
	v_mfma_f32_16x16x32_bf16 v[24:27], v[178:181], v[220:223], v[24:27]
	v_mfma_f32_16x16x32_bf16 v[32:35], v[186:189], v[220:223], v[32:35]
	v_mfma_f32_16x16x32_bf16 v[8:11], v[178:181], v[228:231], v[8:11]
	v_mfma_f32_16x16x32_bf16 v[16:19], v[186:189], v[228:231], v[16:19]
	v_mfma_f32_16x16x32_bf16 v[56:59], v[182:185], v[198:201], v[56:59]
	v_mfma_f32_16x16x32_bf16 v[64:67], v[190:193], v[198:201], v[64:67]
	v_mfma_f32_16x16x32_bf16 v[40:43], v[182:185], v[216:219], v[40:43]
	v_mfma_f32_16x16x32_bf16 v[48:51], v[190:193], v[216:219], v[48:51]
	v_mfma_f32_16x16x32_bf16 v[24:27], v[182:185], v[224:227], v[24:27]
	v_mfma_f32_16x16x32_bf16 v[32:35], v[190:193], v[224:227], v[32:35]
	v_mfma_f32_16x16x32_bf16 v[8:11], v[182:185], v[232:235], v[8:11]
	v_mfma_f32_16x16x32_bf16 v[16:19], v[190:193], v[232:235], v[16:19]
	s_setprio 0
	s_barrier
	s_add_i32 s83, 0, 0x18000
	v_add_u32_e32 v161, s83, v158
	s_add_i32 s84, 0, 0x1c000
	ds_read_b128 v[146:149], v161
	ds_read_b128 v[162:165], v161 offset:1024
	ds_read_b128 v[170:173], v161 offset:2048
	ds_read_b128 v[174:177], v161 offset:3072
	v_add_u32_e32 v161, s84, v158
	ds_read_b128 v[178:181], v161
	ds_read_b128 v[182:185], v161 offset:1024
	ds_read_b128 v[186:189], v161 offset:2048
	ds_read_b128 v[190:193], v161 offset:3072
	s_add_u32 s42, s42, 0x40000
	s_addc_u32 s43, s43, 0
	s_mov_b32 m0, s64
	v_lshl_add_u64 v[240:241], s[42:43], 0, v[134:135]
	ds_read_b128 v[194:197], v160 offset:32768
	ds_read_b128 v[198:201], v160 offset:33792
	ds_read_b128 v[212:215], v160 offset:34816
	ds_read_b128 v[216:219], v160 offset:35840
	ds_read_b128 v[220:223], v160 offset:36864
	ds_read_b128 v[224:227], v160 offset:37888
	ds_read_b128 v[228:231], v160 offset:38912
	ds_read_b128 v[232:235], v160 offset:39936
	s_cmp_lg_u32 s32, 0
	s_cbranch_scc1 .Lbt4_6
	global_load_lds_dwordx4 v[240:241], off
.Lbt4_6:
	v_lshl_add_u64 v[240:241], s[42:43], 0, v[138:139]
	s_mov_b32 m0, s65
	s_nop 0
	s_cmp_lg_u32 s32, 0
	s_cbranch_scc1 .Lbt4_7
	global_load_lds_dwordx4 v[240:241], off

; #define PG8_STAGE(bufoff, gbase, voff) do { _Pragma("unroll") for (int _i = 0; _i < 2; ++_i) \
;         __builtin_amdgcn_global_load_lds((const unsigned*)((const char*)(gbase) + (voff)[_i]), (PG8_LAS unsigned*)(lds + (bufoff) + ldsw + _i * 8192), 16, 0, 0); } while (0)
; #define PG8_LDA(dst, b, h) do { _Pragma("unroll") for (int m = 0; m < 4; ++m) _Pragma("unroll") for (int k = 0; k < 2; ++k) dst[m][k] = *(const PG8_LAS bf16x8*)(lds + PG8_SA(b, h) + aoff + m * 2048 + k * 1024); } while (0)
; #define PG8_LDB(dst, b, h) do { _Pragma("unroll") for (int n = 0; n < 2; ++n) _Pragma("unroll") for (int k = 0; k < 2; ++k) dst[n][k] = *(const PG8_LAS bf16x8*)(lds + PG8_SB(b, h) + boff + n * 2048 + k * 1024); } while (0)
; #define PG8_MMA(ai, bj, At, Bt) do { __builtin_amdgcn_s_setprio(1); _Pragma("unroll") for (int m = 0; m < 4; ++m) _Pragma("unroll") for (int n = 0; n < 2; ++n) _Pragma("unroll") for (int k = 0; k < 2; ++k) \
;         acc[ai][bj][m][n] = __builtin_amdgcn_mfma_f32_16x16x32_bf16(Bt[n][k], At[m][k], acc[ai][bj][m][n], 0, 0, 0); __builtin_amdgcn_s_setprio(0); } while (0)
; #define PG8_WAIT_V(n) asm volatile("s_waitcnt vmcnt(" #n ")" ::: "memory")
; #define PG8_WAIT_L(n) asm volatile("s_waitcnt lgkmcnt(" #n ")" ::: "memory")
; #define PG8_BAR __builtin_amdgcn_s_barrier()
; #define PG8_SCHED __builtin_amdgcn_sched_barrier(0)
; template <class Epi, class Sched, bool ALIGN_EPI = false, bool SP2 = false>
; __device__ __forceinline__ void gemm_phase(PG8_LAS unsigned char* lds, const Gemm g, const Sched& S, const Epi& E, const int tid) {
;     ...
;             PG8_WAIT_V(8); PG8_WAIT_L(0); PG8_BAR; PG8_MMA(1, 0, At, B0); PG8_MMA(1, 1, At, B1); PG8_BAR; PG8_SCHED;
;             PG8_LDB(B0, 1, 0); PG8_LDB(B1, 1, 1); PG8_SCHED; PG8_LDA(At, 1, 0); PG8_STAGE(PG8_SA(0, 1), a2 + hstep, voffA);
;             PG8_WAIT_V(8); PG8_WAIT_L(0); PG8_BAR; PG8_MMA(0, 0, At, B0); PG8_MMA(0, 1, At, B1); PG8_BAR; PG8_SCHED;
;             PG8_LDA(At, 1, 1); PG8_STAGE(PG8_SB(1, 0), b3, voffB); PG8_STAGE(PG8_SB(1, 1), b3 + hstepB, voffB); PG8_STAGE(PG8_SA(1, 0), a3, voffA);
;             PG8_WAIT_V(8); PG8_WAIT_L(0); PG8_BAR; PG8_MMA(1, 0, At, B0); PG8_MMA(1, 1, At, B1); PG8_BAR; PG8_SCHED;
.Lbw4_0:
	s_waitcnt lgkmcnt(0)
	s_barrier
	s_setprio 1
	s_waitcnt lgkmcnt(0)
	v_mfma_f32_16x16x32_bf16 v[120:123], v[146:149], v[194:197], v[120:123]
	v_mfma_f32_16x16x32_bf16 v[128:131], v[170:173], v[194:197], v[128:131]
	v_mfma_f32_16x16x32_bf16 v[100:103], v[146:149], v[212:215], v[100:103]
	v_mfma_f32_16x16x32_bf16 v[108:111], v[170:173], v[212:215], v[108:111]
	v_mfma_f32_16x16x32_bf16 v[84:87], v[146:149], v[220:223], v[84:87]
	v_mfma_f32_16x16x32_bf16 v[92:95], v[170:173], v[220:223], v[92:95]
	v_mfma_f32_16x16x32_bf16 v[68:71], v[146:149], v[228:231], v[68:71]
	v_mfma_f32_16x16x32_bf16 v[76:79], v[170:173], v[228:231], v[76:79]
	v_mfma_f32_16x16x32_bf16 v[120:123], v[162:165], v[198:201], v[120:123]
	v_mfma_f32_16x16x32_bf16 v[128:131], v[174:177], v[198:201], v[128:131]
	v_mfma_f32_16x16x32_bf16 v[100:103], v[162:165], v[216:219], v[100:103]
	v_mfma_f32_16x16x32_bf16 v[108:111], v[174:177], v[216:219], v[108:111]
	v_mfma_f32_16x16x32_bf16 v[84:87], v[162:165], v[224:227], v[84:87]
	v_mfma_f32_16x16x32_bf16 v[92:95], v[174:177], v[224:227], v[92:95]
	v_mfma_f32_16x16x32_bf16 v[68:71], v[162:165], v[232:235], v[68:71]
	v_mfma_f32_16x16x32_bf16 v[76:79], v[174:177], v[232:235], v[76:79]
	s_setprio 0
	s_setprio 1
	v_mfma_f32_16x16x32_bf16 v[116:119], v[178:181], v[194:197], v[116:119]
	v_mfma_f32_16x16x32_bf16 v[124:127], v[186:189], v[194:197], v[124:127]
	v_mfma_f32_16x16x32_bf16 v[104:107], v[178:181], v[212:215], v[104:107]
	v_mfma_f32_16x16x32_bf16 v[112:115], v[186:189], v[212:215], v[112:115]
	v_mfma_f32_16x16x32_bf16 v[88:91], v[178:181], v[220:223], v[88:91]
	v_mfma_f32_16x16x32_bf16 v[96:99], v[186:189], v[220:223], v[96:99]
	v_mfma_f32_16x16x32_bf16 v[72:75], v[178:181], v[228:231], v[72:75]
	v_mfma_f32_16x16x32_bf16 v[80:83], v[186:189], v[228:231], v[80:83]
	v_mfma_f32_16x16x32_bf16 v[116:119], v[182:185], v[198:201], v[116:119]
	v_mfma_f32_16x16x32_bf16 v[124:127], v[190:193], v[198:201], v[124:127]
	v_mfma_f32_16x16x32_bf16 v[104:107], v[182:185], v[216:219], v[104:107]
	v_mfma_f32_16x16x32_bf16 v[112:115], v[190:193], v[216:219], v[112:115]
	v_mfma_f32_16x16x32_bf16 v[88:91], v[182:185], v[224:227], v[88:91]
	v_mfma_f32_16x16x32_bf16 v[96:99], v[190:193], v[224:227], v[96:99]
	v_mfma_f32_16x16x32_bf16 v[72:75], v[182:185], v[232:235], v[72:75]
	v_mfma_f32_16x16x32_bf16 v[80:83], v[190:193], v[232:235], v[80:83]
	s_setprio 0
	s_barrier
	s_add_i32 s42, s83, s55
	v_lshl_add_u64 v[150:151], v[150:151], 0, s[52:53]
	s_mov_b32 m0, s42
	ds_read_b128 v[194:197], v160 offset:49152
	ds_read_b128 v[198:201], v160 offset:50176
	ds_read_b128 v[212:215], v160 offset:51200
	ds_read_b128 v[216:219], v160 offset:52224
	ds_read_b128 v[220:223], v160 offset:53248
	ds_read_b128 v[224:227], v160 offset:54272
	ds_read_b128 v[228:231], v160 offset:55296
	ds_read_b128 v[232:235], v160 offset:56320
	s_cmp_lg_u32 s32, 0
	s_cbranch_scc1 .Lbt4_8
	global_load_lds_dwordx4 v[150:151], off
.Lbt4_8:
	s_add_i32 m0, s42, 0x2000
	s_add_u32 s38, s38, 0x10080
	v_lshl_add_u64 v[150:151], v[166:167], 0, s[52:53]
	s_addc_u32 s39, s39, 0
	s_add_i32 s42, s84, s55
	s_cmp_lg_u32 s32, 0
	s_cbranch_scc1 .Lbt4_9
	global_load_lds_dwordx4 v[150:151], off
.Lbt4_9:
	v_lshl_add_u64 v[150:151], s[38:39], 0, v[136:137]
	s_mov_b32 m0, s42
	s_nop 0
	s_cmp_lg_u32 s32, 0
	s_cbranch_scc1 .Lbt4_10
	global_load_lds_dwordx4 v[150:151], off
.Lbt4_10:
	v_lshl_add_u64 v[150:151], s[38:39], 0, v[140:141]
	s_add_i32 m0, s42, 0x2000
	s_nop 0
	s_cmp_lg_u32 s32, 0
	s_cbranch_scc1 .Lbt4_11
	global_load_lds_dwordx4 v[150:151], off
.Lbt4_11:
	v_lshl_add_u64 v[150:151], v[236:237], 0, s[52:53]
	s_mov_b32 m0, s66
	s_nop 0
	s_cmp_lg_u32 s32, 0
	s_cbranch_scc1 .Lbt4_12
	global_load_lds_dwordx4 v[150:151], off
.Lbt4_12:
	v_lshl_add_u64 v[150:151], v[238:239], 0, s[52:53]
	s_mov_b32 m0, s67
	s_nop 0
	s_cmp_lg_u32 s32, 0
	s_cbranch_scc1 .Lbt4_13
	global_load_lds_dwordx4 v[150:151], off
.Lbt4_13:
	s_waitcnt vmcnt(8)
	s_waitcnt lgkmcnt(0)
	s_barrier
	s_setprio 1
	s_waitcnt lgkmcnt(0)
	v_mfma_f32_16x16x32_bf16 v[52:55], v[146:149], v[194:197], v[52:55]
	v_mfma_f32_16x16x32_bf16 v[60:63], v[170:173], v[194:197], v[60:63]
	v_mfma_f32_16x16x32_bf16 v[36:39], v[146:149], v[212:215], v[36:39]
	v_mfma_f32_16x16x32_bf16 v[44:47], v[170:173], v[212:215], v[44:47]
	v_mfma_f32_16x16x32_bf16 v[20:23], v[146:149], v[220:223], v[20:23]
	v_mfma_f32_16x16x32_bf16 v[28:31], v[170:173], v[220:223], v[28:31]
	v_mfma_f32_16x16x32_bf16 v[4:7], v[146:149], v[228:231], v[4:7]
	v_mfma_f32_16x16x32_bf16 v[12:15], v[170:173], v[228:231], v[12:15]
	v_mfma_f32_16x16x32_bf16 v[52:55], v[162:165], v[198:201], v[52:55]
	v_mfma_f32_16x16x32_bf16 v[60:63], v[174:177], v[198:201], v[60:63]
	v_mfma_f32_16x16x32_bf16 v[36:39], v[162:165], v[216:219], v[36:39]
	v_mfma_f32_16x16x32_bf16 v[44:47], v[174:177], v[216:219], v[44:47]
	v_mfma_f32_16x16x32_bf16 v[20:23], v[162:165], v[224:227], v[20:23]
	v_mfma_f32_16x16x32_bf16 v[28:31], v[174:177], v[224:227], v[28:31]
	v_mfma_f32_16x16x32_bf16 v[4:7], v[162:165], v[232:235], v[4:7]
	v_mfma_f32_16x16x32_bf16 v[12:15], v[174:177], v[232:235], v[12:15]
	s_setprio 0
	s_setprio 1
	v_mfma_f32_16x16x32_bf16 v[56:59], v[178:181], v[194:197], v[56:59]
	v_mfma_f32_16x16x32_bf16 v[64:67], v[186:189], v[194:197], v[64:67]
	v_mfma_f32_16x16x32_bf16 v[40:43], v[178:181], v[212:215], v[40:43]
	v_mfma_f32_16x16x32_bf16 v[48:51], v[186:189], v[212:215], v[48:51]
	v_mfma_f32_16x16x32_bf16 v[24:27], v[178:181], v[220:223], v[24:27]
	v_mfma_f32_16x16x32_bf16 v[32:35], v[186:189], v[220:223], v[32:35]
	v_mfma_f32_16x16x32_bf16 v[8:11], v[178:181], v[228:231], v[8:11]
	v_mfma_f32_16x16x32_bf16 v[16:19], v[186:189], v[228:231], v[16:19]
	v_mfma_f32_16x16x32_bf16 v[56:59], v[182:185], v[198:201], v[56:59]
	v_mfma_f32_16x16x32_bf16 v[64:67], v[190:193], v[198:201], v[64:67]
	v_mfma_f32_16x16x32_bf16 v[40:43], v[182:185], v[216:219], v[40:43]
	v_mfma_f32_16x16x32_bf16 v[48:51], v[190:193], v[216:219], v[48:51]
	v_mfma_f32_16x16x32_bf16 v[24:27], v[182:185], v[224:227], v[24:27]
	v_mfma_f32_16x16x32_bf16 v[32:35], v[190:193], v[224:227], v[32:35]
	v_mfma_f32_16x16x32_bf16 v[8:11], v[182:185], v[232:235], v[8:11]
	v_mfma_f32_16x16x32_bf16 v[16:19], v[190:193], v[232:235], v[16:19]
	s_setprio 0
	s_barrier
	s_add_i32 s82, s82, 2
	s_add_u32 s40, s40, 0x100
	s_addc_u32 s41, s41, 0
	s_add_u32 s80, s80, 0x100
	s_addc_u32 s81, s81, 0
	s_cmp_gt_u32 s82, 13
	s_cbranch_scc0 .LBB0_1266
	s_and_b64 vcc, exec, s[16:17]
	s_cbranch_vccz .LBB0_1269
	s_barrier

; #define PG8_STAGE(bufoff, gbase, voff) do { _Pragma("unroll") for (int _i = 0; _i < 2; ++_i) \
;         __builtin_amdgcn_global_load_lds((const unsigned*)((const char*)(gbase) + (voff)[_i]), (PG8_LAS unsigned*)(lds + (bufoff) + ldsw + _i * 8192), 16, 0, 0); } while (0)
; #define PG8_LDA(dst, b, h) do { _Pragma("unroll") for (int m = 0; m < 4; ++m) _Pragma("unroll") for (int k = 0; k < 2; ++k) dst[m][k] = *(const PG8_LAS bf16x8*)(lds + PG8_SA(b, h) + aoff + m * 2048 + k * 1024); } while (0)
; #define PG8_LDB(dst, b, h) do { _Pragma("unroll") for (int n = 0; n < 2; ++n) _Pragma("unroll") for (int k = 0; k < 2; ++k) dst[n][k] = *(const PG8_LAS bf16x8*)(lds + PG8_SB(b, h) + boff + n * 2048 + k * 1024); } while (0)
; #define PG8_WAIT_V(n) asm volatile("s_waitcnt vmcnt(" #n ")" ::: "memory")
; #define PG8_WAIT_L(n) asm volatile("s_waitcnt lgkmcnt(" #n ")" ::: "memory")
; #define PG8_BAR __builtin_amdgcn_s_barrier()
; #define PG8_SCHED __builtin_amdgcn_sched_barrier(0)
; template <class Epi, class Sched, bool ALIGN_EPI = false, bool SP2 = false>
; __device__ __forceinline__ void gemm_phase(PG8_LAS unsigned char* lds, const Gemm g, const Sched& S, const Epi& E, const int tid) {
;     ...
;         const char* nA = has_next ? (const char*)g.A + (size_t)nxt.pm * tstep : cA; const char* nB = has_next ? (const char*)g.Bt + (size_t)nxt.pn * tstep : cB;
;         for (int t = 0; t < nt; t += 2) {
;             const bool last = (t == nt - 2);
;             const char* a1 = cA + (size_t)(t + 1) * kstep;
;             const char* a2 = last ? nA : cA + (size_t)(t + 2) * kstep; const char* b2 = last ? nB : cB + (size_t)(t + 2) * kstep;
;             const char* a3 = a2 + kstep; const char* b3 = b2 + kstep;
;             if (last && has_next) S.a_ready(nxt);
;             if constexpr (SP2) {
;             PG8_LDB(B0, 0, 0); PG8_LDB(B1, 0, 1); PG8_SCHED; PG8_LDA(At, 0, 0); PG8_STAGE(PG8_SA(1, 1), a1 + hstep, voffA);
;             PG8_WAIT_V(8); PG8_WAIT_L(0); PG8_BAR; PG8_MMA(0, 0, At, B0); PG8_MMA(0, 1, At, B1); PG8_BAR; PG8_SCHED;
;             PG8_LDA(At, 0, 1); PG8_STAGE(PG8_SB(0, 0), b2, voffB); PG8_STAGE(PG8_SB(0, 1), b2 + hstepB, voffB); PG8_STAGE(PG8_SA(0, 0), a2, voffA);
;             PG8_WAIT_V(8); PG8_WAIT_L(0); PG8_BAR; PG8_MMA(1, 0, At, B0); PG8_MMA(1, 1, At, B1); PG8_BAR; PG8_SCHED;
.LBB0_1380:
	s_lshl_b32 s98, s79, 7
	s_add_i32 s98, s98, s84
	s_add_i32 s99, s98, 0x100
	s_and_b32 s98, s98, 0x700
	s_and_b32 s99, s99, 0x700
	s_add_u32 s100, s30, s98
	s_addc_u32 s101, s31, 0
	s_add_u32 s36, s30, 0xfffbff80
	s_addc_u32 s37, s31, -1
	s_add_u32 s36, s36, s99
	s_addc_u32 s37, s37, 0
	s_add_u32 s92, s76, s99
	s_addc_u32 s93, s78, 0
	s_add_i32 s80, 0, 0x10000
	s_cmp_eq_u32 s79, 12
	s_cselect_b32 s39, s17, s37
	s_cselect_b32 s38, s66, s36
	v_add_u32_e32 v150, s80, v158
	s_cselect_b32 s37, s19, s93
	s_cselect_b32 s36, s67, s92
	s_cmp_eq_u32 s79, 12
	s_cselect_b32 s32, 1, 0
	s_andn2_b32 s32, s32, s22
	s_add_i32 s82, 0, 0x14000
	ds_read_b128 v[146:149], v150
	ds_read_b128 v[164:167], v150 offset:1024
	ds_read_b128 v[170:173], v150 offset:2048
	ds_read_b128 v[174:177], v150 offset:3072
	v_add_u32_e32 v150, s82, v158
	ds_read_b128 v[178:181], v150
	ds_read_b128 v[182:185], v150 offset:1024
	ds_read_b128 v[186:189], v150 offset:2048
	ds_read_b128 v[190:193], v150 offset:3072
	v_lshl_add_u64 v[150:151], s[100:101], 0, v[142:143]
	s_add_i32 m0, s29, 0xc000
	ds_read_b128 v[194:197], v163
	ds_read_b128 v[198:201], v163 offset:1024
	ds_read_b128 v[212:215], v163 offset:2048
	ds_read_b128 v[216:219], v163 offset:3072
	ds_read_b128 v[220:223], v163 offset:4096
	ds_read_b128 v[224:227], v163 offset:5120
	ds_read_b128 v[228:231], v163 offset:6144
	ds_read_b128 v[232:235], v163 offset:7168
	global_load_lds_dwordx4 v[150:151], off
	v_lshl_add_u64 v[150:151], s[100:101], 0, v[144:145]
	s_add_i32 m0, s29, 0xe000
	s_nop 0
	global_load_lds_dwordx4 v[150:151], off
	s_waitcnt vmcnt(8)
	s_waitcnt lgkmcnt(0)
	s_barrier
	s_setprio 1
	s_waitcnt lgkmcnt(0)
	v_mfma_f32_16x16x32_bf16 v[128:131], v[146:149], v[194:197], v[128:131]
	v_mfma_f32_16x16x32_bf16 v[124:127], v[170:173], v[194:197], v[124:127]
	v_mfma_f32_16x16x32_bf16 v[112:115], v[146:149], v[212:215], v[112:115]
	v_mfma_f32_16x16x32_bf16 v[108:111], v[170:173], v[212:215], v[108:111]
	v_mfma_f32_16x16x32_bf16 v[96:99], v[146:149], v[220:223], v[96:99]
	v_mfma_f32_16x16x32_bf16 v[92:95], v[170:173], v[220:223], v[92:95]
	v_mfma_f32_16x16x32_bf16 v[80:83], v[146:149], v[228:231], v[80:83]
	v_mfma_f32_16x16x32_bf16 v[76:79], v[170:173], v[228:231], v[76:79]
	v_mfma_f32_16x16x32_bf16 v[128:131], v[164:167], v[198:201], v[128:131]
	v_mfma_f32_16x16x32_bf16 v[124:127], v[174:177], v[198:201], v[124:127]
	v_mfma_f32_16x16x32_bf16 v[112:115], v[164:167], v[216:219], v[112:115]
	v_mfma_f32_16x16x32_bf16 v[108:111], v[174:177], v[216:219], v[108:111]
	v_mfma_f32_16x16x32_bf16 v[96:99], v[164:167], v[224:227], v[96:99]
	v_mfma_f32_16x16x32_bf16 v[92:95], v[174:177], v[224:227], v[92:95]
	v_mfma_f32_16x16x32_bf16 v[80:83], v[164:167], v[232:235], v[80:83]
	v_mfma_f32_16x16x32_bf16 v[76:79], v[174:177], v[232:235], v[76:79]
	s_setprio 0
	s_setprio 1
	v_mfma_f32_16x16x32_bf16 v[120:123], v[178:181], v[194:197], v[120:123]
	v_mfma_f32_16x16x32_bf16 v[116:119], v[186:189], v[194:197], v[116:119]
	v_mfma_f32_16x16x32_bf16 v[104:107], v[178:181], v[212:215], v[104:107]
	v_mfma_f32_16x16x32_bf16 v[100:103], v[186:189], v[212:215], v[100:103]
	v_mfma_f32_16x16x32_bf16 v[88:91], v[178:181], v[220:223], v[88:91]
	v_mfma_f32_16x16x32_bf16 v[84:87], v[186:189], v[220:223], v[84:87]
	v_mfma_f32_16x16x32_bf16 v[72:75], v[178:181], v[228:231], v[72:75]
	v_mfma_f32_16x16x32_bf16 v[68:71], v[186:189], v[228:231], v[68:71]
	v_mfma_f32_16x16x32_bf16 v[120:123], v[182:185], v[198:201], v[120:123]
	v_mfma_f32_16x16x32_bf16 v[116:119], v[190:193], v[198:201], v[116:119]
	v_mfma_f32_16x16x32_bf16 v[104:107], v[182:185], v[216:219], v[104:107]
	v_mfma_f32_16x16x32_bf16 v[100:103], v[190:193], v[216:219], v[100:103]
	v_mfma_f32_16x16x32_bf16 v[88:91], v[182:185], v[224:227], v[88:91]
	v_mfma_f32_16x16x32_bf16 v[84:87], v[190:193], v[224:227], v[84:87]
	v_mfma_f32_16x16x32_bf16 v[72:75], v[182:185], v[232:235], v[72:75]
	v_mfma_f32_16x16x32_bf16 v[68:71], v[190:193], v[232:235], v[68:71]
	s_setprio 0
	s_barrier
	s_add_i32 s80, s80, s42
	v_lshl_add_u64 v[150:151], s[36:37], 0, v[138:139]
	s_mov_b32 m0, s80
	ds_read_b128 v[194:197], v163 offset:16384
	ds_read_b128 v[198:201], v163 offset:17408
	ds_read_b128 v[212:215], v163 offset:18432
	ds_read_b128 v[216:219], v163 offset:19456
	ds_read_b128 v[220:223], v163 offset:20480
	ds_read_b128 v[224:227], v163 offset:21504
	ds_read_b128 v[228:231], v163 offset:22528
	ds_read_b128 v[232:235], v163 offset:23552
	s_cmp_lg_u32 s32, 0
	s_cbranch_scc1 .Lbt5_0
	global_load_lds_dwordx4 v[150:151], off
.Lbt5_0:
	s_add_i32 m0, s80, 0x2000
	s_add_u32 s80, s36, 0x10000
	v_lshl_add_u64 v[236:237], s[36:37], 0, v[134:135]
	s_addc_u32 s81, s37, 0
	s_add_i32 s82, s82, s42
	s_cmp_lg_u32 s32, 0
	s_cbranch_scc1 .Lbt5_1
	global_load_lds_dwordx4 v[236:237], off
.Lbt5_1:
	v_lshl_add_u64 v[238:239], s[80:81], 0, v[138:139]
	s_mov_b32 m0, s82
	v_lshl_add_u64 v[240:241], s[38:39], 0, v[136:137]
	s_cmp_lg_u32 s32, 0
	s_cbranch_scc1 .Lbt5_2
	global_load_lds_dwordx4 v[238:239], off
.Lbt5_2:
	v_lshl_add_u64 v[238:239], s[80:81], 0, v[134:135]
	s_add_i32 m0, s82, 0x2000
	s_nop 0
	s_cmp_lg_u32 s32, 0
	s_cbranch_scc1 .Lbt5_3
	global_load_lds_dwordx4 v[238:239], off
.Lbt5_3:
	v_lshl_add_u64 v[238:239], s[38:39], 0, v[140:141]
	s_mov_b32 m0, s29
	s_nop 0
	s_cmp_lg_u32 s32, 0
	s_cbranch_scc1 .Lbt5_4
	global_load_lds_dwordx4 v[238:239], off
.Lbt5_4:
	s_mov_b32 m0, s54
	s_nop 0
	s_cmp_lg_u32 s32, 0
	s_cbranch_scc1 .Lbt5_5
	global_load_lds_dwordx4 v[240:241], off

; #define PG8_STAGE(bufoff, gbase, voff) do { _Pragma("unroll") for (int _i = 0; _i < 2; ++_i) \
;         __builtin_amdgcn_global_load_lds((const unsigned*)((const char*)(gbase) + (voff)[_i]), (PG8_LAS unsigned*)(lds + (bufoff) + ldsw + _i * 8192), 16, 0, 0); } while (0)
; #define PG8_LDA(dst, b, h) do { _Pragma("unroll") for (int m = 0; m < 4; ++m) _Pragma("unroll") for (int k = 0; k < 2; ++k) dst[m][k] = *(const PG8_LAS bf16x8*)(lds + PG8_SA(b, h) + aoff + m * 2048 + k * 1024); } while (0)
; #define PG8_LDB(dst, b, h) do { _Pragma("unroll") for (int n = 0; n < 2; ++n) _Pragma("unroll") for (int k = 0; k < 2; ++k) dst[n][k] = *(const PG8_LAS bf16x8*)(lds + PG8_SB(b, h) + boff + n * 2048 + k * 1024); } while (0)
; #define PG8_MMA(ai, bj, At, Bt) do { __builtin_amdgcn_s_setprio(1); _Pragma("unroll") for (int m = 0; m < 4; ++m) _Pragma("unroll") for (int n = 0; n < 2; ++n) _Pragma("unroll") for (int k = 0; k < 2; ++k) \
;         acc[ai][bj][m][n] = __builtin_amdgcn_mfma_f32_16x16x32_bf16(Bt[n][k], At[m][k], acc[ai][bj][m][n], 0, 0, 0); __builtin_amdgcn_s_setprio(0); } while (0)
; #define PG8_WAIT_V(n) asm volatile("s_waitcnt vmcnt(" #n ")" ::: "memory")
; #define PG8_WAIT_L(n) asm volatile("s_waitcnt lgkmcnt(" #n ")" ::: "memory")
; #define PG8_BAR __builtin_amdgcn_s_barrier()
; #define PG8_SCHED __builtin_amdgcn_sched_barrier(0)
; template <class Epi, class Sched, bool ALIGN_EPI = false, bool SP2 = false>
; __device__ __forceinline__ void gemm_phase(PG8_LAS unsigned char* lds, const Gemm g, const Sched& S, const Epi& E, const int tid) {
;     ...
;             PG8_WAIT_V(8); PG8_WAIT_L(0); PG8_BAR; PG8_MMA(1, 0, At, B0); PG8_MMA(1, 1, At, B1); PG8_BAR; PG8_SCHED;
;             PG8_LDB(B0, 1, 0); PG8_LDB(B1, 1, 1); PG8_SCHED; PG8_LDA(At, 1, 0); PG8_STAGE(PG8_SA(0, 1), a2 + hstep, voffA);
;             PG8_WAIT_V(8); PG8_WAIT_L(0); PG8_BAR; PG8_MMA(0, 0, At, B0); PG8_MMA(0, 1, At, B1); PG8_BAR; PG8_SCHED;
.Lbw5_2:
	s_waitcnt lgkmcnt(0)
	s_barrier
	s_setprio 1
	s_waitcnt lgkmcnt(0)
	v_mfma_f32_16x16x32_bf16 v[64:67], v[146:149], v[194:197], v[64:67]
	v_mfma_f32_16x16x32_bf16 v[60:63], v[170:173], v[194:197], v[60:63]
	v_mfma_f32_16x16x32_bf16 v[48:51], v[146:149], v[212:215], v[48:51]
	v_mfma_f32_16x16x32_bf16 v[44:47], v[170:173], v[212:215], v[44:47]
	v_mfma_f32_16x16x32_bf16 v[32:35], v[146:149], v[220:223], v[32:35]
	v_mfma_f32_16x16x32_bf16 v[28:31], v[170:173], v[220:223], v[28:31]
	v_mfma_f32_16x16x32_bf16 v[16:19], v[146:149], v[228:231], v[16:19]
	v_mfma_f32_16x16x32_bf16 v[12:15], v[170:173], v[228:231], v[12:15]
	v_mfma_f32_16x16x32_bf16 v[64:67], v[164:167], v[198:201], v[64:67]
	v_mfma_f32_16x16x32_bf16 v[60:63], v[174:177], v[198:201], v[60:63]
	v_mfma_f32_16x16x32_bf16 v[48:51], v[164:167], v[216:219], v[48:51]
	v_mfma_f32_16x16x32_bf16 v[44:47], v[174:177], v[216:219], v[44:47]
	v_mfma_f32_16x16x32_bf16 v[32:35], v[164:167], v[224:227], v[32:35]
	v_mfma_f32_16x16x32_bf16 v[28:31], v[174:177], v[224:227], v[28:31]
	v_mfma_f32_16x16x32_bf16 v[16:19], v[164:167], v[232:235], v[16:19]
	v_mfma_f32_16x16x32_bf16 v[12:15], v[174:177], v[232:235], v[12:15]
	s_setprio 0
	s_setprio 1
	v_mfma_f32_16x16x32_bf16 v[56:59], v[178:181], v[194:197], v[56:59]
	v_mfma_f32_16x16x32_bf16 v[52:55], v[186:189], v[194:197], v[52:55]
	v_mfma_f32_16x16x32_bf16 v[40:43], v[178:181], v[212:215], v[40:43]
	v_mfma_f32_16x16x32_bf16 v[36:39], v[186:189], v[212:215], v[36:39]
	v_mfma_f32_16x16x32_bf16 v[24:27], v[178:181], v[220:223], v[24:27]
	v_mfma_f32_16x16x32_bf16 v[20:23], v[186:189], v[220:223], v[20:23]
	v_mfma_f32_16x16x32_bf16 v[8:11], v[178:181], v[228:231], v[8:11]
	v_mfma_f32_16x16x32_bf16 v[4:7], v[186:189], v[228:231], v[4:7]
	v_mfma_f32_16x16x32_bf16 v[56:59], v[182:185], v[198:201], v[56:59]
	v_mfma_f32_16x16x32_bf16 v[52:55], v[190:193], v[198:201], v[52:55]
	v_mfma_f32_16x16x32_bf16 v[40:43], v[182:185], v[216:219], v[40:43]
	v_mfma_f32_16x16x32_bf16 v[36:39], v[190:193], v[216:219], v[36:39]
	v_mfma_f32_16x16x32_bf16 v[24:27], v[182:185], v[224:227], v[24:27]
	v_mfma_f32_16x16x32_bf16 v[20:23], v[190:193], v[224:227], v[20:23]
	v_mfma_f32_16x16x32_bf16 v[8:11], v[182:185], v[232:235], v[8:11]
	v_mfma_f32_16x16x32_bf16 v[4:7], v[190:193], v[232:235], v[4:7]
	s_setprio 0
	s_barrier
	s_add_i32 s80, 0, 0x18000
	s_add_i32 s81, 0, 0x1c000
	v_add_u32_e32 v174, s80, v158
	v_add_u32_e32 v190, s81, v158
	ds_read_b128 v[146:149], v174
	ds_read_b128 v[164:167], v174 offset:1024
	ds_read_b128 v[170:173], v174 offset:2048
	ds_read_b128 v[174:177], v174 offset:3072
	ds_read_b128 v[178:181], v190
	ds_read_b128 v[182:185], v190 offset:1024
	ds_read_b128 v[186:189], v190 offset:2048
	ds_read_b128 v[190:193], v190 offset:3072
	s_add_u32 s38, s38, 0x40000
	s_addc_u32 s39, s39, 0
	s_mov_b32 m0, s55
	v_lshl_add_u64 v[242:243], s[38:39], 0, v[140:141]
	ds_read_b128 v[194:197], v163 offset:32768
	ds_read_b128 v[198:201], v163 offset:33792
	ds_read_b128 v[212:215], v163 offset:34816
	ds_read_b128 v[216:219], v163 offset:35840
	ds_read_b128 v[220:223], v163 offset:36864
	ds_read_b128 v[224:227], v163 offset:37888
	ds_read_b128 v[228:231], v163 offset:38912
	ds_read_b128 v[232:235], v163 offset:39936
	s_cmp_lg_u32 s32, 0
	s_cbranch_scc1 .Lbt5_6
	global_load_lds_dwordx4 v[242:243], off
.Lbt5_6:
	v_lshl_add_u64 v[242:243], s[38:39], 0, v[136:137]
	s_mov_b32 m0, s62
	s_nop 0
	s_cmp_lg_u32 s32, 0
	s_cbranch_scc1 .Lbt5_7
	global_load_lds_dwordx4 v[242:243], off

; #define PG8_STAGE(bufoff, gbase, voff) do { _Pragma("unroll") for (int _i = 0; _i < 2; ++_i) \
;         __builtin_amdgcn_global_load_lds((const unsigned*)((const char*)(gbase) + (voff)[_i]), (PG8_LAS unsigned*)(lds + (bufoff) + ldsw + _i * 8192), 16, 0, 0); } while (0)
; #define PG8_LDA(dst, b, h) do { _Pragma("unroll") for (int m = 0; m < 4; ++m) _Pragma("unroll") for (int k = 0; k < 2; ++k) dst[m][k] = *(const PG8_LAS bf16x8*)(lds + PG8_SA(b, h) + aoff + m * 2048 + k * 1024); } while (0)
; #define PG8_LDB(dst, b, h) do { _Pragma("unroll") for (int n = 0; n < 2; ++n) _Pragma("unroll") for (int k = 0; k < 2; ++k) dst[n][k] = *(const PG8_LAS bf16x8*)(lds + PG8_SB(b, h) + boff + n * 2048 + k * 1024); } while (0)
; #define PG8_MMA(ai, bj, At, Bt) do { __builtin_amdgcn_s_setprio(1); _Pragma("unroll") for (int m = 0; m < 4; ++m) _Pragma("unroll") for (int n = 0; n < 2; ++n) _Pragma("unroll") for (int k = 0; k < 2; ++k) \
;         acc[ai][bj][m][n] = __builtin_amdgcn_mfma_f32_16x16x32_bf16(Bt[n][k], At[m][k], acc[ai][bj][m][n], 0, 0, 0); __builtin_amdgcn_s_setprio(0); } while (0)
; #define PG8_WAIT_V(n) asm volatile("s_waitcnt vmcnt(" #n ")" ::: "memory")
; #define PG8_WAIT_L(n) asm volatile("s_waitcnt lgkmcnt(" #n ")" ::: "memory")
; #define PG8_BAR __builtin_amdgcn_s_barrier()
; #define PG8_SCHED __builtin_amdgcn_sched_barrier(0)
; template <class Epi, class Sched, bool ALIGN_EPI = false, bool SP2 = false>
; __device__ __forceinline__ void gemm_phase(PG8_LAS unsigned char* lds, const Gemm g, const Sched& S, const Epi& E, const int tid) {
;     ...
;             PG8_WAIT_V(8); PG8_WAIT_L(0); PG8_BAR; PG8_MMA(1, 0, At, B0); PG8_MMA(1, 1, At, B1); PG8_BAR; PG8_SCHED;
;             PG8_LDB(B0, 1, 0); PG8_LDB(B1, 1, 1); PG8_SCHED; PG8_LDA(At, 1, 0); PG8_STAGE(PG8_SA(0, 1), a2 + hstep, voffA);
;             PG8_WAIT_V(8); PG8_WAIT_L(0); PG8_BAR; PG8_MMA(0, 0, At, B0); PG8_MMA(0, 1, At, B1); PG8_BAR; PG8_SCHED;
;             PG8_LDA(At, 1, 1); PG8_STAGE(PG8_SB(1, 0), b3, voffB); PG8_STAGE(PG8_SB(1, 1), b3 + hstepB, voffB); PG8_STAGE(PG8_SA(1, 0), a3, voffA);
;             PG8_WAIT_V(8); PG8_WAIT_L(0); PG8_BAR; PG8_MMA(1, 0, At, B0); PG8_MMA(1, 1, At, B1); PG8_BAR; PG8_SCHED;
.Lbw5_0:
	s_waitcnt lgkmcnt(0)
	s_barrier
	s_setprio 1
	s_waitcnt lgkmcnt(0)
	v_mfma_f32_16x16x32_bf16 v[128:131], v[146:149], v[194:197], v[128:131]
	v_mfma_f32_16x16x32_bf16 v[124:127], v[170:173], v[194:197], v[124:127]
	v_mfma_f32_16x16x32_bf16 v[112:115], v[146:149], v[212:215], v[112:115]
	v_mfma_f32_16x16x32_bf16 v[108:111], v[170:173], v[212:215], v[108:111]
	v_mfma_f32_16x16x32_bf16 v[96:99], v[146:149], v[220:223], v[96:99]
	v_mfma_f32_16x16x32_bf16 v[92:95], v[170:173], v[220:223], v[92:95]
	v_mfma_f32_16x16x32_bf16 v[80:83], v[146:149], v[228:231], v[80:83]
	v_mfma_f32_16x16x32_bf16 v[76:79], v[170:173], v[228:231], v[76:79]
	v_mfma_f32_16x16x32_bf16 v[128:131], v[164:167], v[198:201], v[128:131]
	v_mfma_f32_16x16x32_bf16 v[124:127], v[174:177], v[198:201], v[124:127]
	v_mfma_f32_16x16x32_bf16 v[112:115], v[164:167], v[216:219], v[112:115]
	v_mfma_f32_16x16x32_bf16 v[108:111], v[174:177], v[216:219], v[108:111]
	v_mfma_f32_16x16x32_bf16 v[96:99], v[164:167], v[224:227], v[96:99]
	v_mfma_f32_16x16x32_bf16 v[92:95], v[174:177], v[224:227], v[92:95]
	v_mfma_f32_16x16x32_bf16 v[80:83], v[164:167], v[232:235], v[80:83]
	v_mfma_f32_16x16x32_bf16 v[76:79], v[174:177], v[232:235], v[76:79]
	s_setprio 0
	s_setprio 1
	v_mfma_f32_16x16x32_bf16 v[120:123], v[178:181], v[194:197], v[120:123]
	v_mfma_f32_16x16x32_bf16 v[116:119], v[186:189], v[194:197], v[116:119]
	v_mfma_f32_16x16x32_bf16 v[104:107], v[178:181], v[212:215], v[104:107]
	v_mfma_f32_16x16x32_bf16 v[100:103], v[186:189], v[212:215], v[100:103]
	v_mfma_f32_16x16x32_bf16 v[88:91], v[178:181], v[220:223], v[88:91]
	v_mfma_f32_16x16x32_bf16 v[84:87], v[186:189], v[220:223], v[84:87]
	v_mfma_f32_16x16x32_bf16 v[72:75], v[178:181], v[228:231], v[72:75]
	v_mfma_f32_16x16x32_bf16 v[68:71], v[186:189], v[228:231], v[68:71]
	v_mfma_f32_16x16x32_bf16 v[120:123], v[182:185], v[198:201], v[120:123]
	v_mfma_f32_16x16x32_bf16 v[116:119], v[190:193], v[198:201], v[116:119]
	v_mfma_f32_16x16x32_bf16 v[104:107], v[182:185], v[216:219], v[104:107]
	v_mfma_f32_16x16x32_bf16 v[100:103], v[190:193], v[216:219], v[100:103]
	v_mfma_f32_16x16x32_bf16 v[88:91], v[182:185], v[224:227], v[88:91]
	v_mfma_f32_16x16x32_bf16 v[84:87], v[190:193], v[224:227], v[84:87]
	v_mfma_f32_16x16x32_bf16 v[72:75], v[182:185], v[232:235], v[72:75]
	v_mfma_f32_16x16x32_bf16 v[68:71], v[190:193], v[232:235], v[68:71]
	s_setprio 0
	s_barrier
	s_add_i32 s38, s80, s42
	v_lshl_add_u64 v[150:151], v[150:151], 0, s[52:53]
	s_mov_b32 m0, s38
	ds_read_b128 v[194:197], v163 offset:49152
	ds_read_b128 v[198:201], v163 offset:50176
	ds_read_b128 v[212:215], v163 offset:51200
	ds_read_b128 v[216:219], v163 offset:52224
	ds_read_b128 v[220:223], v163 offset:53248
	ds_read_b128 v[224:227], v163 offset:54272
	ds_read_b128 v[228:231], v163 offset:55296
	ds_read_b128 v[232:235], v163 offset:56320
	s_cmp_lg_u32 s32, 0
	s_cbranch_scc1 .Lbt5_8
	global_load_lds_dwordx4 v[150:151], off
.Lbt5_8:
	s_add_i32 m0, s38, 0x2000
	s_add_u32 s36, s36, 0x10080
	v_lshl_add_u64 v[150:151], v[236:237], 0, s[52:53]
	s_addc_u32 s37, s37, 0
	s_add_i32 s38, s81, s42
	s_cmp_lg_u32 s32, 0
	s_cbranch_scc1 .Lbt5_9
	global_load_lds_dwordx4 v[150:151], off
.Lbt5_9:
	v_lshl_add_u64 v[150:151], s[36:37], 0, v[138:139]
	s_mov_b32 m0, s38
	s_nop 0
	s_cmp_lg_u32 s32, 0
	s_cbranch_scc1 .Lbt5_10
	global_load_lds_dwordx4 v[150:151], off
.Lbt5_10:
	v_lshl_add_u64 v[150:151], s[36:37], 0, v[134:135]
	s_add_i32 m0, s38, 0x2000
	s_nop 0
	s_cmp_lg_u32 s32, 0
	s_cbranch_scc1 .Lbt5_11
	global_load_lds_dwordx4 v[150:151], off
.Lbt5_11:
	v_lshl_add_u64 v[150:151], v[238:239], 0, s[52:53]
	s_mov_b32 m0, s63
	s_nop 0
	s_cmp_lg_u32 s32, 0
	s_cbranch_scc1 .Lbt5_12
	global_load_lds_dwordx4 v[150:151], off
.Lbt5_12:
	v_lshl_add_u64 v[150:151], v[240:241], 0, s[52:53]
	s_mov_b32 m0, s64
	s_nop 0
	s_cmp_lg_u32 s32, 0
	s_cbranch_scc1 .Lbt5_13
	global_load_lds_dwordx4 v[150:151], off
.Lbt5_13:
	s_waitcnt vmcnt(8)
	s_waitcnt lgkmcnt(0)
	s_barrier
	s_setprio 1
	s_waitcnt lgkmcnt(0)
	v_mfma_f32_16x16x32_bf16 v[64:67], v[146:149], v[194:197], v[64:67]
	v_mfma_f32_16x16x32_bf16 v[60:63], v[170:173], v[194:197], v[60:63]
	v_mfma_f32_16x16x32_bf16 v[48:51], v[146:149], v[212:215], v[48:51]
	v_mfma_f32_16x16x32_bf16 v[44:47], v[170:173], v[212:215], v[44:47]
	v_mfma_f32_16x16x32_bf16 v[32:35], v[146:149], v[220:223], v[32:35]
	v_mfma_f32_16x16x32_bf16 v[28:31], v[170:173], v[220:223], v[28:31]
	v_mfma_f32_16x16x32_bf16 v[16:19], v[146:149], v[228:231], v[16:19]
	v_mfma_f32_16x16x32_bf16 v[12:15], v[170:173], v[228:231], v[12:15]
	v_mfma_f32_16x16x32_bf16 v[64:67], v[164:167], v[198:201], v[64:67]
	v_mfma_f32_16x16x32_bf16 v[60:63], v[174:177], v[198:201], v[60:63]
	v_mfma_f32_16x16x32_bf16 v[48:51], v[164:167], v[216:219], v[48:51]
	v_mfma_f32_16x16x32_bf16 v[44:47], v[174:177], v[216:219], v[44:47]
	v_mfma_f32_16x16x32_bf16 v[32:35], v[164:167], v[224:227], v[32:35]
	v_mfma_f32_16x16x32_bf16 v[28:31], v[174:177], v[224:227], v[28:31]
	v_mfma_f32_16x16x32_bf16 v[16:19], v[164:167], v[232:235], v[16:19]
	v_mfma_f32_16x16x32_bf16 v[12:15], v[174:177], v[232:235], v[12:15]
	s_setprio 0
	s_setprio 1
	v_mfma_f32_16x16x32_bf16 v[56:59], v[178:181], v[194:197], v[56:59]
	v_mfma_f32_16x16x32_bf16 v[52:55], v[186:189], v[194:197], v[52:55]
	v_mfma_f32_16x16x32_bf16 v[40:43], v[178:181], v[212:215], v[40:43]
	v_mfma_f32_16x16x32_bf16 v[36:39], v[186:189], v[212:215], v[36:39]
	v_mfma_f32_16x16x32_bf16 v[24:27], v[178:181], v[220:223], v[24:27]
	v_mfma_f32_16x16x32_bf16 v[20:23], v[186:189], v[220:223], v[20:23]
	v_mfma_f32_16x16x32_bf16 v[8:11], v[178:181], v[228:231], v[8:11]
	v_mfma_f32_16x16x32_bf16 v[4:7], v[186:189], v[228:231], v[4:7]
	v_mfma_f32_16x16x32_bf16 v[56:59], v[182:185], v[198:201], v[56:59]
	v_mfma_f32_16x16x32_bf16 v[52:55], v[190:193], v[198:201], v[52:55]
	v_mfma_f32_16x16x32_bf16 v[40:43], v[182:185], v[216:219], v[40:43]
	v_mfma_f32_16x16x32_bf16 v[36:39], v[190:193], v[216:219], v[36:39]
	v_mfma_f32_16x16x32_bf16 v[24:27], v[182:185], v[224:227], v[24:27]
	v_mfma_f32_16x16x32_bf16 v[20:23], v[190:193], v[224:227], v[20:23]
	v_mfma_f32_16x16x32_bf16 v[8:11], v[182:185], v[232:235], v[8:11]
	v_mfma_f32_16x16x32_bf16 v[4:7], v[190:193], v[232:235], v[4:7]
	s_setprio 0
	s_barrier
	s_add_i32 s79, s79, 2
	s_cmp_gt_u32 s79, 13
	s_cbranch_scc0 .LBB0_1380
	s_and_b64 vcc, exec, s[14:15]
	s_cbranch_vccz .LBB0_1383
	s_barrier

; #define PG8_STAGE(bufoff, gbase, voff) do { _Pragma("unroll") for (int _i = 0; _i < 2; ++_i) \
;         __builtin_amdgcn_global_load_lds((const unsigned*)((const char*)(gbase) + (voff)[_i]), (PG8_LAS unsigned*)(lds + (bufoff) + ldsw + _i * 8192), 16, 0, 0); } while (0)
; #define PG8_LDA(dst, b, h) do { _Pragma("unroll") for (int m = 0; m < 4; ++m) _Pragma("unroll") for (int k = 0; k < 2; ++k) dst[m][k] = *(const PG8_LAS bf16x8*)(lds + PG8_SA(b, h) + aoff + m * 2048 + k * 1024); } while (0)
; #define PG8_LDB(dst, b, h) do { _Pragma("unroll") for (int n = 0; n < 2; ++n) _Pragma("unroll") for (int k = 0; k < 2; ++k) dst[n][k] = *(const PG8_LAS bf16x8*)(lds + PG8_SB(b, h) + boff + n * 2048 + k * 1024); } while (0)
; #define PG8_WAIT_V(n) asm volatile("s_waitcnt vmcnt(" #n ")" ::: "memory")
; #define PG8_WAIT_L(n) asm volatile("s_waitcnt lgkmcnt(" #n ")" ::: "memory")
; #define PG8_BAR __builtin_amdgcn_s_barrier()
; #define PG8_SCHED __builtin_amdgcn_sched_barrier(0)
; template <class Epi, class Sched, bool ALIGN_EPI = false, bool SP2 = false>
; __device__ __forceinline__ void gemm_phase(PG8_LAS unsigned char* lds, const Gemm g, const Sched& S, const Epi& E, const int tid) {
;     ...
;         const char* nA = has_next ? (const char*)g.A + (size_t)nxt.pm * tstep : cA; const char* nB = has_next ? (const char*)g.Bt + (size_t)nxt.pn * tstep : cB;
;         for (int t = 0; t < nt; t += 2) {
;             const bool last = (t == nt - 2);
;             const char* a1 = cA + (size_t)(t + 1) * kstep;
;             const char* a2 = last ? nA : cA + (size_t)(t + 2) * kstep; const char* b2 = last ? nB : cB + (size_t)(t + 2) * kstep;
;             const char* a3 = a2 + kstep; const char* b3 = b2 + kstep;
;             if (last && has_next) S.a_ready(nxt);
;             if constexpr (SP2) {
;             PG8_LDB(B0, 0, 0); PG8_LDB(B1, 0, 1); PG8_SCHED; PG8_LDA(At, 0, 0); PG8_STAGE(PG8_SA(1, 1), a1 + hstep, voffA);
;             PG8_WAIT_V(8); PG8_WAIT_L(0); PG8_BAR; PG8_MMA(0, 0, At, B0); PG8_MMA(0, 1, At, B1); PG8_BAR; PG8_SCHED;
;             PG8_LDA(At, 0, 1); PG8_STAGE(PG8_SB(0, 0), b2, voffB); PG8_STAGE(PG8_SB(0, 1), b2 + hstepB, voffB); PG8_STAGE(PG8_SA(0, 0), a2, voffA);
;             PG8_WAIT_V(8); PG8_WAIT_L(0); PG8_BAR; PG8_MMA(1, 0, At, B0); PG8_MMA(1, 1, At, B1); PG8_BAR; PG8_SCHED;
.LBB0_1460:
	s_add_u32 s36, s38, 0xfff00080
	s_addc_u32 s37, s39, -1
	s_add_i32 s81, 0, 0x10000
	s_cmp_eq_u32 s80, 60
	s_cselect_b32 s41, s19, s37
	s_cselect_b32 s40, s25, s36
	v_add_u32_e32 v150, s81, v158
	s_cselect_b32 s37, s17, s79
	s_cselect_b32 s36, s76, s78
	s_cmp_eq_u32 s80, 60
	s_cselect_b32 s32, 1, 0
	s_andn2_b32 s32, s32, s30
	s_add_i32 s84, 0, 0x14000
	ds_read_b128 v[146:149], v150
	ds_read_b128 v[162:165], v150 offset:1024
	ds_read_b128 v[170:173], v150 offset:2048
	ds_read_b128 v[174:177], v150 offset:3072
	v_add_u32_e32 v150, s84, v158
	ds_read_b128 v[178:181], v150
	ds_read_b128 v[182:185], v150 offset:1024
	ds_read_b128 v[186:189], v150 offset:2048
	ds_read_b128 v[190:193], v150 offset:3072
	v_lshl_add_u64 v[150:151], s[38:39], 0, v[142:143]
	s_add_i32 m0, s29, 0xc000
	ds_read_b128 v[194:197], v160
	ds_read_b128 v[198:201], v160 offset:1024
	ds_read_b128 v[212:215], v160 offset:2048
	ds_read_b128 v[216:219], v160 offset:3072
	ds_read_b128 v[220:223], v160 offset:4096
	ds_read_b128 v[224:227], v160 offset:5120
	ds_read_b128 v[228:231], v160 offset:6144
	ds_read_b128 v[232:235], v160 offset:7168
	global_load_lds_dwordx4 v[150:151], off
	v_lshl_add_u64 v[150:151], s[38:39], 0, v[144:145]
	s_add_i32 m0, s29, 0xe000
	s_nop 0
	global_load_lds_dwordx4 v[150:151], off
	s_waitcnt vmcnt(8)
	s_waitcnt lgkmcnt(0)
	s_barrier
	s_setprio 1
	s_waitcnt lgkmcnt(0)
	v_mfma_f32_16x16x32_bf16 v[120:123], v[146:149], v[194:197], v[120:123]
	v_mfma_f32_16x16x32_bf16 v[128:131], v[170:173], v[194:197], v[128:131]
	v_mfma_f32_16x16x32_bf16 v[100:103], v[146:149], v[212:215], v[100:103]
	v_mfma_f32_16x16x32_bf16 v[108:111], v[170:173], v[212:215], v[108:111]
	v_mfma_f32_16x16x32_bf16 v[84:87], v[146:149], v[220:223], v[84:87]
	v_mfma_f32_16x16x32_bf16 v[92:95], v[170:173], v[220:223], v[92:95]
	v_mfma_f32_16x16x32_bf16 v[68:71], v[146:149], v[228:231], v[68:71]
	v_mfma_f32_16x16x32_bf16 v[76:79], v[170:173], v[228:231], v[76:79]
	v_mfma_f32_16x16x32_bf16 v[120:123], v[162:165], v[198:201], v[120:123]
	v_mfma_f32_16x16x32_bf16 v[128:131], v[174:177], v[198:201], v[128:131]
	v_mfma_f32_16x16x32_bf16 v[100:103], v[162:165], v[216:219], v[100:103]
	v_mfma_f32_16x16x32_bf16 v[108:111], v[174:177], v[216:219], v[108:111]
	v_mfma_f32_16x16x32_bf16 v[84:87], v[162:165], v[224:227], v[84:87]
	v_mfma_f32_16x16x32_bf16 v[92:95], v[174:177], v[224:227], v[92:95]
	v_mfma_f32_16x16x32_bf16 v[68:71], v[162:165], v[232:235], v[68:71]
	v_mfma_f32_16x16x32_bf16 v[76:79], v[174:177], v[232:235], v[76:79]
	s_setprio 0
	s_setprio 1
	v_mfma_f32_16x16x32_bf16 v[116:119], v[178:181], v[194:197], v[116:119]
	v_mfma_f32_16x16x32_bf16 v[124:127], v[186:189], v[194:197], v[124:127]
	v_mfma_f32_16x16x32_bf16 v[104:107], v[178:181], v[212:215], v[104:107]
	v_mfma_f32_16x16x32_bf16 v[112:115], v[186:189], v[212:215], v[112:115]
	v_mfma_f32_16x16x32_bf16 v[88:91], v[178:181], v[220:223], v[88:91]
	v_mfma_f32_16x16x32_bf16 v[96:99], v[186:189], v[220:223], v[96:99]
	v_mfma_f32_16x16x32_bf16 v[72:75], v[178:181], v[228:231], v[72:75]
	v_mfma_f32_16x16x32_bf16 v[80:83], v[186:189], v[228:231], v[80:83]
	v_mfma_f32_16x16x32_bf16 v[116:119], v[182:185], v[198:201], v[116:119]
	v_mfma_f32_16x16x32_bf16 v[124:127], v[190:193], v[198:201], v[124:127]
	v_mfma_f32_16x16x32_bf16 v[104:107], v[182:185], v[216:219], v[104:107]
	v_mfma_f32_16x16x32_bf16 v[112:115], v[190:193], v[216:219], v[112:115]
	v_mfma_f32_16x16x32_bf16 v[88:91], v[182:185], v[224:227], v[88:91]
	v_mfma_f32_16x16x32_bf16 v[96:99], v[190:193], v[224:227], v[96:99]
	v_mfma_f32_16x16x32_bf16 v[72:75], v[182:185], v[232:235], v[72:75]
	v_mfma_f32_16x16x32_bf16 v[80:83], v[190:193], v[232:235], v[80:83]
	s_setprio 0
	s_barrier
	s_add_i32 s81, s81, s43
	v_lshl_add_u64 v[150:151], s[36:37], 0, v[136:137]
	s_mov_b32 m0, s81
	ds_read_b128 v[194:197], v160 offset:16384
	ds_read_b128 v[198:201], v160 offset:17408
	ds_read_b128 v[212:215], v160 offset:18432
	ds_read_b128 v[216:219], v160 offset:19456
	ds_read_b128 v[220:223], v160 offset:20480
	ds_read_b128 v[224:227], v160 offset:21504
	ds_read_b128 v[228:231], v160 offset:22528
	ds_read_b128 v[232:235], v160 offset:23552
	s_cmp_lg_u32 s32, 0
	s_cbranch_scc1 .Lbt1460_0
	global_load_lds_dwordx4 v[150:151], off
.Lbt1460_0:
	s_add_i32 m0, s81, 0x2000
	s_add_u32 s82, s36, 0x40000
	v_lshl_add_u64 v[166:167], s[36:37], 0, v[140:141]
	s_addc_u32 s83, s37, 0
	s_add_i32 s81, s84, s43
	s_cmp_lg_u32 s32, 0
	s_cbranch_scc1 .Lbt1460_1
	global_load_lds_dwordx4 v[166:167], off

; #define PG8_STAGE(bufoff, gbase, voff) do { _Pragma("unroll") for (int _i = 0; _i < 2; ++_i) \
;         __builtin_amdgcn_global_load_lds((const unsigned*)((const char*)(gbase) + (voff)[_i]), (PG8_LAS unsigned*)(lds + (bufoff) + ldsw + _i * 8192), 16, 0, 0); } while (0)
; #define PG8_LDA(dst, b, h) do { _Pragma("unroll") for (int m = 0; m < 4; ++m) _Pragma("unroll") for (int k = 0; k < 2; ++k) dst[m][k] = *(const PG8_LAS bf16x8*)(lds + PG8_SA(b, h) + aoff + m * 2048 + k * 1024); } while (0)
; #define PG8_LDB(dst, b, h) do { _Pragma("unroll") for (int n = 0; n < 2; ++n) _Pragma("unroll") for (int k = 0; k < 2; ++k) dst[n][k] = *(const PG8_LAS bf16x8*)(lds + PG8_SB(b, h) + boff + n * 2048 + k * 1024); } while (0)
; #define PG8_MMA(ai, bj, At, Bt) do { __builtin_amdgcn_s_setprio(1); _Pragma("unroll") for (int m = 0; m < 4; ++m) _Pragma("unroll") for (int n = 0; n < 2; ++n) _Pragma("unroll") for (int k = 0; k < 2; ++k) \
;         acc[ai][bj][m][n] = __builtin_amdgcn_mfma_f32_16x16x32_bf16(Bt[n][k], At[m][k], acc[ai][bj][m][n], 0, 0, 0); __builtin_amdgcn_s_setprio(0); } while (0)
; #define PG8_WAIT_V(n) asm volatile("s_waitcnt vmcnt(" #n ")" ::: "memory")
; #define PG8_WAIT_L(n) asm volatile("s_waitcnt lgkmcnt(" #n ")" ::: "memory")
; #define PG8_BAR __builtin_amdgcn_s_barrier()
; #define PG8_SCHED __builtin_amdgcn_sched_barrier(0)
; template <class Epi, class Sched, bool ALIGN_EPI = false, bool SP2 = false>
; __device__ __forceinline__ void gemm_phase(PG8_LAS unsigned char* lds, const Gemm g, const Sched& S, const Epi& E, const int tid) {
;     ...
;             PG8_WAIT_V(8); PG8_WAIT_L(0); PG8_BAR; PG8_MMA(1, 0, At, B0); PG8_MMA(1, 1, At, B1); PG8_BAR; PG8_SCHED;
;             PG8_LDB(B0, 1, 0); PG8_LDB(B1, 1, 1); PG8_SCHED; PG8_LDA(At, 1, 0); PG8_STAGE(PG8_SA(0, 1), a2 + hstep, voffA);
;             PG8_WAIT_V(8); PG8_WAIT_L(0); PG8_BAR; PG8_MMA(0, 0, At, B0); PG8_MMA(0, 1, At, B1); PG8_BAR; PG8_SCHED;
.Lbw1460_2:
	s_waitcnt lgkmcnt(0)
	s_barrier
	s_setprio 1
	s_waitcnt lgkmcnt(0)
	v_mfma_f32_16x16x32_bf16 v[52:55], v[146:149], v[194:197], v[52:55]
	v_mfma_f32_16x16x32_bf16 v[60:63], v[170:173], v[194:197], v[60:63]
	v_mfma_f32_16x16x32_bf16 v[36:39], v[146:149], v[212:215], v[36:39]
	v_mfma_f32_16x16x32_bf16 v[44:47], v[170:173], v[212:215], v[44:47]
	v_mfma_f32_16x16x32_bf16 v[20:23], v[146:149], v[220:223], v[20:23]
	v_mfma_f32_16x16x32_bf16 v[28:31], v[170:173], v[220:223], v[28:31]
	v_mfma_f32_16x16x32_bf16 v[4:7], v[146:149], v[228:231], v[4:7]
	v_mfma_f32_16x16x32_bf16 v[12:15], v[170:173], v[228:231], v[12:15]
	v_mfma_f32_16x16x32_bf16 v[52:55], v[162:165], v[198:201], v[52:55]
	v_mfma_f32_16x16x32_bf16 v[60:63], v[174:177], v[198:201], v[60:63]
	v_mfma_f32_16x16x32_bf16 v[36:39], v[162:165], v[216:219], v[36:39]
	v_mfma_f32_16x16x32_bf16 v[44:47], v[174:177], v[216:219], v[44:47]
	v_mfma_f32_16x16x32_bf16 v[20:23], v[162:165], v[224:227], v[20:23]
	v_mfma_f32_16x16x32_bf16 v[28:31], v[174:177], v[224:227], v[28:31]
	v_mfma_f32_16x16x32_bf16 v[4:7], v[162:165], v[232:235], v[4:7]
	v_mfma_f32_16x16x32_bf16 v[12:15], v[174:177], v[232:235], v[12:15]
	s_setprio 0
	s_setprio 1
	v_mfma_f32_16x16x32_bf16 v[56:59], v[178:181], v[194:197], v[56:59]
	v_mfma_f32_16x16x32_bf16 v[64:67], v[186:189], v[194:197], v[64:67]
	v_mfma_f32_16x16x32_bf16 v[40:43], v[178:181], v[212:215], v[40:43]
	v_mfma_f32_16x16x32_bf16 v[48:51], v[186:189], v[212:215], v[48:51]
	v_mfma_f32_16x16x32_bf16 v[24:27], v[178:181], v[220:223], v[24:27]
	v_mfma_f32_16x16x32_bf16 v[32:35], v[186:189], v[220:223], v[32:35]
	v_mfma_f32_16x16x32_bf16 v[8:11], v[178:181], v[228:231], v[8:11]
	v_mfma_f32_16x16x32_bf16 v[16:19], v[186:189], v[228:231], v[16:19]
	v_mfma_f32_16x16x32_bf16 v[56:59], v[182:185], v[198:201], v[56:59]
	v_mfma_f32_16x16x32_bf16 v[64:67], v[190:193], v[198:201], v[64:67]
	v_mfma_f32_16x16x32_bf16 v[40:43], v[182:185], v[216:219], v[40:43]
	v_mfma_f32_16x16x32_bf16 v[48:51], v[190:193], v[216:219], v[48:51]
	v_mfma_f32_16x16x32_bf16 v[24:27], v[182:185], v[224:227], v[24:27]
	v_mfma_f32_16x16x32_bf16 v[32:35], v[190:193], v[224:227], v[32:35]
	v_mfma_f32_16x16x32_bf16 v[8:11], v[182:185], v[232:235], v[8:11]
	v_mfma_f32_16x16x32_bf16 v[16:19], v[190:193], v[232:235], v[16:19]
	s_setprio 0
	s_barrier
	s_add_i32 s81, 0, 0x18000
	v_add_u32_e32 v161, s81, v158
	s_add_i32 s82, 0, 0x1c000
	ds_read_b128 v[146:149], v161
	ds_read_b128 v[162:165], v161 offset:1024
	ds_read_b128 v[170:173], v161 offset:2048
	ds_read_b128 v[174:177], v161 offset:3072
	v_add_u32_e32 v161, s82, v158
	ds_read_b128 v[178:181], v161
	ds_read_b128 v[182:185], v161 offset:1024
	ds_read_b128 v[186:189], v161 offset:2048
	ds_read_b128 v[190:193], v161 offset:3072
	s_add_u32 s40, s40, 0x100000
	s_addc_u32 s41, s41, 0
	s_mov_b32 m0, s62
	v_lshl_add_u64 v[240:241], s[40:41], 0, v[134:135]
	ds_read_b128 v[194:197], v160 offset:32768
	ds_read_b128 v[198:201], v160 offset:33792
	ds_read_b128 v[212:215], v160 offset:34816
	ds_read_b128 v[216:219], v160 offset:35840
	ds_read_b128 v[220:223], v160 offset:36864
	ds_read_b128 v[224:227], v160 offset:37888
	ds_read_b128 v[228:231], v160 offset:38912
	ds_read_b128 v[232:235], v160 offset:39936
	s_cmp_lg_u32 s32, 0
	s_cbranch_scc1 .Lbt1460_6
	global_load_lds_dwordx4 v[240:241], off

; #define PG8_STAGE(bufoff, gbase, voff) do { _Pragma("unroll") for (int _i = 0; _i < 2; ++_i) \
;         __builtin_amdgcn_global_load_lds((const unsigned*)((const char*)(gbase) + (voff)[_i]), (PG8_LAS unsigned*)(lds + (bufoff) + ldsw + _i * 8192), 16, 0, 0); } while (0)
; #define PG8_LDA(dst, b, h) do { _Pragma("unroll") for (int m = 0; m < 4; ++m) _Pragma("unroll") for (int k = 0; k < 2; ++k) dst[m][k] = *(const PG8_LAS bf16x8*)(lds + PG8_SA(b, h) + aoff + m * 2048 + k * 1024); } while (0)
; #define PG8_MMA(ai, bj, At, Bt) do { __builtin_amdgcn_s_setprio(1); _Pragma("unroll") for (int m = 0; m < 4; ++m) _Pragma("unroll") for (int n = 0; n < 2; ++n) _Pragma("unroll") for (int k = 0; k < 2; ++k) \
;         acc[ai][bj][m][n] = __builtin_amdgcn_mfma_f32_16x16x32_bf16(Bt[n][k], At[m][k], acc[ai][bj][m][n], 0, 0, 0); __builtin_amdgcn_s_setprio(0); } while (0)
; #define PG8_WAIT_V(n) asm volatile("s_waitcnt vmcnt(" #n ")" ::: "memory")
; #define PG8_WAIT_L(n) asm volatile("s_waitcnt lgkmcnt(" #n ")" ::: "memory")
; #define PG8_BAR __builtin_amdgcn_s_barrier()
; #define PG8_SCHED __builtin_amdgcn_sched_barrier(0)
; template <class Epi, class Sched, bool ALIGN_EPI = false, bool SP2 = false>
; __device__ __forceinline__ void gemm_phase(PG8_LAS unsigned char* lds, const Gemm g, const Sched& S, const Epi& E, const int tid) {
;     ...
;             PG8_LDA(At, 1, 1); PG8_STAGE(PG8_SB(1, 0), b3, voffB); PG8_STAGE(PG8_SB(1, 1), b3 + hstepB, voffB); PG8_STAGE(PG8_SA(1, 0), a3, voffA);
;             PG8_WAIT_V(8); PG8_WAIT_L(0); PG8_BAR; PG8_MMA(1, 0, At, B0); PG8_MMA(1, 1, At, B1); PG8_BAR; PG8_SCHED;
.Lbt1460_8:
	s_add_i32 m0, s40, 0x2000
	s_add_u32 s36, s36, 0x40080
	v_lshl_add_u64 v[150:151], v[166:167], 0, s[52:53]
	s_addc_u32 s37, s37, 0
	s_add_i32 s40, s82, s43
	s_cmp_lg_u32 s32, 0
	s_cbranch_scc1 .Lbt1460_9
	global_load_lds_dwordx4 v[150:151], off

; #define PG8_STAGE(bufoff, gbase, voff) do { _Pragma("unroll") for (int _i = 0; _i < 2; ++_i) \
;         __builtin_amdgcn_global_load_lds((const unsigned*)((const char*)(gbase) + (voff)[_i]), (PG8_LAS unsigned*)(lds + (bufoff) + ldsw + _i * 8192), 16, 0, 0); } while (0)
; #define PG8_LDA(dst, b, h) do { _Pragma("unroll") for (int m = 0; m < 4; ++m) _Pragma("unroll") for (int k = 0; k < 2; ++k) dst[m][k] = *(const PG8_LAS bf16x8*)(lds + PG8_SA(b, h) + aoff + m * 2048 + k * 1024); } while (0)
; #define PG8_MMA(ai, bj, At, Bt) do { __builtin_amdgcn_s_setprio(1); _Pragma("unroll") for (int m = 0; m < 4; ++m) _Pragma("unroll") for (int n = 0; n < 2; ++n) _Pragma("unroll") for (int k = 0; k < 2; ++k) \
;         acc[ai][bj][m][n] = __builtin_amdgcn_mfma_f32_16x16x32_bf16(Bt[n][k], At[m][k], acc[ai][bj][m][n], 0, 0, 0); __builtin_amdgcn_s_setprio(0); } while (0)
; #define PG8_WAIT_V(n) asm volatile("s_waitcnt vmcnt(" #n ")" ::: "memory")
; #define PG8_WAIT_L(n) asm volatile("s_waitcnt lgkmcnt(" #n ")" ::: "memory")
; #define PG8_BAR __builtin_amdgcn_s_barrier()
; #define PG8_SCHED __builtin_amdgcn_sched_barrier(0)
; template <class Epi, class Sched, bool ALIGN_EPI = false, bool SP2 = false>
; __device__ __forceinline__ void gemm_phase(PG8_LAS unsigned char* lds, const Gemm g, const Sched& S, const Epi& E, const int tid) {
;     ...
;             PG8_LDA(At, 1, 1); PG8_STAGE(PG8_SB(1, 0), b3, voffB); PG8_STAGE(PG8_SB(1, 1), b3 + hstepB, voffB); PG8_STAGE(PG8_SA(1, 0), a3, voffA);
;             PG8_WAIT_V(8); PG8_WAIT_L(0); PG8_BAR; PG8_MMA(1, 0, At, B0); PG8_MMA(1, 1, At, B1); PG8_BAR; PG8_SCHED;
.Lbt1460_13:
	s_waitcnt vmcnt(8)
	s_waitcnt lgkmcnt(0)
	s_barrier
	s_setprio 1
	s_waitcnt lgkmcnt(0)
	v_mfma_f32_16x16x32_bf16 v[52:55], v[146:149], v[194:197], v[52:55]
	v_mfma_f32_16x16x32_bf16 v[60:63], v[170:173], v[194:197], v[60:63]
	v_mfma_f32_16x16x32_bf16 v[36:39], v[146:149], v[212:215], v[36:39]
	v_mfma_f32_16x16x32_bf16 v[44:47], v[170:173], v[212:215], v[44:47]
	v_mfma_f32_16x16x32_bf16 v[20:23], v[146:149], v[220:223], v[20:23]
	v_mfma_f32_16x16x32_bf16 v[28:31], v[170:173], v[220:223], v[28:31]
	v_mfma_f32_16x16x32_bf16 v[4:7], v[146:149], v[228:231], v[4:7]
	v_mfma_f32_16x16x32_bf16 v[12:15], v[170:173], v[228:231], v[12:15]
	v_mfma_f32_16x16x32_bf16 v[52:55], v[162:165], v[198:201], v[52:55]
	v_mfma_f32_16x16x32_bf16 v[60:63], v[174:177], v[198:201], v[60:63]
	v_mfma_f32_16x16x32_bf16 v[36:39], v[162:165], v[216:219], v[36:39]
	v_mfma_f32_16x16x32_bf16 v[44:47], v[174:177], v[216:219], v[44:47]
	v_mfma_f32_16x16x32_bf16 v[20:23], v[162:165], v[224:227], v[20:23]
	v_mfma_f32_16x16x32_bf16 v[28:31], v[174:177], v[224:227], v[28:31]
	v_mfma_f32_16x16x32_bf16 v[4:7], v[162:165], v[232:235], v[4:7]
	v_mfma_f32_16x16x32_bf16 v[12:15], v[174:177], v[232:235], v[12:15]
	s_setprio 0
	s_setprio 1
	v_mfma_f32_16x16x32_bf16 v[56:59], v[178:181], v[194:197], v[56:59]
	v_mfma_f32_16x16x32_bf16 v[64:67], v[186:189], v[194:197], v[64:67]
	v_mfma_f32_16x16x32_bf16 v[40:43], v[178:181], v[212:215], v[40:43]
	v_mfma_f32_16x16x32_bf16 v[48:51], v[186:189], v[212:215], v[48:51]
	v_mfma_f32_16x16x32_bf16 v[24:27], v[178:181], v[220:223], v[24:27]
	v_mfma_f32_16x16x32_bf16 v[32:35], v[186:189], v[220:223], v[32:35]
	v_mfma_f32_16x16x32_bf16 v[8:11], v[178:181], v[228:231], v[8:11]
	v_mfma_f32_16x16x32_bf16 v[16:19], v[186:189], v[228:231], v[16:19]
	v_mfma_f32_16x16x32_bf16 v[56:59], v[182:185], v[198:201], v[56:59]
	v_mfma_f32_16x16x32_bf16 v[64:67], v[190:193], v[198:201], v[64:67]
	v_mfma_f32_16x16x32_bf16 v[40:43], v[182:185], v[216:219], v[40:43]
	v_mfma_f32_16x16x32_bf16 v[48:51], v[190:193], v[216:219], v[48:51]
	v_mfma_f32_16x16x32_bf16 v[24:27], v[182:185], v[224:227], v[24:27]
	v_mfma_f32_16x16x32_bf16 v[32:35], v[190:193], v[224:227], v[32:35]
	v_mfma_f32_16x16x32_bf16 v[8:11], v[182:185], v[232:235], v[8:11]
	v_mfma_f32_16x16x32_bf16 v[16:19], v[190:193], v[232:235], v[16:19]
	s_setprio 0
	s_barrier
	s_add_i32 s80, s80, 2
	s_add_u32 s38, s38, 0x100
	s_addc_u32 s39, s39, 0
	s_add_u32 s78, s78, 0x100
	s_addc_u32 s79, s79, 0
	s_cmp_gt_u32 s80, 61
	s_cbranch_scc0 .LBB0_1460
	s_and_b64 vcc, exec, s[14:15]
	s_cbranch_vccz .LBB0_1463
	s_barrier
